# out-proj / q-proj / attn-out GEMM k-loops: next k-step's global loads issued at the start of the MFMA phase into a separate staging register set
# speedup vs baseline: 1.0074x; 1.0030x over previous
; template <class Epi>
; DI void gemm256(const bf16_t* __restrict__ A, int lda, const bf16_t* __restrict__ B, int ldb, int K, int m0, int n0,
;                 bf16_t* sA, bf16_t* sB, Epi epi) {
;     ...
;   f32x16 acc[4][2];
; #pragma unroll
;   for (int i = 0; i < 4; ++i)
; #pragma unroll
;     for (int j = 0; j < 2; ++j)
; #pragma unroll
;       for (int r = 0; r < 16; ++r) acc[i][j][r] = 0.f;
;   u32x4 ra0, ra1, ra2, ra3, ra4, ra5, ra6, ra7, rb0, rb1, rb2, rb3;
;   const bf16_t* Ap = A + (size_t)(m0 + lr) * lda + lc;
;   const bf16_t* Bp = B + (size_t)(n0 + lr) * ldb + lc;
;     ...
;   G256_LOAD(0)
; __global__ void __launch_bounds__(256, 2) hymba_mega(Params p) {
;     ...
;     for (int tile = blockIdx.x; tile < 64 * 8; tile += gridDim.x) {
;       const int mt = (tile & 7) * 8 + (tile >> 6), nt = (tile >> 3) & 7;
;       gemm256((const bf16_t*)(ws + OFF_MX), 1024, (const bf16_t*)(ws + OFF_WOUTT), 1024, 1024, mt * 256, nt * 128, sA, (bf16_t*)(smem + 36864),
;               [&](int m, int n, float v) { out[(size_t)m * 1024 + n] = x[(size_t)m * 1024 + n] + v; });
.LBB0_920:
	s_lshl_b32 s10, s43, 3
	s_and_b32 s10, s10, 56
	s_ashr_i32 s52, s43, 6
	s_add_i32 s10, s10, s52
	v_mov_b32_e32 v185, v192
	s_lshl_b32 s44, s10, 8
	s_lshl_b32 s10, s43, 4
	v_ashrrev_i32_e32 v0, 3, v185
	v_add_u32_e32 v2, s44, v0
	v_ashrrev_i32_e32 v3, 31, v2
	v_lshlrev_b64 v[2:3], 11, v[2:3]
	v_lshlrev_b32_e32 v1, 4, v185
	v_lshl_add_u64 v[2:3], s[6:7], 0, v[2:3]
	v_and_b32_e32 v176, 0x70, v1
	v_lshl_add_u64 v[2:3], v[2:3], 0, v[176:177]
	v_add_co_u32_e32 v6, vcc, s5, v2
	s_and_b32 s45, s10, 0x380
	s_nop 0
	v_addc_co_u32_e32 v7, vcc, 0, v3, vcc
	s_waitcnt vmcnt(6)
	v_add_co_u32_e32 v8, vcc, s12, v2
	v_add_u32_e32 v4, s45, v0
	s_nop 0
	v_addc_co_u32_e32 v9, vcc, 0, v3, vcc
	global_load_dwordx4 v[200:203], v[6:7], off
	global_load_dwordx4 v[204:207], v[8:9], off
	v_add_co_u32_e32 v6, vcc, s13, v2
	v_ashrrev_i32_e32 v5, 31, v4
	s_nop 0
	v_addc_co_u32_e32 v7, vcc, 0, v3, vcc
	v_add_co_u32_e32 v8, vcc, s14, v2
	v_lshlrev_b64 v[4:5], 11, v[4:5]
	s_nop 0
	v_addc_co_u32_e32 v9, vcc, 0, v3, vcc
	global_load_dwordx4 v[208:211], v[6:7], off
	global_load_dwordx4 v[212:215], v[8:9], off
	v_add_co_u32_e32 v6, vcc, s15, v2
	v_lshl_add_u64 v[4:5], s[24:25], 0, v[4:5]
	s_nop 0
	v_addc_co_u32_e32 v7, vcc, 0, v3, vcc
	v_add_co_u32_e32 v8, vcc, s16, v2
	v_lshl_add_u64 v[4:5], v[4:5], 0, v[176:177]
	s_nop 0
	v_addc_co_u32_e32 v9, vcc, 0, v3, vcc
	global_load_dwordx4 v[216:219], v[6:7], off
	global_load_dwordx4 v[220:223], v[8:9], off
	v_add_co_u32_e32 v6, vcc, s17, v2
	global_load_dwordx4 v[232:235], v[2:3], off
	global_load_dwordx4 v[224:227], v[4:5], off
	v_addc_co_u32_e32 v7, vcc, 0, v3, vcc
	v_add_co_u32_e32 v2, vcc, s5, v4
	s_lshl_b32 s2, s0, 8
	s_nop 0
	v_addc_co_u32_e32 v3, vcc, 0, v5, vcc
	global_load_dwordx4 v[236:239], v[6:7], off
	global_load_dwordx4 v[240:243], v[2:3], off
	v_add_co_u32_e32 v2, vcc, s12, v4
	v_mad_u64_u32 v[178:179], s[10:11], v0, s20, v[176:177]
	s_nop 0
	v_addc_co_u32_e32 v3, vcc, 0, v5, vcc
	v_add_co_u32_e32 v4, vcc, s13, v4
	s_and_b32 s2, s2, 0x3800
	s_nop 0
	v_addc_co_u32_e32 v5, vcc, 0, v5, vcc
	global_load_dwordx4 v[244:247], v[2:3], off
	global_load_dwordx4 v[248:251], v[4:5], off
	v_and_b32_e32 v1, 0xfffff9f, v185
	s_lshl_b32 s10, s52, 8
	v_lshrrev_b32_e32 v2, 1, v185
	v_mul_lo_u32 v5, v1, s20
	v_or_b32_e32 v1, 0x60, v185
	s_add_i32 s10, s10, s2
	s_lshl_b32 s8, s3, 11
	v_and_b32_e32 v4, 16, v2
	v_mul_lo_u32 v6, v1, s20
	v_add_u32_e32 v2, s10, v0
	v_ashrrev_i32_e32 v1, 31, v0
	s_and_b32 s8, s8, 0x1c0000
	v_ashrrev_i32_e32 v3, 31, v2
	v_lshlrev_b64 v[0:1], 11, v[0:1]
	v_lshlrev_b64 v[2:3], 11, v[2:3]
	v_lshl_add_u64 v[0:1], s[8:9], 0, v[0:1]
	v_and_b32_e32 v186, 0x5f, v185
	v_or_b32_e32 v2, v2, v176
	v_or_b32_e32 v0, v0, v176
	v_mad_u32_u24 v184, v186, s20, v4
	v_lshl_add_u64 v[180:181], s[86:87], 0, v[2:3]
	v_lshl_add_u64 v[182:183], s[86:87], 0, v[0:1]
	s_mov_b64 s[10:11], 0
	v_add_u32_e32 v179, v4, v5
	v_add_u32_e32 v176, v4, v6
	v_mov_b32_e32 v0, 0
	v_mov_b32_e32 v1, v177
	v_mov_b32_e32 v2, v177
	v_mov_b32_e32 v3, v177
	v_mov_b32_e32 v4, v177
	v_mov_b32_e32 v5, v177
	v_mov_b32_e32 v6, v177
	v_mov_b32_e32 v7, v177
	v_mov_b32_e32 v8, v177
	v_mov_b32_e32 v9, v177
	v_mov_b32_e32 v10, v177
	v_mov_b32_e32 v11, v177
	v_mov_b32_e32 v12, v177
	v_mov_b32_e32 v13, v177
	v_mov_b32_e32 v14, v177
	v_mov_b32_e32 v15, v177
	v_mov_b32_e32 v16, 0
	v_mov_b32_e32 v17, v177
	v_mov_b32_e32 v18, v177
	v_mov_b32_e32 v19, v177
	v_mov_b32_e32 v20, v177
	v_mov_b32_e32 v21, v177
	v_mov_b32_e32 v22, v177
	v_mov_b32_e32 v23, v177
	v_mov_b32_e32 v24, v177
	v_mov_b32_e32 v25, v177
	v_mov_b32_e32 v26, v177
	v_mov_b32_e32 v27, v177
	v_mov_b32_e32 v28, v177
	v_mov_b32_e32 v29, v177
	v_mov_b32_e32 v30, v177
	v_mov_b32_e32 v31, v177
	s_waitcnt vmcnt(17)
	v_mov_b32_e32 v32, 0
	v_mov_b32_e32 v33, v177
	v_mov_b32_e32 v34, v177
	v_mov_b32_e32 v35, v177
	v_mov_b32_e32 v36, v177
	v_mov_b32_e32 v37, v177
	v_mov_b32_e32 v38, v177
	v_mov_b32_e32 v39, v177
	v_mov_b32_e32 v40, v177
	v_mov_b32_e32 v41, v177
	v_mov_b32_e32 v42, v177
	v_mov_b32_e32 v43, v177
	v_mov_b32_e32 v44, v177
	v_mov_b32_e32 v45, v177
	v_mov_b32_e32 v46, v177
	v_mov_b32_e32 v47, v177
	v_mov_b32_e32 v48, 0
	v_mov_b32_e32 v49, v177
	v_mov_b32_e32 v50, v177
	v_mov_b32_e32 v51, v177
	v_mov_b32_e32 v52, v177
	v_mov_b32_e32 v53, v177
	v_mov_b32_e32 v54, v177
	v_mov_b32_e32 v55, v177
	v_mov_b32_e32 v56, v177
	v_mov_b32_e32 v57, v177
	v_mov_b32_e32 v58, v177
	v_mov_b32_e32 v59, v177
	v_mov_b32_e32 v60, v177
	v_mov_b32_e32 v61, v177
	v_mov_b32_e32 v62, v177
	v_mov_b32_e32 v63, v177
	v_mov_b32_e32 v64, 0
	v_mov_b32_e32 v65, v177
	v_mov_b32_e32 v66, v177
	v_mov_b32_e32 v67, v177
	v_mov_b32_e32 v68, v177
	v_mov_b32_e32 v69, v177
	v_mov_b32_e32 v70, v177
	v_mov_b32_e32 v71, v177
	v_mov_b32_e32 v72, v177
	v_mov_b32_e32 v73, v177
	v_mov_b32_e32 v74, v177
	v_mov_b32_e32 v75, v177
	v_mov_b32_e32 v76, v177
	v_mov_b32_e32 v77, v177
	v_mov_b32_e32 v78, v177
	v_mov_b32_e32 v79, v177
	v_mov_b32_e32 v80, 0
	v_mov_b32_e32 v81, v177
	v_mov_b32_e32 v82, v177
	v_mov_b32_e32 v83, v177
	v_mov_b32_e32 v84, v177
	v_mov_b32_e32 v85, v177
	v_mov_b32_e32 v86, v177
	v_mov_b32_e32 v87, v177
	v_mov_b32_e32 v88, v177
	v_mov_b32_e32 v89, v177
	v_mov_b32_e32 v90, v177
	v_mov_b32_e32 v91, v177
	v_mov_b32_e32 v92, v177
	v_mov_b32_e32 v93, v177
	v_mov_b32_e32 v94, v177
	v_mov_b32_e32 v95, v177
	v_mov_b32_e32 v96, 0
	v_mov_b32_e32 v97, v177
	v_mov_b32_e32 v98, v177
	v_mov_b32_e32 v99, v177
	v_mov_b32_e32 v100, v177
	v_mov_b32_e32 v101, v177
	v_mov_b32_e32 v102, v177
	v_mov_b32_e32 v103, v177
	v_mov_b32_e32 v104, v177
	v_mov_b32_e32 v105, v177
	v_mov_b32_e32 v106, v177
	v_mov_b32_e32 v107, v177
	v_mov_b32_e32 v108, v177
	v_mov_b32_e32 v109, v177
	v_mov_b32_e32 v110, v177
	v_mov_b32_e32 v111, v177
	v_mov_b32_e32 v112, 0
	v_mov_b32_e32 v113, v177
	v_mov_b32_e32 v114, v177
	v_mov_b32_e32 v115, v177
	v_mov_b32_e32 v116, v177
	v_mov_b32_e32 v117, v177
	v_mov_b32_e32 v118, v177
	v_mov_b32_e32 v119, v177
	v_mov_b32_e32 v120, v177
	v_mov_b32_e32 v121, v177
	v_mov_b32_e32 v122, v177
	v_mov_b32_e32 v123, v177
	v_mov_b32_e32 v124, v177
	v_mov_b32_e32 v125, v177
	v_mov_b32_e32 v126, v177
	v_mov_b32_e32 v127, v177
; #define MFMA32(a, b, c) __builtin_amdgcn_mfma_f32_32x32x16_bf16((a), (b), (c), 0, 0, 0)
; template <class Epi>
; DI void gemm256(const bf16_t* __restrict__ A, int lda, const bf16_t* __restrict__ B, int ldb, int K, int m0, int n0,
;                 bf16_t* sA, bf16_t* sB, Epi epi) {
;     ...
;   for (int kt = 0; kt < nk; ++kt) {
;     __syncthreads();
;     *(u32x4*)(sA + (lr) * LDS_ROW + lc) = ra0; *(u32x4*)(sA + (lr + 32) * LDS_ROW + lc) = ra1;
;     *(u32x4*)(sA + (lr + 64) * LDS_ROW + lc) = ra2; *(u32x4*)(sA + (lr + 96) * LDS_ROW + lc) = ra3;
;     *(u32x4*)(sA + (lr + 128) * LDS_ROW + lc) = ra4; *(u32x4*)(sA + (lr + 160) * LDS_ROW + lc) = ra5;
;     *(u32x4*)(sA + (lr + 192) * LDS_ROW + lc) = ra6; *(u32x4*)(sA + (lr + 224) * LDS_ROW + lc) = ra7;
;     *(u32x4*)(sB + (lr) * LDS_ROW + lc) = rb0; *(u32x4*)(sB + (lr + 32) * LDS_ROW + lc) = rb1;
;     *(u32x4*)(sB + (lr + 64) * LDS_ROW + lc) = rb2; *(u32x4*)(sB + (lr + 96) * LDS_ROW + lc) = rb3;
;     __syncthreads();
;     if (kt + 1 < nk) {
;       const int ko2 = (kt + 1) * 64;
;       G256_LOAD(ko2)
;     }
; #pragma unroll
;     for (int s = 0; s < 4; ++s) {
;       const int ko = s * 16 + (lane >> 5) * 8;
;       bf16x8 b0 = *(const bf16x8*)(sB + (wn * 64 + (lane & 31)) * LDS_ROW + ko);
;       bf16x8 b1 = *(const bf16x8*)(sB + (wn * 64 + 32 + (lane & 31)) * LDS_ROW + ko);
; #pragma unroll
;       for (int i = 0; i < 4; ++i) {
;         bf16x8 a = *(const bf16x8*)(sA + (wm * 128 + i * 32 + (lane & 31)) * LDS_ROW + ko);
;         acc[i][0] = MFMA32(a, b0, acc[i][0]);
;         acc[i][1] = MFMA32(a, b1, acc[i][1]);
;       }
;     }
.LBB0_921:
	s_barrier
	s_waitcnt vmcnt(5)
	ds_write_b128 v178, v[232:235]
	ds_write_b128 v178, v[200:203] offset:4608
	ds_write_b128 v178, v[204:207] offset:9216
	ds_write_b128 v178, v[208:211] offset:13824
	ds_write_b128 v178, v[212:215] offset:18432
	ds_write_b128 v178, v[216:219] offset:23040
	ds_write_b128 v178, v[220:223] offset:27648
	s_waitcnt vmcnt(3)
	ds_write_b128 v178, v[236:239] offset:32256
	ds_write_b128 v178, v[224:227] offset:36864
	s_waitcnt vmcnt(2)
	ds_write_b128 v178, v[240:243] offset:41472
	s_waitcnt vmcnt(1)
	ds_write_b128 v178, v[244:247] offset:46080
	s_waitcnt vmcnt(0)
	ds_write_b128 v178, v[248:251] offset:50688
	s_waitcnt lgkmcnt(0)
	s_barrier
	v_lshl_add_u64 v[252:253], v[180:181], 0, s[10:11]
	v_lshl_add_u64 v[254:255], v[182:183], 0, s[10:11]
	ds_read_b128 v[128:131], v179
	ds_read_b128 v[132:135], v184 offset:36864
	ds_read_b128 v[136:139], v184 offset:36896
	ds_read_b128 v[140:143], v179 offset:32
	ds_read_b128 v[144:147], v184 offset:41472
	ds_read_b128 v[148:151], v184 offset:41504
	s_waitcnt lgkmcnt(4)
	v_mfma_f32_32x32x16_bf16 v[112:127], v[128:131], v[132:135], v[112:127]
	v_add_co_u32_e64 v228, vcc, s21, v252
	v_add_co_u32_e64 v198, s[98:99], s26, v252
	s_waitcnt lgkmcnt(1)
	v_mfma_f32_32x32x16_bf16 v[96:111], v[128:131], v[144:147], v[96:111]
	v_addc_co_u32_e64 v229, vcc, 0, v253, vcc
	v_addc_co_u32_e64 v199, s[98:99], 0, v253, s[98:99]
	global_load_dwordx4 v[232:235], v[228:229], off offset:128
	global_load_dwordx4 v[200:203], v[198:199], off offset:128
	ds_read_b128 v[128:131], v179 offset:4608
	ds_read_b128 v[152:155], v179 offset:4640
	s_waitcnt lgkmcnt(1)
	v_mfma_f32_32x32x16_bf16 v[80:95], v[128:131], v[132:135], v[80:95]
	v_add_co_u32_e64 v228, vcc, s27, v252
	v_add_co_u32_e64 v198, s[98:99], s28, v252
	v_mfma_f32_32x32x16_bf16 v[64:79], v[128:131], v[144:147], v[64:79]
	v_addc_co_u32_e64 v229, vcc, 0, v253, vcc
	v_addc_co_u32_e64 v199, s[98:99], 0, v253, s[98:99]
	global_load_dwordx4 v[204:207], v[228:229], off offset:128
	global_load_dwordx4 v[208:211], v[198:199], off offset:128
	ds_read_b128 v[128:131], v179 offset:9216
	ds_read_b128 v[156:159], v179 offset:9248
	s_waitcnt lgkmcnt(1)
	v_mfma_f32_32x32x16_bf16 v[48:63], v[128:131], v[132:135], v[48:63]
	v_add_co_u32_e64 v228, vcc, s29, v252
	v_add_co_u32_e64 v198, s[98:99], s30, v252
	v_mfma_f32_32x32x16_bf16 v[32:47], v[128:131], v[144:147], v[32:47]
	v_addc_co_u32_e64 v229, vcc, 0, v253, vcc
	v_addc_co_u32_e64 v199, s[98:99], 0, v253, s[98:99]
	global_load_dwordx4 v[212:215], v[228:229], off offset:128
	global_load_dwordx4 v[216:219], v[198:199], off offset:128
	ds_read_b128 v[128:131], v176
	ds_read_b128 v[160:163], v176 offset:32
	s_waitcnt lgkmcnt(1)
	v_mfma_f32_32x32x16_bf16 v[16:31], v[128:131], v[132:135], v[16:31]
	v_add_co_u32_e64 v228, vcc, s31, v252
	v_add_co_u32_e64 v198, s[98:99], s34, v252
	v_mfma_f32_32x32x16_bf16 v[112:127], v[140:143], v[136:139], v[112:127]
	v_addc_co_u32_e64 v229, vcc, 0, v253, vcc
	v_addc_co_u32_e64 v199, s[98:99], 0, v253, s[98:99]
	global_load_dwordx4 v[220:223], v[228:229], off offset:128
	global_load_dwordx4 v[236:239], v[198:199], off offset:128
	v_mfma_f32_32x32x16_bf16 v[96:111], v[140:143], v[148:151], v[96:111]
	v_add_co_u32_e64 v228, vcc, s35, v254
	v_add_co_u32_e64 v198, s[98:99], s36, v254
	v_mfma_f32_32x32x16_bf16 v[0:15], v[128:131], v[144:147], v[0:15]
	v_addc_co_u32_e64 v229, vcc, 0, v255, vcc
	v_addc_co_u32_e64 v199, s[98:99], 0, v255, s[98:99]
	global_load_dwordx4 v[224:227], v[228:229], off offset:128
	global_load_dwordx4 v[240:243], v[198:199], off offset:128
	v_mfma_f32_32x32x16_bf16 v[80:95], v[152:155], v[136:139], v[80:95]
	v_add_co_u32_e64 v228, vcc, s37, v254
	v_add_co_u32_e64 v198, s[98:99], s42, v254
	v_mfma_f32_32x32x16_bf16 v[64:79], v[152:155], v[148:151], v[64:79]
	v_addc_co_u32_e64 v229, vcc, 0, v255, vcc
	v_addc_co_u32_e64 v199, s[98:99], 0, v255, s[98:99]
	global_load_dwordx4 v[244:247], v[228:229], off offset:128
	global_load_dwordx4 v[248:251], v[198:199], off offset:128
	v_mfma_f32_32x32x16_bf16 v[48:63], v[156:159], v[136:139], v[48:63]
	s_waitcnt lgkmcnt(0)
	v_mfma_f32_32x32x16_bf16 v[16:31], v[160:163], v[136:139], v[16:31]
	ds_read_b128 v[128:131], v179 offset:64
	ds_read_b128 v[132:135], v184 offset:36928
	ds_read_b128 v[172:175], v184 offset:36960
	ds_read_b128 v[136:139], v179 offset:96
	ds_read_b128 v[140:143], v184 offset:41536
	ds_read_b128 v[188:191], v184 offset:41568
	v_mfma_f32_32x32x16_bf16 v[32:47], v[156:159], v[148:151], v[32:47]
	s_waitcnt lgkmcnt(4)
	v_mfma_f32_32x32x16_bf16 v[112:127], v[128:131], v[132:135], v[112:127]
	s_waitcnt lgkmcnt(1)
	v_mfma_f32_32x32x16_bf16 v[96:111], v[128:131], v[140:143], v[96:111]
	ds_read_b128 v[128:131], v179 offset:4672
	ds_read_b128 v[144:147], v179 offset:4704
	v_mfma_f32_32x32x16_bf16 v[0:15], v[160:163], v[148:151], v[0:15]
	s_waitcnt lgkmcnt(1)
	v_mfma_f32_32x32x16_bf16 v[80:95], v[128:131], v[132:135], v[80:95]
	v_mfma_f32_32x32x16_bf16 v[64:79], v[128:131], v[140:143], v[64:79]
	ds_read_b128 v[128:131], v179 offset:9280
	ds_read_b128 v[148:151], v179 offset:9312
	s_waitcnt lgkmcnt(1)
	v_mfma_f32_32x32x16_bf16 v[48:63], v[128:131], v[132:135], v[48:63]
	v_mfma_f32_32x32x16_bf16 v[32:47], v[128:131], v[140:143], v[32:47]
	ds_read_b128 v[128:131], v176 offset:64
	ds_read_b128 v[194:197], v176 offset:96
	s_waitcnt lgkmcnt(1)
	v_mfma_f32_32x32x16_bf16 v[16:31], v[128:131], v[132:135], v[16:31]
	s_add_u32 s10, s10, 0x80
	v_mfma_f32_32x32x16_bf16 v[0:15], v[128:131], v[140:143], v[0:15]
	s_addc_u32 s11, s11, 0
	v_mfma_f32_32x32x16_bf16 v[112:127], v[136:139], v[172:175], v[112:127]
	s_cmpk_lg_i32 s10, 0x780
	v_mfma_f32_32x32x16_bf16 v[96:111], v[136:139], v[188:191], v[96:111]
	v_mfma_f32_32x32x16_bf16 v[80:95], v[144:147], v[172:175], v[80:95]
	v_mfma_f32_32x32x16_bf16 v[64:79], v[144:147], v[188:191], v[64:79]
	v_mfma_f32_32x32x16_bf16 v[48:63], v[148:151], v[172:175], v[48:63]
	v_mfma_f32_32x32x16_bf16 v[32:47], v[148:151], v[188:191], v[32:47]
	s_waitcnt lgkmcnt(0)
	v_mfma_f32_32x32x16_bf16 v[16:31], v[194:197], v[172:175], v[16:31]
	v_mfma_f32_32x32x16_bf16 v[0:15], v[194:197], v[188:191], v[0:15]
	s_cbranch_scc1 .LBB0_921
; #define MFMA32(a, b, c) __builtin_amdgcn_mfma_f32_32x32x16_bf16((a), (b), (c), 0, 0, 0)
; DI int crow32(int r, int half) { return (r & 3) + 8 * (r >> 2) + 4 * half; }
; template <class Epi>
; DI void gemm256(const bf16_t* __restrict__ A, int lda, const bf16_t* __restrict__ B, int ldb, int K, int m0, int n0,
;                 bf16_t* sA, bf16_t* sB, Epi epi) {
;     ...
;   for (int kt = 0; kt < nk; ++kt) {
;     __syncthreads();
;     *(u32x4*)(sA + (lr) * LDS_ROW + lc) = ra0; *(u32x4*)(sA + (lr + 32) * LDS_ROW + lc) = ra1;
;     *(u32x4*)(sA + (lr + 64) * LDS_ROW + lc) = ra2; *(u32x4*)(sA + (lr + 96) * LDS_ROW + lc) = ra3;
;     *(u32x4*)(sA + (lr + 128) * LDS_ROW + lc) = ra4; *(u32x4*)(sA + (lr + 160) * LDS_ROW + lc) = ra5;
;     *(u32x4*)(sA + (lr + 192) * LDS_ROW + lc) = ra6; *(u32x4*)(sA + (lr + 224) * LDS_ROW + lc) = ra7;
;     *(u32x4*)(sB + (lr) * LDS_ROW + lc) = rb0; *(u32x4*)(sB + (lr + 32) * LDS_ROW + lc) = rb1;
;     *(u32x4*)(sB + (lr + 64) * LDS_ROW + lc) = rb2; *(u32x4*)(sB + (lr + 96) * LDS_ROW + lc) = rb3;
;     __syncthreads();
;     if (kt + 1 < nk) {
;       const int ko2 = (kt + 1) * 64;
;       G256_LOAD(ko2)
;     }
; #pragma unroll
;     for (int s = 0; s < 4; ++s) {
;       const int ko = s * 16 + (lane >> 5) * 8;
;       bf16x8 b0 = *(const bf16x8*)(sB + (wn * 64 + (lane & 31)) * LDS_ROW + ko);
;       bf16x8 b1 = *(const bf16x8*)(sB + (wn * 64 + 32 + (lane & 31)) * LDS_ROW + ko);
; #pragma unroll
;       for (int i = 0; i < 4; ++i) {
;         bf16x8 a = *(const bf16x8*)(sA + (wm * 128 + i * 32 + (lane & 31)) * LDS_ROW + ko);
;         acc[i][0] = MFMA32(a, b0, acc[i][0]);
;         acc[i][1] = MFMA32(a, b1, acc[i][1]);
;       }
;     }
;   }
;     ...
; #pragma unroll
;   for (int i = 0; i < 4; ++i)
; #pragma unroll
;     for (int j = 0; j < 2; ++j)
; #pragma unroll
;       for (int r = 0; r < 16; ++r) {
;         const int m = m0 + wm * 128 + i * 32 + crow32(r, lane >> 5);
;         const int n = n0 + wn * 64 + j * 32 + (lane & 31);
;         epi(m, n, acc[i][j][r]);
;       }
	s_barrier
	s_waitcnt vmcnt(11)
	ds_write_b128 v178, v[232:235]
	s_waitcnt vmcnt(10)
	ds_write_b128 v178, v[200:203] offset:4608
	s_waitcnt vmcnt(9)
	ds_write_b128 v178, v[204:207] offset:9216
	s_waitcnt vmcnt(8)
	ds_write_b128 v178, v[208:211] offset:13824
	s_waitcnt vmcnt(7)
	ds_write_b128 v178, v[212:215] offset:18432
	s_waitcnt vmcnt(6)
	ds_write_b128 v178, v[216:219] offset:23040
	s_waitcnt vmcnt(5)
	ds_write_b128 v178, v[220:223] offset:27648
	s_waitcnt vmcnt(4)
	ds_write_b128 v178, v[236:239] offset:32256
	s_waitcnt vmcnt(3)
	ds_write_b128 v178, v[224:227] offset:36864
	s_waitcnt vmcnt(2)
	ds_write_b128 v178, v[240:243] offset:41472
	s_waitcnt vmcnt(1)
	ds_write_b128 v178, v[244:247] offset:46080
	s_waitcnt vmcnt(0)
	ds_write_b128 v178, v[248:251] offset:50688
	s_waitcnt lgkmcnt(0)
	s_barrier
	ds_read_b128 v[128:131], v179
	ds_read_b128 v[132:135], v184 offset:36864
	ds_read_b128 v[136:139], v184 offset:36896
	ds_read_b128 v[140:143], v179 offset:32
	ds_read_b128 v[144:147], v184 offset:41472
	ds_read_b128 v[148:151], v184 offset:41504
	s_waitcnt lgkmcnt(4)
	v_mfma_f32_32x32x16_bf16 v[112:127], v[128:131], v[132:135], v[112:127]
	s_waitcnt lgkmcnt(1)
	v_mfma_f32_32x32x16_bf16 v[96:111], v[128:131], v[144:147], v[96:111]
	ds_read_b128 v[128:131], v179 offset:4608
	ds_read_b128 v[152:155], v179 offset:4640
	s_waitcnt lgkmcnt(1)
	v_mfma_f32_32x32x16_bf16 v[80:95], v[128:131], v[132:135], v[80:95]
	v_mfma_f32_32x32x16_bf16 v[64:79], v[128:131], v[144:147], v[64:79]
	ds_read_b128 v[128:131], v179 offset:9216
	ds_read_b128 v[156:159], v179 offset:9248
	s_waitcnt lgkmcnt(1)
	v_mfma_f32_32x32x16_bf16 v[48:63], v[128:131], v[132:135], v[48:63]
	v_mfma_f32_32x32x16_bf16 v[32:47], v[128:131], v[144:147], v[32:47]
	ds_read_b128 v[128:131], v176
	ds_read_b128 v[160:163], v176 offset:32
	s_waitcnt lgkmcnt(1)
	v_mfma_f32_32x32x16_bf16 v[16:31], v[128:131], v[132:135], v[16:31]
	v_mfma_f32_32x32x16_bf16 v[112:127], v[140:143], v[136:139], v[112:127]
	v_mfma_f32_32x32x16_bf16 v[96:111], v[140:143], v[148:151], v[96:111]
	v_mfma_f32_32x32x16_bf16 v[0:15], v[128:131], v[144:147], v[0:15]
	v_mfma_f32_32x32x16_bf16 v[80:95], v[152:155], v[136:139], v[80:95]
	v_mfma_f32_32x32x16_bf16 v[64:79], v[152:155], v[148:151], v[64:79]
	v_mfma_f32_32x32x16_bf16 v[48:63], v[156:159], v[136:139], v[48:63]
	s_waitcnt lgkmcnt(0)
	v_mfma_f32_32x32x16_bf16 v[16:31], v[160:163], v[136:139], v[16:31]
	ds_read_b128 v[128:131], v179 offset:64
	ds_read_b128 v[132:135], v184 offset:36928
	ds_read_b128 v[172:175], v184 offset:36960
	ds_read_b128 v[136:139], v179 offset:96
	ds_read_b128 v[140:143], v184 offset:41536
	ds_read_b128 v[188:191], v184 offset:41568
	v_mfma_f32_32x32x16_bf16 v[32:47], v[156:159], v[148:151], v[32:47]
	s_waitcnt lgkmcnt(4)
	v_mfma_f32_32x32x16_bf16 v[112:127], v[128:131], v[132:135], v[112:127]
	s_waitcnt lgkmcnt(1)
	v_mfma_f32_32x32x16_bf16 v[96:111], v[128:131], v[140:143], v[96:111]
	ds_read_b128 v[128:131], v179 offset:4672
	ds_read_b128 v[144:147], v179 offset:4704
	v_mfma_f32_32x32x16_bf16 v[0:15], v[160:163], v[148:151], v[0:15]
	s_waitcnt lgkmcnt(1)
	v_mfma_f32_32x32x16_bf16 v[80:95], v[128:131], v[132:135], v[80:95]
	v_mfma_f32_32x32x16_bf16 v[64:79], v[128:131], v[140:143], v[64:79]
	ds_read_b128 v[128:131], v179 offset:9280
	ds_read_b128 v[148:151], v179 offset:9312
	s_waitcnt lgkmcnt(1)
	v_mfma_f32_32x32x16_bf16 v[48:63], v[128:131], v[132:135], v[48:63]
	v_mfma_f32_32x32x16_bf16 v[32:47], v[128:131], v[140:143], v[32:47]
	ds_read_b128 v[128:131], v176 offset:64
	ds_read_b128 v[194:197], v176 offset:96
	s_waitcnt lgkmcnt(1)
	v_mfma_f32_32x32x16_bf16 v[16:31], v[128:131], v[132:135], v[16:31]
	v_mfma_f32_32x32x16_bf16 v[0:15], v[128:131], v[140:143], v[0:15]
	v_mfma_f32_32x32x16_bf16 v[112:127], v[136:139], v[172:175], v[112:127]
	v_mfma_f32_32x32x16_bf16 v[96:111], v[136:139], v[188:191], v[96:111]
	v_mfma_f32_32x32x16_bf16 v[80:95], v[144:147], v[172:175], v[80:95]
	v_mfma_f32_32x32x16_bf16 v[64:79], v[144:147], v[188:191], v[64:79]
	v_mfma_f32_32x32x16_bf16 v[48:63], v[148:151], v[172:175], v[48:63]
	v_mfma_f32_32x32x16_bf16 v[32:47], v[148:151], v[188:191], v[32:47]
	s_waitcnt lgkmcnt(0)
	v_mfma_f32_32x32x16_bf16 v[16:31], v[194:197], v[172:175], v[16:31]
	v_mfma_f32_32x32x16_bf16 v[0:15], v[194:197], v[188:191], v[0:15]
	v_and_b32_e32 v200, 0xffffff80, v185
	v_lshrrev_b32_e32 v201, 3, v185
	v_add_u32_e32 v200, s44, v200
	v_and_or_b32 v200, v201, 4, v200
	v_or_b32_e32 v201, s45, v186
	v_lshlrev_b32_e32 v200, 12, v200
	v_lshl_add_u32 v200, v201, 2, v200
	v_mov_b32_e32 v202, v200
	v_add_u32_e32 v203, 0x1000, v200
	v_add_u32_e32 v204, 0x2000, v200
	v_add_u32_e32 v205, 0x3000, v200
	v_add_u32_e32 v206, 0x8000, v200
	v_add_u32_e32 v207, 0x9000, v200
	v_add_u32_e32 v208, 0xa000, v200
	v_add_u32_e32 v209, 0xb000, v200
	v_add_u32_e32 v210, 0x10000, v200
	v_add_u32_e32 v211, 0x11000, v200
	v_add_u32_e32 v212, 0x12000, v200
	v_add_u32_e32 v213, 0x13000, v200
	v_add_u32_e32 v214, 0x18000, v200
	v_add_u32_e32 v215, 0x19000, v200
	v_add_u32_e32 v216, 0x1a000, v200
	v_add_u32_e32 v217, 0x1b000, v200
	v_mov_b32_e32 v128, v202
	global_load_dword v144, v128, s[68:69]
	v_mov_b32_e32 v129, v203
	global_load_dword v145, v129, s[68:69]
	v_mov_b32_e32 v130, v204
	global_load_dword v146, v130, s[68:69]
	v_mov_b32_e32 v131, v205
	global_load_dword v147, v131, s[68:69]
	v_mov_b32_e32 v132, v206
	global_load_dword v148, v132, s[68:69]
	v_mov_b32_e32 v133, v207
	global_load_dword v149, v133, s[68:69]
	v_mov_b32_e32 v134, v208
	global_load_dword v150, v134, s[68:69]
	v_mov_b32_e32 v135, v209
	global_load_dword v151, v135, s[68:69]
	v_mov_b32_e32 v136, v210
; DI int crow32(int r, int half) { return (r & 3) + 8 * (r >> 2) + 4 * half; }
; template <class Epi>
; DI void gemm256(const bf16_t* __restrict__ A, int lda, const bf16_t* __restrict__ B, int ldb, int K, int m0, int n0,
;                 bf16_t* sA, bf16_t* sB, Epi epi) {
;     ...
; #pragma unroll
;   for (int i = 0; i < 4; ++i)
; #pragma unroll
;     for (int j = 0; j < 2; ++j)
; #pragma unroll
;       for (int r = 0; r < 16; ++r) {
;         const int m = m0 + wm * 128 + i * 32 + crow32(r, lane >> 5);
;         const int n = n0 + wn * 64 + j * 32 + (lane & 31);
;         epi(m, n, acc[i][j][r]);
;       }
; __global__ void __launch_bounds__(256, 2) hymba_mega(Params p) {
;     ...
;               [&](int m, int n, float v) { out[(size_t)m * 1024 + n] = x[(size_t)m * 1024 + n] + v; });
	global_load_dword v152, v136, s[68:69]
	v_mov_b32_e32 v137, v211
	global_load_dword v153, v137, s[68:69]
	v_mov_b32_e32 v138, v212
	global_load_dword v154, v138, s[68:69]
	v_mov_b32_e32 v139, v213
	global_load_dword v155, v139, s[68:69]
	v_mov_b32_e32 v140, v214
	global_load_dword v156, v140, s[68:69]
	v_mov_b32_e32 v141, v215
	global_load_dword v157, v141, s[68:69]
	v_mov_b32_e32 v142, v216
	global_load_dword v158, v142, s[68:69]
	v_mov_b32_e32 v143, v217
	global_load_dword v159, v143, s[68:69]
	v_add_u32_e32 v160, 0x80, v202
	global_load_dword v236, v160, s[68:69]
	v_add_u32_e32 v161, 0x80, v203
	global_load_dword v237, v161, s[68:69]
	v_add_u32_e32 v162, 0x80, v204
	global_load_dword v238, v162, s[68:69]
	v_add_u32_e32 v163, 0x80, v205
	global_load_dword v239, v163, s[68:69]
	v_add_u32_e32 v164, 0x80, v206
	global_load_dword v240, v164, s[68:69]
	v_add_u32_e32 v165, 0x80, v207
	global_load_dword v241, v165, s[68:69]
	v_add_u32_e32 v166, 0x80, v208
	global_load_dword v242, v166, s[68:69]
	v_add_u32_e32 v167, 0x80, v209
	global_load_dword v243, v167, s[68:69]
	v_add_u32_e32 v168, 0x80, v210
	global_load_dword v244, v168, s[68:69]
	v_add_u32_e32 v169, 0x80, v211
	global_load_dword v245, v169, s[68:69]
	v_add_u32_e32 v170, 0x80, v212
	global_load_dword v246, v170, s[68:69]
	v_add_u32_e32 v171, 0x80, v213
	global_load_dword v247, v171, s[68:69]
	v_add_u32_e32 v172, 0x80, v214
	global_load_dword v248, v172, s[68:69]
	v_add_u32_e32 v173, 0x80, v215
	global_load_dword v249, v173, s[68:69]
	v_add_u32_e32 v174, 0x80, v216
	global_load_dword v250, v174, s[68:69]
	v_add_u32_e32 v175, 0x80, v217
	global_load_dword v251, v175, s[68:69]
	s_waitcnt vmcnt(16)
	v_add_f32_e32 v144, v112, v144
	global_store_dword v128, v144, s[84:85]
	v_add_f32_e32 v145, v113, v145
	global_store_dword v129, v145, s[84:85]
	v_add_f32_e32 v146, v114, v146
	global_store_dword v130, v146, s[84:85]
	v_add_f32_e32 v147, v115, v147
	global_store_dword v131, v147, s[84:85]
	v_add_f32_e32 v148, v116, v148
	global_store_dword v132, v148, s[84:85]
	v_add_f32_e32 v149, v117, v149
	global_store_dword v133, v149, s[84:85]
	v_add_f32_e32 v150, v118, v150
	global_store_dword v134, v150, s[84:85]
	v_add_f32_e32 v151, v119, v151
	global_store_dword v135, v151, s[84:85]
	v_add_f32_e32 v152, v120, v152
	global_store_dword v136, v152, s[84:85]
	v_add_f32_e32 v153, v121, v153
	global_store_dword v137, v153, s[84:85]
	v_add_f32_e32 v154, v122, v154
	global_store_dword v138, v154, s[84:85]
	v_add_f32_e32 v155, v123, v155
	global_store_dword v139, v155, s[84:85]
	v_add_f32_e32 v156, v124, v156
	global_store_dword v140, v156, s[84:85]
	v_add_f32_e32 v157, v125, v157
	global_store_dword v141, v157, s[84:85]
	v_add_f32_e32 v158, v126, v158
	global_store_dword v142, v158, s[84:85]
	v_add_f32_e32 v159, v127, v159
	global_store_dword v143, v159, s[84:85]
	v_add_u32_e32 v128, 0x20000, v202
	global_load_dword v144, v128, s[68:69]
	v_add_u32_e32 v129, 0x20000, v203
	global_load_dword v145, v129, s[68:69]
	v_add_u32_e32 v130, 0x20000, v204
	global_load_dword v146, v130, s[68:69]
	v_add_u32_e32 v131, 0x20000, v205
	global_load_dword v147, v131, s[68:69]
	v_add_u32_e32 v132, 0x20000, v206
	global_load_dword v148, v132, s[68:69]
	v_add_u32_e32 v133, 0x20000, v207
	global_load_dword v149, v133, s[68:69]
	v_add_u32_e32 v134, 0x20000, v208
	global_load_dword v150, v134, s[68:69]
	v_add_u32_e32 v135, 0x20000, v209
	global_load_dword v151, v135, s[68:69]
	v_add_u32_e32 v136, 0x20000, v210
	global_load_dword v152, v136, s[68:69]
	v_add_u32_e32 v137, 0x20000, v211
	global_load_dword v153, v137, s[68:69]
	v_add_u32_e32 v138, 0x20000, v212
	global_load_dword v154, v138, s[68:69]
	v_add_u32_e32 v139, 0x20000, v213
	global_load_dword v155, v139, s[68:69]
	v_add_u32_e32 v140, 0x20000, v214
	global_load_dword v156, v140, s[68:69]
	v_add_u32_e32 v141, 0x20000, v215
	global_load_dword v157, v141, s[68:69]
	v_add_u32_e32 v142, 0x20000, v216
	global_load_dword v158, v142, s[68:69]
	v_add_u32_e32 v143, 0x20000, v217
	global_load_dword v159, v143, s[68:69]
	s_waitcnt vmcnt(32)
	v_add_f32_e32 v236, v96, v236
	global_store_dword v160, v236, s[84:85]
	v_add_f32_e32 v237, v97, v237
	global_store_dword v161, v237, s[84:85]
	v_add_f32_e32 v238, v98, v238
	global_store_dword v162, v238, s[84:85]
	v_add_f32_e32 v239, v99, v239
	global_store_dword v163, v239, s[84:85]
	v_add_f32_e32 v240, v100, v240
	global_store_dword v164, v240, s[84:85]
	v_add_f32_e32 v241, v101, v241
	global_store_dword v165, v241, s[84:85]
	v_add_f32_e32 v242, v102, v242
	global_store_dword v166, v242, s[84:85]
	v_add_f32_e32 v243, v103, v243
	global_store_dword v167, v243, s[84:85]
	v_add_f32_e32 v244, v104, v244
	global_store_dword v168, v244, s[84:85]
	v_add_f32_e32 v245, v105, v245
	global_store_dword v169, v245, s[84:85]
	v_add_f32_e32 v246, v106, v246
	global_store_dword v170, v246, s[84:85]
	v_add_f32_e32 v247, v107, v247
	global_store_dword v171, v247, s[84:85]
	v_add_f32_e32 v248, v108, v248
	global_store_dword v172, v248, s[84:85]
	v_add_f32_e32 v249, v109, v249
	global_store_dword v173, v249, s[84:85]
	v_add_f32_e32 v250, v110, v250
	global_store_dword v174, v250, s[84:85]
	v_add_f32_e32 v251, v111, v251
	global_store_dword v175, v251, s[84:85]
	v_add_u32_e32 v160, 0x20080, v202
	global_load_dword v236, v160, s[68:69]
	v_add_u32_e32 v161, 0x20080, v203
	global_load_dword v237, v161, s[68:69]
	v_add_u32_e32 v162, 0x20080, v204
	global_load_dword v238, v162, s[68:69]
	v_add_u32_e32 v163, 0x20080, v205
	global_load_dword v239, v163, s[68:69]
	v_add_u32_e32 v164, 0x20080, v206
	global_load_dword v240, v164, s[68:69]
	v_add_u32_e32 v165, 0x20080, v207
	global_load_dword v241, v165, s[68:69]
	v_add_u32_e32 v166, 0x20080, v208
	global_load_dword v242, v166, s[68:69]
	v_add_u32_e32 v167, 0x20080, v209
	global_load_dword v243, v167, s[68:69]
	v_add_u32_e32 v168, 0x20080, v210
	global_load_dword v244, v168, s[68:69]
	v_add_u32_e32 v169, 0x20080, v211
	global_load_dword v245, v169, s[68:69]
	v_add_u32_e32 v170, 0x20080, v212
	global_load_dword v246, v170, s[68:69]
	v_add_u32_e32 v171, 0x20080, v213
	global_load_dword v247, v171, s[68:69]
	v_add_u32_e32 v172, 0x20080, v214
	global_load_dword v248, v172, s[68:69]
	v_add_u32_e32 v173, 0x20080, v215
	global_load_dword v249, v173, s[68:69]
	v_add_u32_e32 v174, 0x20080, v216
	global_load_dword v250, v174, s[68:69]
	v_add_u32_e32 v175, 0x20080, v217
	global_load_dword v251, v175, s[68:69]
	s_waitcnt vmcnt(32)
; DI int crow32(int r, int half) { return (r & 3) + 8 * (r >> 2) + 4 * half; }
; template <class Epi>
; DI void gemm256(const bf16_t* __restrict__ A, int lda, const bf16_t* __restrict__ B, int ldb, int K, int m0, int n0,
;                 bf16_t* sA, bf16_t* sB, Epi epi) {
;     ...
; #pragma unroll
;   for (int i = 0; i < 4; ++i)
; #pragma unroll
;     for (int j = 0; j < 2; ++j)
; #pragma unroll
;       for (int r = 0; r < 16; ++r) {
;         const int m = m0 + wm * 128 + i * 32 + crow32(r, lane >> 5);
;         const int n = n0 + wn * 64 + j * 32 + (lane & 31);
;         epi(m, n, acc[i][j][r]);
;       }
; __global__ void __launch_bounds__(256, 2) hymba_mega(Params p) {
;     ...
;               [&](int m, int n, float v) { out[(size_t)m * 1024 + n] = x[(size_t)m * 1024 + n] + v; });
	v_add_f32_e32 v144, v80, v144
	global_store_dword v128, v144, s[84:85]
	v_add_f32_e32 v145, v81, v145
	global_store_dword v129, v145, s[84:85]
	v_add_f32_e32 v146, v82, v146
	global_store_dword v130, v146, s[84:85]
	v_add_f32_e32 v147, v83, v147
	global_store_dword v131, v147, s[84:85]
	v_add_f32_e32 v148, v84, v148
	global_store_dword v132, v148, s[84:85]
	v_add_f32_e32 v149, v85, v149
	global_store_dword v133, v149, s[84:85]
	v_add_f32_e32 v150, v86, v150
	global_store_dword v134, v150, s[84:85]
	v_add_f32_e32 v151, v87, v151
	global_store_dword v135, v151, s[84:85]
	v_add_f32_e32 v152, v88, v152
	global_store_dword v136, v152, s[84:85]
	v_add_f32_e32 v153, v89, v153
	global_store_dword v137, v153, s[84:85]
	v_add_f32_e32 v154, v90, v154
	global_store_dword v138, v154, s[84:85]
	v_add_f32_e32 v155, v91, v155
	global_store_dword v139, v155, s[84:85]
	v_add_f32_e32 v156, v92, v156
	global_store_dword v140, v156, s[84:85]
	v_add_f32_e32 v157, v93, v157
	global_store_dword v141, v157, s[84:85]
	v_add_f32_e32 v158, v94, v158
	global_store_dword v142, v158, s[84:85]
	v_add_f32_e32 v159, v95, v159
	global_store_dword v143, v159, s[84:85]
	v_add_u32_e32 v128, 0x40000, v202
	global_load_dword v144, v128, s[68:69]
	v_add_u32_e32 v129, 0x40000, v203
	global_load_dword v145, v129, s[68:69]
	v_add_u32_e32 v130, 0x40000, v204
	global_load_dword v146, v130, s[68:69]
	v_add_u32_e32 v131, 0x40000, v205
	global_load_dword v147, v131, s[68:69]
	v_add_u32_e32 v132, 0x40000, v206
	global_load_dword v148, v132, s[68:69]
	v_add_u32_e32 v133, 0x40000, v207
	global_load_dword v149, v133, s[68:69]
	v_add_u32_e32 v134, 0x40000, v208
	global_load_dword v150, v134, s[68:69]
	v_add_u32_e32 v135, 0x40000, v209
	global_load_dword v151, v135, s[68:69]
	v_add_u32_e32 v136, 0x40000, v210
	global_load_dword v152, v136, s[68:69]
	v_add_u32_e32 v137, 0x40000, v211
	global_load_dword v153, v137, s[68:69]
	v_add_u32_e32 v138, 0x40000, v212
	global_load_dword v154, v138, s[68:69]
	v_add_u32_e32 v139, 0x40000, v213
	global_load_dword v155, v139, s[68:69]
	v_add_u32_e32 v140, 0x40000, v214
	global_load_dword v156, v140, s[68:69]
	v_add_u32_e32 v141, 0x40000, v215
	global_load_dword v157, v141, s[68:69]
	v_add_u32_e32 v142, 0x40000, v216
	global_load_dword v158, v142, s[68:69]
	v_add_u32_e32 v143, 0x40000, v217
	global_load_dword v159, v143, s[68:69]
	s_waitcnt vmcnt(32)
	v_add_f32_e32 v236, v64, v236
	global_store_dword v160, v236, s[84:85]
	v_add_f32_e32 v237, v65, v237
	global_store_dword v161, v237, s[84:85]
	v_add_f32_e32 v238, v66, v238
	global_store_dword v162, v238, s[84:85]
	v_add_f32_e32 v239, v67, v239
	global_store_dword v163, v239, s[84:85]
	v_add_f32_e32 v240, v68, v240
	global_store_dword v164, v240, s[84:85]
	v_add_f32_e32 v241, v69, v241
	global_store_dword v165, v241, s[84:85]
	v_add_f32_e32 v242, v70, v242
	global_store_dword v166, v242, s[84:85]
	v_add_f32_e32 v243, v71, v243
	global_store_dword v167, v243, s[84:85]
	v_add_f32_e32 v244, v72, v244
	global_store_dword v168, v244, s[84:85]
	v_add_f32_e32 v245, v73, v245
	global_store_dword v169, v245, s[84:85]
	v_add_f32_e32 v246, v74, v246
	global_store_dword v170, v246, s[84:85]
	v_add_f32_e32 v247, v75, v247
	global_store_dword v171, v247, s[84:85]
	v_add_f32_e32 v248, v76, v248
	global_store_dword v172, v248, s[84:85]
	v_add_f32_e32 v249, v77, v249
	global_store_dword v173, v249, s[84:85]
	v_add_f32_e32 v250, v78, v250
	global_store_dword v174, v250, s[84:85]
	v_add_f32_e32 v251, v79, v251
	global_store_dword v175, v251, s[84:85]
	v_add_u32_e32 v160, 0x40080, v202
	global_load_dword v236, v160, s[68:69]
	v_add_u32_e32 v161, 0x40080, v203
	global_load_dword v237, v161, s[68:69]
	v_add_u32_e32 v162, 0x40080, v204
	global_load_dword v238, v162, s[68:69]
	v_add_u32_e32 v163, 0x40080, v205
	global_load_dword v239, v163, s[68:69]
	v_add_u32_e32 v164, 0x40080, v206
	global_load_dword v240, v164, s[68:69]
	v_add_u32_e32 v165, 0x40080, v207
	global_load_dword v241, v165, s[68:69]
	v_add_u32_e32 v166, 0x40080, v208
	global_load_dword v242, v166, s[68:69]
	v_add_u32_e32 v167, 0x40080, v209
	global_load_dword v243, v167, s[68:69]
	v_add_u32_e32 v168, 0x40080, v210
	global_load_dword v244, v168, s[68:69]
	v_add_u32_e32 v169, 0x40080, v211
	global_load_dword v245, v169, s[68:69]
	v_add_u32_e32 v170, 0x40080, v212
	global_load_dword v246, v170, s[68:69]
	v_add_u32_e32 v171, 0x40080, v213
	global_load_dword v247, v171, s[68:69]
	v_add_u32_e32 v172, 0x40080, v214
	global_load_dword v248, v172, s[68:69]
	v_add_u32_e32 v173, 0x40080, v215
	global_load_dword v249, v173, s[68:69]
	v_add_u32_e32 v174, 0x40080, v216
	global_load_dword v250, v174, s[68:69]
	v_add_u32_e32 v175, 0x40080, v217
	global_load_dword v251, v175, s[68:69]
	s_waitcnt vmcnt(32)
; DI int crow32(int r, int half) { return (r & 3) + 8 * (r >> 2) + 4 * half; }
; template <class Epi>
; DI void gemm256(const bf16_t* __restrict__ A, int lda, const bf16_t* __restrict__ B, int ldb, int K, int m0, int n0,
;                 bf16_t* sA, bf16_t* sB, Epi epi) {
;     ...
; #pragma unroll
;   for (int i = 0; i < 4; ++i)
; #pragma unroll
;     for (int j = 0; j < 2; ++j)
; #pragma unroll
;       for (int r = 0; r < 16; ++r) {
;         const int m = m0 + wm * 128 + i * 32 + crow32(r, lane >> 5);
;         const int n = n0 + wn * 64 + j * 32 + (lane & 31);
;         epi(m, n, acc[i][j][r]);
;       }
; __global__ void __launch_bounds__(256, 2) hymba_mega(Params p) {
;     ...
;               [&](int m, int n, float v) { out[(size_t)m * 1024 + n] = x[(size_t)m * 1024 + n] + v; });
	v_add_f32_e32 v144, v48, v144
	global_store_dword v128, v144, s[84:85]
	v_add_f32_e32 v145, v49, v145
	global_store_dword v129, v145, s[84:85]
	v_add_f32_e32 v146, v50, v146
	global_store_dword v130, v146, s[84:85]
	v_add_f32_e32 v147, v51, v147
	global_store_dword v131, v147, s[84:85]
	v_add_f32_e32 v148, v52, v148
	global_store_dword v132, v148, s[84:85]
	v_add_f32_e32 v149, v53, v149
	global_store_dword v133, v149, s[84:85]
	v_add_f32_e32 v150, v54, v150
	global_store_dword v134, v150, s[84:85]
	v_add_f32_e32 v151, v55, v151
	global_store_dword v135, v151, s[84:85]
	v_add_f32_e32 v152, v56, v152
	global_store_dword v136, v152, s[84:85]
	v_add_f32_e32 v153, v57, v153
	global_store_dword v137, v153, s[84:85]
	v_add_f32_e32 v154, v58, v154
	global_store_dword v138, v154, s[84:85]
	v_add_f32_e32 v155, v59, v155
	global_store_dword v139, v155, s[84:85]
	v_add_f32_e32 v156, v60, v156
	global_store_dword v140, v156, s[84:85]
	v_add_f32_e32 v157, v61, v157
	global_store_dword v141, v157, s[84:85]
	v_add_f32_e32 v158, v62, v158
	global_store_dword v142, v158, s[84:85]
	v_add_f32_e32 v159, v63, v159
	global_store_dword v143, v159, s[84:85]
	v_add_u32_e32 v128, 0x60000, v202
	global_load_dword v144, v128, s[68:69]
	v_add_u32_e32 v129, 0x60000, v203
	global_load_dword v145, v129, s[68:69]
	v_add_u32_e32 v130, 0x60000, v204
	global_load_dword v146, v130, s[68:69]
	v_add_u32_e32 v131, 0x60000, v205
	global_load_dword v147, v131, s[68:69]
	v_add_u32_e32 v132, 0x60000, v206
	global_load_dword v148, v132, s[68:69]
	v_add_u32_e32 v133, 0x60000, v207
	global_load_dword v149, v133, s[68:69]
	v_add_u32_e32 v134, 0x60000, v208
	global_load_dword v150, v134, s[68:69]
	v_add_u32_e32 v135, 0x60000, v209
	global_load_dword v151, v135, s[68:69]
	v_add_u32_e32 v136, 0x60000, v210
	global_load_dword v152, v136, s[68:69]
	v_add_u32_e32 v137, 0x60000, v211
	global_load_dword v153, v137, s[68:69]
	v_add_u32_e32 v138, 0x60000, v212
	global_load_dword v154, v138, s[68:69]
	v_add_u32_e32 v139, 0x60000, v213
	global_load_dword v155, v139, s[68:69]
	v_add_u32_e32 v140, 0x60000, v214
	global_load_dword v156, v140, s[68:69]
	v_add_u32_e32 v141, 0x60000, v215
	global_load_dword v157, v141, s[68:69]
	v_add_u32_e32 v142, 0x60000, v216
	global_load_dword v158, v142, s[68:69]
	v_add_u32_e32 v143, 0x60000, v217
	global_load_dword v159, v143, s[68:69]
	s_waitcnt vmcnt(32)
	v_add_f32_e32 v236, v32, v236
	global_store_dword v160, v236, s[84:85]
	v_add_f32_e32 v237, v33, v237
	global_store_dword v161, v237, s[84:85]
	v_add_f32_e32 v238, v34, v238
	global_store_dword v162, v238, s[84:85]
	v_add_f32_e32 v239, v35, v239
	global_store_dword v163, v239, s[84:85]
	v_add_f32_e32 v240, v36, v240
	global_store_dword v164, v240, s[84:85]
	v_add_f32_e32 v241, v37, v241
	global_store_dword v165, v241, s[84:85]
	v_add_f32_e32 v242, v38, v242
	global_store_dword v166, v242, s[84:85]
	v_add_f32_e32 v243, v39, v243
	global_store_dword v167, v243, s[84:85]
	v_add_f32_e32 v244, v40, v244
	global_store_dword v168, v244, s[84:85]
	v_add_f32_e32 v245, v41, v245
	global_store_dword v169, v245, s[84:85]
	v_add_f32_e32 v246, v42, v246
	global_store_dword v170, v246, s[84:85]
	v_add_f32_e32 v247, v43, v247
	global_store_dword v171, v247, s[84:85]
	v_add_f32_e32 v248, v44, v248
	global_store_dword v172, v248, s[84:85]
	v_add_f32_e32 v249, v45, v249
	global_store_dword v173, v249, s[84:85]
	v_add_f32_e32 v250, v46, v250
	global_store_dword v174, v250, s[84:85]
	v_add_f32_e32 v251, v47, v251
	global_store_dword v175, v251, s[84:85]
	v_add_u32_e32 v160, 0x60080, v202
	global_load_dword v236, v160, s[68:69]
	v_add_u32_e32 v161, 0x60080, v203
	global_load_dword v237, v161, s[68:69]
	v_add_u32_e32 v162, 0x60080, v204
	global_load_dword v238, v162, s[68:69]
	v_add_u32_e32 v163, 0x60080, v205
	global_load_dword v239, v163, s[68:69]
	v_add_u32_e32 v164, 0x60080, v206
	global_load_dword v240, v164, s[68:69]
	v_add_u32_e32 v165, 0x60080, v207
	global_load_dword v241, v165, s[68:69]
	v_add_u32_e32 v166, 0x60080, v208
	global_load_dword v242, v166, s[68:69]
	v_add_u32_e32 v167, 0x60080, v209
	global_load_dword v243, v167, s[68:69]
	v_add_u32_e32 v168, 0x60080, v210
	global_load_dword v244, v168, s[68:69]
	v_add_u32_e32 v169, 0x60080, v211
	global_load_dword v245, v169, s[68:69]
	v_add_u32_e32 v170, 0x60080, v212
	global_load_dword v246, v170, s[68:69]
	v_add_u32_e32 v171, 0x60080, v213
	global_load_dword v247, v171, s[68:69]
	v_add_u32_e32 v172, 0x60080, v214
	global_load_dword v248, v172, s[68:69]
	v_add_u32_e32 v173, 0x60080, v215
	global_load_dword v249, v173, s[68:69]
	v_add_u32_e32 v174, 0x60080, v216
	global_load_dword v250, v174, s[68:69]
	v_add_u32_e32 v175, 0x60080, v217
	global_load_dword v251, v175, s[68:69]
	s_waitcnt vmcnt(32)
; DI int crow32(int r, int half) { return (r & 3) + 8 * (r >> 2) + 4 * half; }
; template <class Epi>
; DI void gemm256(const bf16_t* __restrict__ A, int lda, const bf16_t* __restrict__ B, int ldb, int K, int m0, int n0,
;                 bf16_t* sA, bf16_t* sB, Epi epi) {
;     ...
; #pragma unroll
;   for (int i = 0; i < 4; ++i)
; #pragma unroll
;     for (int j = 0; j < 2; ++j)
; #pragma unroll
;       for (int r = 0; r < 16; ++r) {
;         const int m = m0 + wm * 128 + i * 32 + crow32(r, lane >> 5);
;         const int n = n0 + wn * 64 + j * 32 + (lane & 31);
;         epi(m, n, acc[i][j][r]);
;       }
; __global__ void __launch_bounds__(256, 2) hymba_mega(Params p) {
;     ...
;     for (int tile = blockIdx.x; tile < 64 * 8; tile += gridDim.x) {
	v_add_f32_e32 v144, v16, v144
	global_store_dword v128, v144, s[84:85]
	v_add_f32_e32 v145, v17, v145
	global_store_dword v129, v145, s[84:85]
	v_add_f32_e32 v146, v18, v146
	global_store_dword v130, v146, s[84:85]
	v_add_f32_e32 v147, v19, v147
	global_store_dword v131, v147, s[84:85]
	v_add_f32_e32 v148, v20, v148
	global_store_dword v132, v148, s[84:85]
	v_add_f32_e32 v149, v21, v149
	global_store_dword v133, v149, s[84:85]
	v_add_f32_e32 v150, v22, v150
	global_store_dword v134, v150, s[84:85]
	v_add_f32_e32 v151, v23, v151
	global_store_dword v135, v151, s[84:85]
	v_add_f32_e32 v152, v24, v152
	global_store_dword v136, v152, s[84:85]
	v_add_f32_e32 v153, v25, v153
	global_store_dword v137, v153, s[84:85]
	v_add_f32_e32 v154, v26, v154
	global_store_dword v138, v154, s[84:85]
	v_add_f32_e32 v155, v27, v155
	global_store_dword v139, v155, s[84:85]
	v_add_f32_e32 v156, v28, v156
	global_store_dword v140, v156, s[84:85]
	v_add_f32_e32 v157, v29, v157
	global_store_dword v141, v157, s[84:85]
	v_add_f32_e32 v158, v30, v158
	global_store_dword v142, v158, s[84:85]
	v_add_f32_e32 v159, v31, v159
	global_store_dword v143, v159, s[84:85]
	s_waitcnt vmcnt(16)
	v_add_f32_e32 v236, v0, v236
	global_store_dword v160, v236, s[84:85]
	v_add_f32_e32 v237, v1, v237
	global_store_dword v161, v237, s[84:85]
	v_add_f32_e32 v238, v2, v238
	global_store_dword v162, v238, s[84:85]
	v_add_f32_e32 v239, v3, v239
	global_store_dword v163, v239, s[84:85]
	v_add_f32_e32 v240, v4, v240
	global_store_dword v164, v240, s[84:85]
	v_add_f32_e32 v241, v5, v241
	global_store_dword v165, v241, s[84:85]
	v_add_f32_e32 v242, v6, v242
	global_store_dword v166, v242, s[84:85]
	v_add_f32_e32 v243, v7, v243
	global_store_dword v167, v243, s[84:85]
	v_add_f32_e32 v244, v8, v244
	global_store_dword v168, v244, s[84:85]
	v_add_f32_e32 v245, v9, v245
	global_store_dword v169, v245, s[84:85]
	v_add_f32_e32 v246, v10, v246
	global_store_dword v170, v246, s[84:85]
	v_add_f32_e32 v247, v11, v247
	global_store_dword v171, v247, s[84:85]
	v_add_f32_e32 v248, v12, v248
	global_store_dword v172, v248, s[84:85]
	v_add_f32_e32 v249, v13, v249
	global_store_dword v173, v249, s[84:85]
	v_add_f32_e32 v250, v14, v250
	global_store_dword v174, v250, s[84:85]
	v_add_f32_e32 v251, v15, v251
	global_store_dword v175, v251, s[84:85]
	s_add_i32 s43, s43, s88
	s_add_i32 s0, s0, s1
	s_add_i32 s3, s3, s4
	s_cmpk_gt_i32 s43, 0x1ff
	s_cbranch_scc0 .LBB0_920

; DI bf16_t f2bf(float f) { return (bf16_t)(pk2(f, 0.f) & 0xffffu); }
; template <class Epi>
; DI void gemm256(const bf16_t* __restrict__ A, int lda, const bf16_t* __restrict__ B, int ldb, int K, int m0, int n0,
;                 bf16_t* sA, bf16_t* sB, Epi epi) {
;     ...
;   f32x16 acc[4][2];
; #pragma unroll
;   for (int i = 0; i < 4; ++i)
; #pragma unroll
;     for (int j = 0; j < 2; ++j)
; #pragma unroll
;       for (int r = 0; r < 16; ++r) acc[i][j][r] = 0.f;
;   u32x4 ra0, ra1, ra2, ra3, ra4, ra5, ra6, ra7, rb0, rb1, rb2, rb3;
;   const bf16_t* Ap = A + (size_t)(m0 + lr) * lda + lc;
;   const bf16_t* Bp = B + (size_t)(n0 + lr) * ldb + lc;
;     ...
;   G256_LOAD(0)
; __global__ void __launch_bounds__(256, 2) hymba_mega(Params p) {
;     ...
;     for (int tile = blockIdx.x; tile < 64 * 8; tile += gridDim.x) {
;       const int mt = (tile & 7) * 8 + (tile >> 6), nt = (tile >> 3) & 7;
;       gemm256((const bf16_t*)(ws + OFF_H2), 1024, (const bf16_t*)(ws + OFF_WQT), 1024, 1024, mt * 256, nt * 128, sA, (bf16_t*)(smem + 36864),
;               [&](int m, int n, float v) { Qx[(size_t)m * 1024 + n] = f2bf(v); });
.LBB0_1039:
	s_lshl_b32 s14, s31, 3
	s_and_b32 s14, s14, 56
	s_ashr_i32 s36, s31, 6
	s_add_i32 s14, s14, s36
	v_mov_b32_e32 v184, v192
	s_lshl_b32 s34, s14, 8
	s_lshl_b32 s14, s31, 4
	v_ashrrev_i32_e32 v0, 3, v184
	v_add_u32_e32 v2, s34, v0
	v_ashrrev_i32_e32 v3, 31, v2
	v_lshlrev_b64 v[2:3], 11, v[2:3]
	v_lshlrev_b32_e32 v1, 4, v184
	v_lshl_add_u64 v[2:3], s[86:87], 0, v[2:3]
	v_and_b32_e32 v176, 0x70, v1
	v_lshl_add_u64 v[2:3], v[2:3], 0, v[176:177]
	v_add_co_u32_e32 v6, vcc, s5, v2
	s_and_b32 s35, s14, 0x380
	s_nop 0
	v_addc_co_u32_e32 v7, vcc, 0, v3, vcc
	s_waitcnt vmcnt(6)
	v_add_co_u32_e32 v8, vcc, s16, v2
	v_add_u32_e32 v4, s35, v0
	s_nop 0
	v_addc_co_u32_e32 v9, vcc, 0, v3, vcc
	global_load_dwordx4 v[200:203], v[6:7], off
	global_load_dwordx4 v[204:207], v[8:9], off
	v_add_co_u32_e32 v6, vcc, s17, v2
	v_ashrrev_i32_e32 v5, 31, v4
	s_nop 0
	v_addc_co_u32_e32 v7, vcc, 0, v3, vcc
	v_add_co_u32_e32 v8, vcc, s20, v2
	v_lshlrev_b64 v[4:5], 11, v[4:5]
	s_nop 0
	v_addc_co_u32_e32 v9, vcc, 0, v3, vcc
	global_load_dwordx4 v[208:211], v[6:7], off
	global_load_dwordx4 v[212:215], v[8:9], off
	v_add_co_u32_e32 v6, vcc, s21, v2
	v_lshl_add_u64 v[4:5], s[22:23], 0, v[4:5]
	s_nop 0
	v_addc_co_u32_e32 v7, vcc, 0, v3, vcc
	v_add_co_u32_e32 v8, vcc, s24, v2
	v_lshl_add_u64 v[4:5], v[4:5], 0, v[176:177]
	s_nop 0
	v_addc_co_u32_e32 v9, vcc, 0, v3, vcc
	global_load_dwordx4 v[216:219], v[6:7], off
	global_load_dwordx4 v[220:223], v[8:9], off
	v_add_co_u32_e32 v6, vcc, s25, v2
	global_load_dwordx4 v[232:235], v[2:3], off
	global_load_dwordx4 v[224:227], v[4:5], off
	v_addc_co_u32_e32 v7, vcc, 0, v3, vcc
	v_add_co_u32_e32 v2, vcc, s5, v4
	s_lshl_b32 s2, s0, 8
	s_nop 0
	v_addc_co_u32_e32 v3, vcc, 0, v5, vcc
	global_load_dwordx4 v[236:239], v[6:7], off
	global_load_dwordx4 v[240:243], v[2:3], off
	v_add_co_u32_e32 v2, vcc, s16, v4
	v_mad_u64_u32 v[178:179], s[14:15], v0, s26, v[176:177]
	s_nop 0
	v_addc_co_u32_e32 v3, vcc, 0, v5, vcc
	v_add_co_u32_e32 v4, vcc, s17, v4
	s_and_b32 s2, s2, 0x3800
	s_nop 0
	v_addc_co_u32_e32 v5, vcc, 0, v5, vcc
	global_load_dwordx4 v[244:247], v[2:3], off
	global_load_dwordx4 v[248:251], v[4:5], off
	v_and_b32_e32 v1, 0xfffff9f, v184
	s_lshl_b32 s14, s36, 8
	v_lshrrev_b32_e32 v2, 1, v184
	v_mul_lo_u32 v5, v1, s26
	v_or_b32_e32 v1, 0x60, v184
	s_add_i32 s14, s14, s2
	s_lshl_b32 s6, s3, 11
	v_and_b32_e32 v4, 16, v2
	v_mul_lo_u32 v6, v1, s26
	v_add_u32_e32 v2, s14, v0
	v_ashrrev_i32_e32 v1, 31, v0
	s_and_b32 s6, s6, 0x1c0000
	v_ashrrev_i32_e32 v3, 31, v2
	v_lshlrev_b64 v[0:1], 11, v[0:1]
	v_lshlrev_b64 v[2:3], 11, v[2:3]
	v_lshl_add_u64 v[0:1], s[6:7], 0, v[0:1]
	v_and_b32_e32 v179, 0x5f, v184
	v_or_b32_e32 v2, v2, v176
	v_or_b32_e32 v0, v0, v176
	v_mad_u32_u24 v185, v179, s26, v4
	v_lshl_add_u64 v[180:181], s[86:87], 0, v[2:3]
	v_lshl_add_u64 v[182:183], s[86:87], 0, v[0:1]
	s_mov_b64 s[14:15], 0
	v_add_u32_e32 v186, v4, v5
	v_add_u32_e32 v176, v4, v6
	v_mov_b32_e32 v0, 0
	v_mov_b32_e32 v1, v177
	v_mov_b32_e32 v2, v177
	v_mov_b32_e32 v3, v177
	v_mov_b32_e32 v4, v177
	v_mov_b32_e32 v5, v177
	v_mov_b32_e32 v6, v177
	v_mov_b32_e32 v7, v177
	v_mov_b32_e32 v8, v177
	v_mov_b32_e32 v9, v177
	v_mov_b32_e32 v10, v177
	v_mov_b32_e32 v11, v177
	v_mov_b32_e32 v12, v177
	v_mov_b32_e32 v13, v177
	v_mov_b32_e32 v14, v177
	v_mov_b32_e32 v15, v177
	v_mov_b32_e32 v16, 0
	v_mov_b32_e32 v17, v177
	v_mov_b32_e32 v18, v177
	v_mov_b32_e32 v19, v177
	v_mov_b32_e32 v20, v177
	v_mov_b32_e32 v21, v177
	v_mov_b32_e32 v22, v177
	v_mov_b32_e32 v23, v177
	v_mov_b32_e32 v24, v177
	v_mov_b32_e32 v25, v177
	v_mov_b32_e32 v26, v177
	v_mov_b32_e32 v27, v177
	v_mov_b32_e32 v28, v177
	v_mov_b32_e32 v29, v177
	v_mov_b32_e32 v30, v177
	v_mov_b32_e32 v31, v177
	s_waitcnt vmcnt(17)
	v_mov_b32_e32 v32, 0
	v_mov_b32_e32 v33, v177
	v_mov_b32_e32 v34, v177
	v_mov_b32_e32 v35, v177
	v_mov_b32_e32 v36, v177
	v_mov_b32_e32 v37, v177
	v_mov_b32_e32 v38, v177
	v_mov_b32_e32 v39, v177
	v_mov_b32_e32 v40, v177
	v_mov_b32_e32 v41, v177
	v_mov_b32_e32 v42, v177
	v_mov_b32_e32 v43, v177
	v_mov_b32_e32 v44, v177
	v_mov_b32_e32 v45, v177
	v_mov_b32_e32 v46, v177
	v_mov_b32_e32 v47, v177
	v_mov_b32_e32 v48, 0
	v_mov_b32_e32 v49, v177
	v_mov_b32_e32 v50, v177
	v_mov_b32_e32 v51, v177
	v_mov_b32_e32 v52, v177
	v_mov_b32_e32 v53, v177
	v_mov_b32_e32 v54, v177
	v_mov_b32_e32 v55, v177
	v_mov_b32_e32 v56, v177
	v_mov_b32_e32 v57, v177
	v_mov_b32_e32 v58, v177
	v_mov_b32_e32 v59, v177
	v_mov_b32_e32 v60, v177
	v_mov_b32_e32 v61, v177
	v_mov_b32_e32 v62, v177
	v_mov_b32_e32 v63, v177
	v_mov_b32_e32 v64, 0
	v_mov_b32_e32 v65, v177
	v_mov_b32_e32 v66, v177
	v_mov_b32_e32 v67, v177
	v_mov_b32_e32 v68, v177
	v_mov_b32_e32 v69, v177
	v_mov_b32_e32 v70, v177
	v_mov_b32_e32 v71, v177
	v_mov_b32_e32 v72, v177
	v_mov_b32_e32 v73, v177
	v_mov_b32_e32 v74, v177
	v_mov_b32_e32 v75, v177
	v_mov_b32_e32 v76, v177
	v_mov_b32_e32 v77, v177
	v_mov_b32_e32 v78, v177
	v_mov_b32_e32 v79, v177
	v_mov_b32_e32 v80, 0
	v_mov_b32_e32 v81, v177
	v_mov_b32_e32 v82, v177
	v_mov_b32_e32 v83, v177
	v_mov_b32_e32 v84, v177
	v_mov_b32_e32 v85, v177
	v_mov_b32_e32 v86, v177
	v_mov_b32_e32 v87, v177
	v_mov_b32_e32 v88, v177
	v_mov_b32_e32 v89, v177
	v_mov_b32_e32 v90, v177
	v_mov_b32_e32 v91, v177
	v_mov_b32_e32 v92, v177
	v_mov_b32_e32 v93, v177
	v_mov_b32_e32 v94, v177
	v_mov_b32_e32 v95, v177
	v_mov_b32_e32 v96, 0
	v_mov_b32_e32 v97, v177
	v_mov_b32_e32 v98, v177
	v_mov_b32_e32 v99, v177
	v_mov_b32_e32 v100, v177
	v_mov_b32_e32 v101, v177
	v_mov_b32_e32 v102, v177
	v_mov_b32_e32 v103, v177
	v_mov_b32_e32 v104, v177
	v_mov_b32_e32 v105, v177
	v_mov_b32_e32 v106, v177
	v_mov_b32_e32 v107, v177
	v_mov_b32_e32 v108, v177
	v_mov_b32_e32 v109, v177
	v_mov_b32_e32 v110, v177
	v_mov_b32_e32 v111, v177
	v_mov_b32_e32 v112, 0
	v_mov_b32_e32 v113, v177
	v_mov_b32_e32 v114, v177
	v_mov_b32_e32 v115, v177
	v_mov_b32_e32 v116, v177
	v_mov_b32_e32 v117, v177
	v_mov_b32_e32 v118, v177
	v_mov_b32_e32 v119, v177
	v_mov_b32_e32 v120, v177
	v_mov_b32_e32 v121, v177
	v_mov_b32_e32 v122, v177
	v_mov_b32_e32 v123, v177
	v_mov_b32_e32 v124, v177
	v_mov_b32_e32 v125, v177
	v_mov_b32_e32 v126, v177
	v_mov_b32_e32 v127, v177
; #define MFMA32(a, b, c) __builtin_amdgcn_mfma_f32_32x32x16_bf16((a), (b), (c), 0, 0, 0)
; template <class Epi>
; DI void gemm256(const bf16_t* __restrict__ A, int lda, const bf16_t* __restrict__ B, int ldb, int K, int m0, int n0,
;                 bf16_t* sA, bf16_t* sB, Epi epi) {
;     ...
;   for (int kt = 0; kt < nk; ++kt) {
;     __syncthreads();
;     *(u32x4*)(sA + (lr) * LDS_ROW + lc) = ra0; *(u32x4*)(sA + (lr + 32) * LDS_ROW + lc) = ra1;
;     *(u32x4*)(sA + (lr + 64) * LDS_ROW + lc) = ra2; *(u32x4*)(sA + (lr + 96) * LDS_ROW + lc) = ra3;
;     *(u32x4*)(sA + (lr + 128) * LDS_ROW + lc) = ra4; *(u32x4*)(sA + (lr + 160) * LDS_ROW + lc) = ra5;
;     *(u32x4*)(sA + (lr + 192) * LDS_ROW + lc) = ra6; *(u32x4*)(sA + (lr + 224) * LDS_ROW + lc) = ra7;
;     *(u32x4*)(sB + (lr) * LDS_ROW + lc) = rb0; *(u32x4*)(sB + (lr + 32) * LDS_ROW + lc) = rb1;
;     *(u32x4*)(sB + (lr + 64) * LDS_ROW + lc) = rb2; *(u32x4*)(sB + (lr + 96) * LDS_ROW + lc) = rb3;
;     __syncthreads();
;     if (kt + 1 < nk) {
;       const int ko2 = (kt + 1) * 64;
;       G256_LOAD(ko2)
;     }
; #pragma unroll
;     for (int s = 0; s < 4; ++s) {
;       const int ko = s * 16 + (lane >> 5) * 8;
;       bf16x8 b0 = *(const bf16x8*)(sB + (wn * 64 + (lane & 31)) * LDS_ROW + ko);
;       bf16x8 b1 = *(const bf16x8*)(sB + (wn * 64 + 32 + (lane & 31)) * LDS_ROW + ko);
; #pragma unroll
;       for (int i = 0; i < 4; ++i) {
;         bf16x8 a = *(const bf16x8*)(sA + (wm * 128 + i * 32 + (lane & 31)) * LDS_ROW + ko);
;         acc[i][0] = MFMA32(a, b0, acc[i][0]);
;         acc[i][1] = MFMA32(a, b1, acc[i][1]);
;       }
;     }
;   }
.LBB0_1040:
	s_barrier
	s_waitcnt vmcnt(5)
	ds_write_b128 v178, v[232:235]
	ds_write_b128 v178, v[200:203] offset:4608
	ds_write_b128 v178, v[204:207] offset:9216
	ds_write_b128 v178, v[208:211] offset:13824
	ds_write_b128 v178, v[212:215] offset:18432
	ds_write_b128 v178, v[216:219] offset:23040
	ds_write_b128 v178, v[220:223] offset:27648
	s_waitcnt vmcnt(3)
	ds_write_b128 v178, v[236:239] offset:32256
	ds_write_b128 v178, v[224:227] offset:36864
	s_waitcnt vmcnt(2)
	ds_write_b128 v178, v[240:243] offset:41472
	s_waitcnt vmcnt(1)
	ds_write_b128 v178, v[244:247] offset:46080
	s_waitcnt vmcnt(0)
	ds_write_b128 v178, v[248:251] offset:50688
	s_waitcnt lgkmcnt(0)
	s_barrier
	v_lshl_add_u64 v[252:253], v[180:181], 0, s[14:15]
	v_lshl_add_u64 v[254:255], v[182:183], 0, s[14:15]
	ds_read_b128 v[128:131], v186
	ds_read_b128 v[132:135], v185 offset:36864
	ds_read_b128 v[136:139], v185 offset:36896
	ds_read_b128 v[140:143], v186 offset:32
	ds_read_b128 v[144:147], v185 offset:41472
	ds_read_b128 v[148:151], v185 offset:41504
	s_waitcnt lgkmcnt(4)
	v_mfma_f32_32x32x16_bf16 v[112:127], v[128:131], v[132:135], v[112:127]
	v_add_co_u32_e64 v198, s[98:99], s5, v252
	s_nop 0
	s_waitcnt lgkmcnt(1)
	v_mfma_f32_32x32x16_bf16 v[96:111], v[128:131], v[144:147], v[96:111]
	v_addc_co_u32_e64 v199, s[98:99], 0, v253, s[98:99]
	global_load_dwordx4 v[232:235], v[252:253], off offset:128
	global_load_dwordx4 v[200:203], v[198:199], off offset:128
	ds_read_b128 v[128:131], v186 offset:4608
	ds_read_b128 v[152:155], v186 offset:4640
	s_waitcnt lgkmcnt(1)
	v_mfma_f32_32x32x16_bf16 v[80:95], v[128:131], v[132:135], v[80:95]
	v_add_co_u32_e64 v228, vcc, s16, v252
	v_add_co_u32_e64 v198, s[98:99], s17, v252
	v_mfma_f32_32x32x16_bf16 v[64:79], v[128:131], v[144:147], v[64:79]
	v_addc_co_u32_e64 v229, vcc, 0, v253, vcc
	v_addc_co_u32_e64 v199, s[98:99], 0, v253, s[98:99]
	global_load_dwordx4 v[204:207], v[228:229], off offset:128
	global_load_dwordx4 v[208:211], v[198:199], off offset:128
	ds_read_b128 v[128:131], v186 offset:9216
	ds_read_b128 v[156:159], v186 offset:9248
	s_waitcnt lgkmcnt(1)
	v_mfma_f32_32x32x16_bf16 v[48:63], v[128:131], v[132:135], v[48:63]
	v_add_co_u32_e64 v228, vcc, s20, v252
	v_add_co_u32_e64 v198, s[98:99], s21, v252
	v_mfma_f32_32x32x16_bf16 v[32:47], v[128:131], v[144:147], v[32:47]
	v_addc_co_u32_e64 v229, vcc, 0, v253, vcc
	v_addc_co_u32_e64 v199, s[98:99], 0, v253, s[98:99]
	global_load_dwordx4 v[212:215], v[228:229], off offset:128
	global_load_dwordx4 v[216:219], v[198:199], off offset:128
	ds_read_b128 v[128:131], v176
	ds_read_b128 v[160:163], v176 offset:32
	s_waitcnt lgkmcnt(1)
	v_mfma_f32_32x32x16_bf16 v[16:31], v[128:131], v[132:135], v[16:31]
	v_add_co_u32_e64 v228, vcc, s24, v252
	v_add_co_u32_e64 v198, s[98:99], s25, v252
	v_mfma_f32_32x32x16_bf16 v[112:127], v[140:143], v[136:139], v[112:127]
	v_addc_co_u32_e64 v229, vcc, 0, v253, vcc
	v_addc_co_u32_e64 v199, s[98:99], 0, v253, s[98:99]
	global_load_dwordx4 v[220:223], v[228:229], off offset:128
	global_load_dwordx4 v[236:239], v[198:199], off offset:128
	v_mfma_f32_32x32x16_bf16 v[96:111], v[140:143], v[148:151], v[96:111]
	v_add_co_u32_e64 v228, vcc, s27, v254
	v_add_co_u32_e64 v198, s[98:99], s28, v254
	v_mfma_f32_32x32x16_bf16 v[0:15], v[128:131], v[144:147], v[0:15]
	v_addc_co_u32_e64 v229, vcc, 0, v255, vcc
	v_addc_co_u32_e64 v199, s[98:99], 0, v255, s[98:99]
	global_load_dwordx4 v[224:227], v[228:229], off offset:128
	global_load_dwordx4 v[240:243], v[198:199], off offset:128
	v_mfma_f32_32x32x16_bf16 v[80:95], v[152:155], v[136:139], v[80:95]
	v_add_co_u32_e64 v228, vcc, s29, v254
	v_add_co_u32_e64 v198, s[98:99], s30, v254
	v_mfma_f32_32x32x16_bf16 v[64:79], v[152:155], v[148:151], v[64:79]
	v_addc_co_u32_e64 v229, vcc, 0, v255, vcc
	v_addc_co_u32_e64 v199, s[98:99], 0, v255, s[98:99]
	global_load_dwordx4 v[244:247], v[228:229], off offset:128
	global_load_dwordx4 v[248:251], v[198:199], off offset:128
	v_mfma_f32_32x32x16_bf16 v[48:63], v[156:159], v[136:139], v[48:63]
	s_waitcnt lgkmcnt(0)
	v_mfma_f32_32x32x16_bf16 v[16:31], v[160:163], v[136:139], v[16:31]
	ds_read_b128 v[128:131], v186 offset:64
	ds_read_b128 v[132:135], v185 offset:36928
	ds_read_b128 v[172:175], v185 offset:36960
	ds_read_b128 v[136:139], v186 offset:96
	ds_read_b128 v[140:143], v185 offset:41536
	ds_read_b128 v[188:191], v185 offset:41568
	v_mfma_f32_32x32x16_bf16 v[32:47], v[156:159], v[148:151], v[32:47]
	s_waitcnt lgkmcnt(4)
	v_mfma_f32_32x32x16_bf16 v[112:127], v[128:131], v[132:135], v[112:127]
	s_waitcnt lgkmcnt(1)
	v_mfma_f32_32x32x16_bf16 v[96:111], v[128:131], v[140:143], v[96:111]
	ds_read_b128 v[128:131], v186 offset:4672
	ds_read_b128 v[144:147], v186 offset:4704
	v_mfma_f32_32x32x16_bf16 v[0:15], v[160:163], v[148:151], v[0:15]
	s_waitcnt lgkmcnt(1)
	v_mfma_f32_32x32x16_bf16 v[80:95], v[128:131], v[132:135], v[80:95]
	v_mfma_f32_32x32x16_bf16 v[64:79], v[128:131], v[140:143], v[64:79]
	ds_read_b128 v[128:131], v186 offset:9280
	ds_read_b128 v[148:151], v186 offset:9312
	s_waitcnt lgkmcnt(1)
	v_mfma_f32_32x32x16_bf16 v[48:63], v[128:131], v[132:135], v[48:63]
	v_mfma_f32_32x32x16_bf16 v[32:47], v[128:131], v[140:143], v[32:47]
	ds_read_b128 v[128:131], v176 offset:64
	ds_read_b128 v[194:197], v176 offset:96
	s_waitcnt lgkmcnt(1)
	v_mfma_f32_32x32x16_bf16 v[16:31], v[128:131], v[132:135], v[16:31]
	s_add_u32 s14, s14, 0x80
	s_addc_u32 s15, s15, 0
	s_cmpk_lg_i32 s14, 0x780
	v_mfma_f32_32x32x16_bf16 v[0:15], v[128:131], v[140:143], v[0:15]
	v_mfma_f32_32x32x16_bf16 v[112:127], v[136:139], v[172:175], v[112:127]
	v_mfma_f32_32x32x16_bf16 v[96:111], v[136:139], v[188:191], v[96:111]
	v_mfma_f32_32x32x16_bf16 v[80:95], v[144:147], v[172:175], v[80:95]
	v_mfma_f32_32x32x16_bf16 v[64:79], v[144:147], v[188:191], v[64:79]
	v_mfma_f32_32x32x16_bf16 v[48:63], v[148:151], v[172:175], v[48:63]
	v_mfma_f32_32x32x16_bf16 v[32:47], v[148:151], v[188:191], v[32:47]
	s_waitcnt lgkmcnt(0)
	v_mfma_f32_32x32x16_bf16 v[16:31], v[194:197], v[172:175], v[16:31]
	v_mfma_f32_32x32x16_bf16 v[0:15], v[194:197], v[188:191], v[0:15]
	s_cbranch_scc1 .LBB0_1040
; #define MFMA32(a, b, c) __builtin_amdgcn_mfma_f32_32x32x16_bf16((a), (b), (c), 0, 0, 0)
; DI int crow32(int r, int half) { return (r & 3) + 8 * (r >> 2) + 4 * half; }
; template <class Epi>
; DI void gemm256(const bf16_t* __restrict__ A, int lda, const bf16_t* __restrict__ B, int ldb, int K, int m0, int n0,
;                 bf16_t* sA, bf16_t* sB, Epi epi) {
;     ...
;     __syncthreads();
;     *(u32x4*)(sA + (lr) * LDS_ROW + lc) = ra0; *(u32x4*)(sA + (lr + 32) * LDS_ROW + lc) = ra1;
;     *(u32x4*)(sA + (lr + 64) * LDS_ROW + lc) = ra2; *(u32x4*)(sA + (lr + 96) * LDS_ROW + lc) = ra3;
;     *(u32x4*)(sA + (lr + 128) * LDS_ROW + lc) = ra4; *(u32x4*)(sA + (lr + 160) * LDS_ROW + lc) = ra5;
;     *(u32x4*)(sA + (lr + 192) * LDS_ROW + lc) = ra6; *(u32x4*)(sA + (lr + 224) * LDS_ROW + lc) = ra7;
;     *(u32x4*)(sB + (lr) * LDS_ROW + lc) = rb0; *(u32x4*)(sB + (lr + 32) * LDS_ROW + lc) = rb1;
;     *(u32x4*)(sB + (lr + 64) * LDS_ROW + lc) = rb2; *(u32x4*)(sB + (lr + 96) * LDS_ROW + lc) = rb3;
;     __syncthreads();
;     if (kt + 1 < nk) {
;       const int ko2 = (kt + 1) * 64;
;       G256_LOAD(ko2)
;     }
; #pragma unroll
;     for (int s = 0; s < 4; ++s) {
;       const int ko = s * 16 + (lane >> 5) * 8;
;       bf16x8 b0 = *(const bf16x8*)(sB + (wn * 64 + (lane & 31)) * LDS_ROW + ko);
;       bf16x8 b1 = *(const bf16x8*)(sB + (wn * 64 + 32 + (lane & 31)) * LDS_ROW + ko);
; #pragma unroll
;       for (int i = 0; i < 4; ++i) {
;         bf16x8 a = *(const bf16x8*)(sA + (wm * 128 + i * 32 + (lane & 31)) * LDS_ROW + ko);
;         acc[i][0] = MFMA32(a, b0, acc[i][0]);
;         acc[i][1] = MFMA32(a, b1, acc[i][1]);
;       }
;     }
;   }
;     ...
; #pragma unroll
;   for (int i = 0; i < 4; ++i)
; #pragma unroll
;     for (int j = 0; j < 2; ++j)
; #pragma unroll
;       for (int r = 0; r < 16; ++r) {
;         const int m = m0 + wm * 128 + i * 32 + crow32(r, lane >> 5);
;         const int n = n0 + wn * 64 + j * 32 + (lane & 31);
;         epi(m, n, acc[i][j][r]);
;       }
	s_barrier
	s_waitcnt vmcnt(11)
	ds_write_b128 v178, v[232:235]
	s_waitcnt vmcnt(10)
	ds_write_b128 v178, v[200:203] offset:4608
	s_waitcnt vmcnt(9)
	ds_write_b128 v178, v[204:207] offset:9216
	s_waitcnt vmcnt(8)
	ds_write_b128 v178, v[208:211] offset:13824
	s_waitcnt vmcnt(7)
	ds_write_b128 v178, v[212:215] offset:18432
	s_waitcnt vmcnt(6)
	ds_write_b128 v178, v[216:219] offset:23040
	s_waitcnt vmcnt(5)
	ds_write_b128 v178, v[220:223] offset:27648
	s_waitcnt vmcnt(4)
	ds_write_b128 v178, v[236:239] offset:32256
	s_waitcnt vmcnt(3)
	ds_write_b128 v178, v[224:227] offset:36864
	s_waitcnt vmcnt(2)
	ds_write_b128 v178, v[240:243] offset:41472
	s_waitcnt vmcnt(1)
	ds_write_b128 v178, v[244:247] offset:46080
	s_waitcnt vmcnt(0)
	ds_write_b128 v178, v[248:251] offset:50688
	s_waitcnt lgkmcnt(0)
	s_barrier
	ds_read_b128 v[128:131], v186
	ds_read_b128 v[144:147], v185 offset:36864
	ds_read_b128 v[148:151], v185 offset:36896
	ds_read_b128 v[152:155], v186 offset:32
	s_waitcnt lgkmcnt(2)
	v_mfma_f32_32x32x16_bf16 v[112:127], v[128:131], v[144:147], v[112:127]
	ds_read_b128 v[156:159], v185 offset:41472
	ds_read_b128 v[160:163], v185 offset:41504
	v_and_b32_e32 v140, 0xffffff80, v184
	v_lshrrev_b32_e32 v141, 3, v184
	v_add_u32_e32 v140, s34, v140
	v_and_or_b32 v142, v141, 4, v140
	v_or_b32_e32 v140, s35, v179
	v_ashrrev_i32_e32 v143, 31, v142
	s_waitcnt lgkmcnt(2)
	v_mfma_f32_32x32x16_bf16 v[112:127], v[152:155], v[148:151], v[112:127]
	v_lshlrev_b64 v[178:179], 11, v[142:143]
	v_or_b32_e32 v184, 2, v142
	s_add_i32 s31, s31, s88
	s_add_i32 s3, s3, s4
	s_waitcnt lgkmcnt(1)
	v_mfma_f32_32x32x16_bf16 v[96:111], v[128:131], v[156:159], v[96:111]
	ds_read_b128 v[128:131], v186 offset:4608
	ds_read_b128 v[164:167], v186 offset:4640
	ds_read_b128 v[168:171], v176
	ds_read_b128 v[172:175], v176 offset:32
	ds_read_b128 v[180:183], v186 offset:9216
	ds_read_b128 v[188:191], v186 offset:9248
	ds_read_b128 v[194:197], v186 offset:64
	ds_read_b128 v[198:201], v185 offset:36928
	ds_read_b128 v[132:135], v185 offset:36960
	s_waitcnt lgkmcnt(1)
	v_mfma_f32_32x32x16_bf16 v[112:127], v[194:197], v[198:201], v[112:127]
	v_mfma_f32_32x32x16_bf16 v[96:111], v[152:155], v[160:163], v[96:111]
	v_or_b32_e32 v152, 16, v142
	v_ashrrev_i32_e32 v153, 31, v152
	v_lshlrev_b64 v[152:153], 11, v[152:153]
	v_or_b32_e32 v154, 18, v142
	v_ashrrev_i32_e32 v155, 31, v154
	v_lshlrev_b64 v[154:155], 11, v[154:155]
	v_mfma_f32_32x32x16_bf16 v[80:95], v[128:131], v[144:147], v[80:95]
	v_mfma_f32_32x32x16_bf16 v[64:79], v[128:131], v[156:159], v[64:79]
	ds_read_b128 v[202:205], v185 offset:41536
	ds_read_b128 v[128:131], v185 offset:41568
	ds_read_b128 v[206:209], v186 offset:96
	ds_read_b128 v[210:213], v186 offset:4672
	ds_read_b128 v[214:217], v186 offset:4704
	ds_read_b128 v[218:221], v186 offset:9280
	ds_read_b128 v[222:225], v186 offset:9312
	ds_read_b128 v[226:229], v176 offset:64
	ds_read_b128 v[136:139], v176 offset:96
	v_lshlrev_b32_e32 v176, 1, v140
	v_lshl_add_u64 v[140:141], s[10:11], 0, v[176:177]
	v_lshl_add_u64 v[178:179], v[140:141], 0, v[178:179]
	v_ashrrev_i32_e32 v185, 31, v184
	v_lshl_add_u64 v[152:153], v[140:141], 0, v[152:153]
	s_waitcnt lgkmcnt(6)
	v_mfma_f32_32x32x16_bf16 v[112:127], v[206:209], v[132:135], v[112:127]
	v_lshl_add_u64 v[154:155], v[140:141], 0, v[154:155]
	v_mfma_f32_32x32x16_bf16 v[96:111], v[194:197], v[202:205], v[96:111]
	s_nop 9
	v_cvt_pk_bf16_f32 v112, v112, s0
	global_store_short v[178:179], v112, off
	v_or_b32_e32 v112, 1, v142
	v_cvt_pk_bf16_f32 v143, v113, s0
	v_ashrrev_i32_e32 v113, 31, v112
	v_lshlrev_b64 v[112:113], 11, v[112:113]
	v_cvt_pk_bf16_f32 v114, v114, s0
	v_mfma_f32_32x32x16_bf16 v[48:63], v[180:183], v[144:147], v[48:63]
	v_lshl_add_u64 v[112:113], v[140:141], 0, v[112:113]
	global_store_short v[112:113], v143, off
	v_cvt_pk_bf16_f32 v143, v115, s0
	v_cvt_pk_bf16_f32 v116, v116, s0
	v_cvt_pk_bf16_f32 v118, v118, s0
	v_cvt_pk_bf16_f32 v120, v120, s0
	global_store_short v[152:153], v120, off
	v_mfma_f32_32x32x16_bf16 v[32:47], v[180:183], v[156:159], v[32:47]
	v_lshlrev_b64 v[180:181], 11, v[184:185]
	v_lshl_add_u64 v[180:181], v[140:141], 0, v[180:181]
	global_store_short v[180:181], v114, off
	v_or_b32_e32 v114, 3, v142
	v_ashrrev_i32_e32 v115, 31, v114
	v_lshlrev_b64 v[114:115], 11, v[114:115]
	v_lshl_add_u64 v[114:115], v[140:141], 0, v[114:115]
	v_mfma_f32_32x32x16_bf16 v[96:111], v[206:209], v[128:131], v[96:111]
	global_store_short v[114:115], v143, off
	v_cvt_pk_bf16_f32 v143, v117, s0
	v_or_b32_e32 v120, 17, v142
	v_cvt_pk_bf16_f32 v122, v122, s0
	global_store_short v[154:155], v122, off
	v_or_b32_e32 v122, 19, v142
	v_cvt_pk_bf16_f32 v124, v124, s0
	v_mfma_f32_32x32x16_bf16 v[16:31], v[168:171], v[144:147], v[16:31]
	v_or_b32_e32 v144, 8, v142
	v_ashrrev_i32_e32 v145, 31, v144
	v_lshlrev_b64 v[144:145], 11, v[144:145]
	v_lshl_add_u64 v[144:145], v[140:141], 0, v[144:145]
	v_or_b32_e32 v146, 10, v142
	global_store_short v[144:145], v116, off
	v_or_b32_e32 v116, 9, v142
	v_mfma_f32_32x32x16_bf16 v[80:95], v[164:167], v[148:151], v[80:95]
	v_ashrrev_i32_e32 v147, 31, v146
	v_ashrrev_i32_e32 v117, 31, v116
	v_lshlrev_b64 v[146:147], 11, v[146:147]
	v_lshlrev_b64 v[116:117], 11, v[116:117]
	v_lshl_add_u64 v[146:147], v[140:141], 0, v[146:147]
	v_lshl_add_u64 v[116:117], v[140:141], 0, v[116:117]
	global_store_short v[146:147], v118, off
	v_or_b32_e32 v118, 11, v142
	v_cvt_pk_bf16_f32 v96, v96, s0
	global_store_short v[116:117], v143, off
	v_cvt_pk_bf16_f32 v143, v119, s0
	v_ashrrev_i32_e32 v119, 31, v118
	global_store_short v[178:179], v96, off offset:64
	v_cvt_pk_bf16_f32 v96, v97, s0
	v_lshlrev_b64 v[118:119], 11, v[118:119]
	global_store_short v[112:113], v96, off offset:64
	v_cvt_pk_bf16_f32 v96, v98, s0
	v_lshl_add_u64 v[118:119], v[140:141], 0, v[118:119]
	s_waitcnt lgkmcnt(5)
; DI bf16_t f2bf(float f) { return (bf16_t)(pk2(f, 0.f) & 0xffffu); }
; DI int crow32(int r, int half) { return (r & 3) + 8 * (r >> 2) + 4 * half; }
; template <class Epi>
; DI void gemm256(const bf16_t* __restrict__ A, int lda, const bf16_t* __restrict__ B, int ldb, int K, int m0, int n0,
;                 bf16_t* sA, bf16_t* sB, Epi epi) {
;     ...
; #pragma unroll
;   for (int i = 0; i < 4; ++i)
; #pragma unroll
;     for (int j = 0; j < 2; ++j)
; #pragma unroll
;       for (int r = 0; r < 16; ++r) {
;         const int m = m0 + wm * 128 + i * 32 + crow32(r, lane >> 5);
;         const int n = n0 + wn * 64 + j * 32 + (lane & 31);
;         epi(m, n, acc[i][j][r]);
;       }
; __global__ void __launch_bounds__(256, 2) hymba_mega(Params p) {
;     ...
;               [&](int m, int n, float v) { Qx[(size_t)m * 1024 + n] = f2bf(v); });
	v_mfma_f32_32x32x16_bf16 v[80:95], v[210:213], v[198:201], v[80:95]
	global_store_short v[180:181], v96, off offset:64
	v_cvt_pk_bf16_f32 v96, v99, s0
	global_store_short v[118:119], v143, off
	v_cvt_pk_bf16_f32 v143, v121, s0
	v_ashrrev_i32_e32 v121, 31, v120
	global_store_short v[114:115], v96, off offset:64
	v_cvt_pk_bf16_f32 v96, v100, s0
	v_mfma_f32_32x32x16_bf16 v[48:63], v[188:191], v[148:151], v[48:63]
	v_lshlrev_b64 v[120:121], 11, v[120:121]
	global_store_short v[144:145], v96, off offset:64
	v_cvt_pk_bf16_f32 v96, v101, s0
	v_lshl_add_u64 v[120:121], v[140:141], 0, v[120:121]
	global_store_short v[116:117], v96, off offset:64
	v_cvt_pk_bf16_f32 v96, v102, s0
	global_store_short v[120:121], v143, off
	v_mfma_f32_32x32x16_bf16 v[16:31], v[172:175], v[148:151], v[16:31]
	v_or_b32_e32 v148, 24, v142
	v_ashrrev_i32_e32 v149, 31, v148
	v_cvt_pk_bf16_f32 v143, v123, s0
	v_ashrrev_i32_e32 v123, 31, v122
	v_lshlrev_b64 v[148:149], 11, v[148:149]
	global_store_short v[146:147], v96, off offset:64
	v_cvt_pk_bf16_f32 v96, v103, s0
	v_lshlrev_b64 v[122:123], 11, v[122:123]
	v_lshl_add_u64 v[148:149], v[140:141], 0, v[148:149]
	v_or_b32_e32 v150, 26, v142
	global_store_short v[118:119], v96, off offset:64
	v_cvt_pk_bf16_f32 v96, v104, s0
	v_lshl_add_u64 v[122:123], v[140:141], 0, v[122:123]
	global_store_short v[148:149], v124, off
	v_or_b32_e32 v124, 25, v142
	v_ashrrev_i32_e32 v151, 31, v150
	global_store_short v[152:153], v96, off offset:64
	v_cvt_pk_bf16_f32 v96, v105, s0
	global_store_short v[122:123], v143, off
	v_cvt_pk_bf16_f32 v143, v125, s0
	v_ashrrev_i32_e32 v125, 31, v124
	v_lshlrev_b64 v[150:151], 11, v[150:151]
	global_store_short v[120:121], v96, off offset:64
	v_cvt_pk_bf16_f32 v96, v106, s0
	v_lshlrev_b64 v[124:125], 11, v[124:125]
	v_cvt_pk_bf16_f32 v126, v126, s0
	v_lshl_add_u64 v[150:151], v[140:141], 0, v[150:151]
	global_store_short v[154:155], v96, off offset:64
	v_cvt_pk_bf16_f32 v96, v107, s0
	s_waitcnt lgkmcnt(4)
	v_mfma_f32_32x32x16_bf16 v[80:95], v[214:217], v[132:135], v[80:95]
	v_lshl_add_u64 v[124:125], v[140:141], 0, v[124:125]
	global_store_short v[150:151], v126, off
	v_or_b32_e32 v126, 27, v142
	global_store_short v[122:123], v96, off offset:64
	v_cvt_pk_bf16_f32 v96, v108, s0
	global_store_short v[124:125], v143, off
	v_cvt_pk_bf16_f32 v143, v127, s0
	v_ashrrev_i32_e32 v127, 31, v126
	global_store_short v[148:149], v96, off offset:64
	v_cvt_pk_bf16_f32 v96, v109, s0
	v_lshlrev_b64 v[126:127], 11, v[126:127]
	global_store_short v[124:125], v96, off offset:64
	v_cvt_pk_bf16_f32 v96, v110, s0
	v_lshl_add_u64 v[126:127], v[140:141], 0, v[126:127]
	global_store_short v[150:151], v96, off offset:64
	v_cvt_pk_bf16_f32 v96, v111, s0
	global_store_short v[126:127], v96, off offset:64
	v_or_b32_e32 v96, 32, v142
	v_ashrrev_i32_e32 v97, 31, v96
	v_lshlrev_b64 v[96:97], 11, v[96:97]
	v_cvt_pk_bf16_f32 v80, v80, s0
	v_lshl_add_u64 v[96:97], v[140:141], 0, v[96:97]
	global_store_short v[96:97], v80, off
	v_or_b32_e32 v80, 33, v142
	v_cvt_pk_bf16_f32 v98, v81, s0
	v_ashrrev_i32_e32 v81, 31, v80
	v_lshlrev_b64 v[80:81], 11, v[80:81]
	v_lshl_add_u64 v[80:81], v[140:141], 0, v[80:81]
	global_store_short v[80:81], v98, off
	v_or_b32_e32 v98, 34, v142
	v_ashrrev_i32_e32 v99, 31, v98
	v_lshlrev_b64 v[98:99], 11, v[98:99]
	v_cvt_pk_bf16_f32 v82, v82, s0
	v_lshl_add_u64 v[98:99], v[140:141], 0, v[98:99]
	global_store_short v[98:99], v82, off
	v_or_b32_e32 v82, 35, v142
	v_cvt_pk_bf16_f32 v100, v83, s0
	v_ashrrev_i32_e32 v83, 31, v82
	v_lshlrev_b64 v[82:83], 11, v[82:83]
	v_lshl_add_u64 v[82:83], v[140:141], 0, v[82:83]
	global_store_short v[82:83], v100, off
	v_or_b32_e32 v100, 40, v142
	v_ashrrev_i32_e32 v101, 31, v100
	v_lshlrev_b64 v[100:101], 11, v[100:101]
	v_cvt_pk_bf16_f32 v84, v84, s0
	v_lshl_add_u64 v[100:101], v[140:141], 0, v[100:101]
	global_store_short v[100:101], v84, off
	v_or_b32_e32 v84, 41, v142
	v_cvt_pk_bf16_f32 v102, v85, s0
	v_ashrrev_i32_e32 v85, 31, v84
	v_lshlrev_b64 v[84:85], 11, v[84:85]
	v_lshl_add_u64 v[84:85], v[140:141], 0, v[84:85]
	v_mfma_f32_32x32x16_bf16 v[64:79], v[164:167], v[160:163], v[64:79]
	global_store_short v[84:85], v102, off
	v_or_b32_e32 v102, 42, v142
	v_ashrrev_i32_e32 v103, 31, v102
	v_lshlrev_b64 v[102:103], 11, v[102:103]
	v_cvt_pk_bf16_f32 v86, v86, s0
	v_lshl_add_u64 v[102:103], v[140:141], 0, v[102:103]
	global_store_short v[102:103], v86, off
	v_or_b32_e32 v86, 43, v142
	v_cvt_pk_bf16_f32 v104, v87, s0
	v_ashrrev_i32_e32 v87, 31, v86
	v_lshlrev_b64 v[86:87], 11, v[86:87]
	v_lshl_add_u64 v[86:87], v[140:141], 0, v[86:87]
	v_mfma_f32_32x32x16_bf16 v[64:79], v[210:213], v[202:205], v[64:79]
	global_store_short v[86:87], v104, off
	v_or_b32_e32 v104, 48, v142
	v_ashrrev_i32_e32 v105, 31, v104
	v_lshlrev_b64 v[104:105], 11, v[104:105]
	v_cvt_pk_bf16_f32 v88, v88, s0
	v_lshl_add_u64 v[104:105], v[140:141], 0, v[104:105]
	global_store_short v[104:105], v88, off
	v_or_b32_e32 v88, 49, v142
	v_cvt_pk_bf16_f32 v106, v89, s0
	v_ashrrev_i32_e32 v89, 31, v88
	v_lshlrev_b64 v[88:89], 11, v[88:89]
	v_lshl_add_u64 v[88:89], v[140:141], 0, v[88:89]
	v_mfma_f32_32x32x16_bf16 v[64:79], v[214:217], v[128:131], v[64:79]
	global_store_short v[88:89], v106, off
	v_or_b32_e32 v106, 50, v142
	v_ashrrev_i32_e32 v107, 31, v106
	v_lshlrev_b64 v[106:107], 11, v[106:107]
	v_cvt_pk_bf16_f32 v90, v90, s0
	v_lshl_add_u64 v[106:107], v[140:141], 0, v[106:107]
	global_store_short v[106:107], v90, off
	v_or_b32_e32 v90, 51, v142
	v_cvt_pk_bf16_f32 v108, v91, s0
	v_ashrrev_i32_e32 v91, 31, v90
	v_lshlrev_b64 v[90:91], 11, v[90:91]
	v_lshl_add_u64 v[90:91], v[140:141], 0, v[90:91]
	global_store_short v[90:91], v108, off
	v_or_b32_e32 v108, 56, v142
	v_cvt_pk_bf16_f32 v64, v64, s0
	v_ashrrev_i32_e32 v109, 31, v108
	global_store_short v[96:97], v64, off offset:64
	v_cvt_pk_bf16_f32 v64, v65, s0
	v_lshlrev_b64 v[108:109], 11, v[108:109]
	global_store_short v[80:81], v64, off offset:64
	v_cvt_pk_bf16_f32 v64, v66, s0
	s_waitcnt lgkmcnt(3)
; DI bf16_t f2bf(float f) { return (bf16_t)(pk2(f, 0.f) & 0xffffu); }
; DI int crow32(int r, int half) { return (r & 3) + 8 * (r >> 2) + 4 * half; }
; template <class Epi>
; DI void gemm256(const bf16_t* __restrict__ A, int lda, const bf16_t* __restrict__ B, int ldb, int K, int m0, int n0,
;                 bf16_t* sA, bf16_t* sB, Epi epi) {
;     ...
; #pragma unroll
;   for (int i = 0; i < 4; ++i)
; #pragma unroll
;     for (int j = 0; j < 2; ++j)
; #pragma unroll
;       for (int r = 0; r < 16; ++r) {
;         const int m = m0 + wm * 128 + i * 32 + crow32(r, lane >> 5);
;         const int n = n0 + wn * 64 + j * 32 + (lane & 31);
;         epi(m, n, acc[i][j][r]);
;       }
; __global__ void __launch_bounds__(256, 2) hymba_mega(Params p) {
;     ...
;               [&](int m, int n, float v) { Qx[(size_t)m * 1024 + n] = f2bf(v); });
	v_mfma_f32_32x32x16_bf16 v[48:63], v[218:221], v[198:201], v[48:63]
	v_cvt_pk_bf16_f32 v92, v92, s0
	v_lshl_add_u64 v[108:109], v[140:141], 0, v[108:109]
	global_store_short v[98:99], v64, off offset:64
	v_cvt_pk_bf16_f32 v64, v67, s0
	global_store_short v[108:109], v92, off
	v_or_b32_e32 v92, 57, v142
	global_store_short v[82:83], v64, off offset:64
	v_cvt_pk_bf16_f32 v64, v68, s0
	v_cvt_pk_bf16_f32 v110, v93, s0
	v_ashrrev_i32_e32 v93, 31, v92
	global_store_short v[100:101], v64, off offset:64
	v_cvt_pk_bf16_f32 v64, v69, s0
	v_lshlrev_b64 v[92:93], 11, v[92:93]
	global_store_short v[84:85], v64, off offset:64
	v_cvt_pk_bf16_f32 v64, v70, s0
	v_lshl_add_u64 v[92:93], v[140:141], 0, v[92:93]
	global_store_short v[102:103], v64, off offset:64
	v_cvt_pk_bf16_f32 v64, v71, s0
	global_store_short v[92:93], v110, off
	v_or_b32_e32 v110, 58, v142
	global_store_short v[86:87], v64, off offset:64
	v_cvt_pk_bf16_f32 v64, v72, s0
	v_ashrrev_i32_e32 v111, 31, v110
	global_store_short v[104:105], v64, off offset:64
	v_cvt_pk_bf16_f32 v64, v73, s0
	v_lshlrev_b64 v[110:111], 11, v[110:111]
	global_store_short v[88:89], v64, off offset:64
	v_cvt_pk_bf16_f32 v64, v74, s0
	s_waitcnt lgkmcnt(2)
	v_mfma_f32_32x32x16_bf16 v[48:63], v[222:225], v[132:135], v[48:63]
	v_cvt_pk_bf16_f32 v94, v94, s0
	v_lshl_add_u64 v[110:111], v[140:141], 0, v[110:111]
	global_store_short v[106:107], v64, off offset:64
	v_cvt_pk_bf16_f32 v64, v75, s0
	global_store_short v[110:111], v94, off
	v_or_b32_e32 v94, 59, v142
	global_store_short v[90:91], v64, off offset:64
	v_cvt_pk_bf16_f32 v64, v76, s0
	v_cvt_pk_bf16_f32 v112, v95, s0
	v_ashrrev_i32_e32 v95, 31, v94
	global_store_short v[108:109], v64, off offset:64
	v_cvt_pk_bf16_f32 v64, v77, s0
	v_lshlrev_b64 v[94:95], 11, v[94:95]
	global_store_short v[92:93], v64, off offset:64
	v_cvt_pk_bf16_f32 v64, v78, s0
	v_lshl_add_u64 v[94:95], v[140:141], 0, v[94:95]
	global_store_short v[110:111], v64, off offset:64
	v_cvt_pk_bf16_f32 v64, v79, s0
	global_store_short v[94:95], v64, off offset:64
	v_or_b32_e32 v64, 64, v142
	v_ashrrev_i32_e32 v65, 31, v64
	v_lshlrev_b64 v[64:65], 11, v[64:65]
	v_cvt_pk_bf16_f32 v48, v48, s0
	v_lshl_add_u64 v[64:65], v[140:141], 0, v[64:65]
	global_store_short v[64:65], v48, off
	v_or_b32_e32 v48, 0x41, v142
	v_cvt_pk_bf16_f32 v66, v49, s0
	v_ashrrev_i32_e32 v49, 31, v48
	v_lshlrev_b64 v[48:49], 11, v[48:49]
	v_lshl_add_u64 v[48:49], v[140:141], 0, v[48:49]
	global_store_short v[48:49], v66, off
	v_or_b32_e32 v66, 0x42, v142
	v_ashrrev_i32_e32 v67, 31, v66
	v_lshlrev_b64 v[66:67], 11, v[66:67]
	v_cvt_pk_bf16_f32 v50, v50, s0
	v_lshl_add_u64 v[66:67], v[140:141], 0, v[66:67]
	global_store_short v[66:67], v50, off
	v_or_b32_e32 v50, 0x43, v142
	v_cvt_pk_bf16_f32 v68, v51, s0
	v_ashrrev_i32_e32 v51, 31, v50
	v_lshlrev_b64 v[50:51], 11, v[50:51]
	v_lshl_add_u64 v[50:51], v[140:141], 0, v[50:51]
	global_store_short v[50:51], v68, off
	v_or_b32_e32 v68, 0x48, v142
	v_ashrrev_i32_e32 v69, 31, v68
	v_lshlrev_b64 v[68:69], 11, v[68:69]
	v_cvt_pk_bf16_f32 v52, v52, s0
	v_lshl_add_u64 v[68:69], v[140:141], 0, v[68:69]
	global_store_short v[68:69], v52, off
	v_or_b32_e32 v52, 0x49, v142
	v_cvt_pk_bf16_f32 v70, v53, s0
	v_ashrrev_i32_e32 v53, 31, v52
	v_lshlrev_b64 v[52:53], 11, v[52:53]
	v_lshl_add_u64 v[52:53], v[140:141], 0, v[52:53]
	v_mfma_f32_32x32x16_bf16 v[32:47], v[188:191], v[160:163], v[32:47]
	global_store_short v[52:53], v70, off
	v_or_b32_e32 v70, 0x4a, v142
	v_ashrrev_i32_e32 v71, 31, v70
	v_lshlrev_b64 v[70:71], 11, v[70:71]
	v_cvt_pk_bf16_f32 v54, v54, s0
	v_lshl_add_u64 v[70:71], v[140:141], 0, v[70:71]
	global_store_short v[70:71], v54, off
	v_or_b32_e32 v54, 0x4b, v142
	v_cvt_pk_bf16_f32 v72, v55, s0
	v_ashrrev_i32_e32 v55, 31, v54
	v_lshlrev_b64 v[54:55], 11, v[54:55]
	v_lshl_add_u64 v[54:55], v[140:141], 0, v[54:55]
	v_mfma_f32_32x32x16_bf16 v[32:47], v[218:221], v[202:205], v[32:47]
	global_store_short v[54:55], v72, off
	v_or_b32_e32 v72, 0x50, v142
	v_ashrrev_i32_e32 v73, 31, v72
	v_lshlrev_b64 v[72:73], 11, v[72:73]
	v_cvt_pk_bf16_f32 v56, v56, s0
	v_lshl_add_u64 v[72:73], v[140:141], 0, v[72:73]
	global_store_short v[72:73], v56, off
	v_or_b32_e32 v56, 0x51, v142
	v_cvt_pk_bf16_f32 v74, v57, s0
	v_ashrrev_i32_e32 v57, 31, v56
	v_lshlrev_b64 v[56:57], 11, v[56:57]
	v_lshl_add_u64 v[56:57], v[140:141], 0, v[56:57]
	v_mfma_f32_32x32x16_bf16 v[32:47], v[222:225], v[128:131], v[32:47]
	global_store_short v[56:57], v74, off
	v_or_b32_e32 v74, 0x52, v142
	v_ashrrev_i32_e32 v75, 31, v74
	v_lshlrev_b64 v[74:75], 11, v[74:75]
	v_cvt_pk_bf16_f32 v58, v58, s0
	v_lshl_add_u64 v[74:75], v[140:141], 0, v[74:75]
	global_store_short v[74:75], v58, off
	v_or_b32_e32 v58, 0x53, v142
	v_cvt_pk_bf16_f32 v76, v59, s0
	v_ashrrev_i32_e32 v59, 31, v58
	v_lshlrev_b64 v[58:59], 11, v[58:59]
	v_lshl_add_u64 v[58:59], v[140:141], 0, v[58:59]
	global_store_short v[58:59], v76, off
	v_or_b32_e32 v76, 0x58, v142
	v_cvt_pk_bf16_f32 v32, v32, s0
	v_ashrrev_i32_e32 v77, 31, v76
	global_store_short v[64:65], v32, off offset:64
	v_cvt_pk_bf16_f32 v32, v33, s0
	v_lshlrev_b64 v[76:77], 11, v[76:77]
	global_store_short v[48:49], v32, off offset:64
	v_cvt_pk_bf16_f32 v32, v34, s0
	s_waitcnt lgkmcnt(1)
; DI bf16_t f2bf(float f) { return (bf16_t)(pk2(f, 0.f) & 0xffffu); }
; DI int crow32(int r, int half) { return (r & 3) + 8 * (r >> 2) + 4 * half; }
; template <class Epi>
; DI void gemm256(const bf16_t* __restrict__ A, int lda, const bf16_t* __restrict__ B, int ldb, int K, int m0, int n0,
;                 bf16_t* sA, bf16_t* sB, Epi epi) {
;     ...
; #pragma unroll
;   for (int i = 0; i < 4; ++i)
; #pragma unroll
;     for (int j = 0; j < 2; ++j)
; #pragma unroll
;       for (int r = 0; r < 16; ++r) {
;         const int m = m0 + wm * 128 + i * 32 + crow32(r, lane >> 5);
;         const int n = n0 + wn * 64 + j * 32 + (lane & 31);
;         epi(m, n, acc[i][j][r]);
;       }
; __global__ void __launch_bounds__(256, 2) hymba_mega(Params p) {
;     ...
;               [&](int m, int n, float v) { Qx[(size_t)m * 1024 + n] = f2bf(v); });
	v_mfma_f32_32x32x16_bf16 v[16:31], v[226:229], v[198:201], v[16:31]
	v_cvt_pk_bf16_f32 v60, v60, s0
	v_lshl_add_u64 v[76:77], v[140:141], 0, v[76:77]
	global_store_short v[66:67], v32, off offset:64
	v_cvt_pk_bf16_f32 v32, v35, s0
	global_store_short v[76:77], v60, off
	v_or_b32_e32 v60, 0x59, v142
	global_store_short v[50:51], v32, off offset:64
	v_cvt_pk_bf16_f32 v32, v36, s0
	v_cvt_pk_bf16_f32 v78, v61, s0
	v_ashrrev_i32_e32 v61, 31, v60
	global_store_short v[68:69], v32, off offset:64
	v_cvt_pk_bf16_f32 v32, v37, s0
	v_lshlrev_b64 v[60:61], 11, v[60:61]
	global_store_short v[52:53], v32, off offset:64
	v_cvt_pk_bf16_f32 v32, v38, s0
	v_lshl_add_u64 v[60:61], v[140:141], 0, v[60:61]
	global_store_short v[70:71], v32, off offset:64
	v_cvt_pk_bf16_f32 v32, v39, s0
	global_store_short v[60:61], v78, off
	v_or_b32_e32 v78, 0x5a, v142
	global_store_short v[54:55], v32, off offset:64
	v_cvt_pk_bf16_f32 v32, v40, s0
	v_ashrrev_i32_e32 v79, 31, v78
	global_store_short v[72:73], v32, off offset:64
	v_cvt_pk_bf16_f32 v32, v41, s0
	v_lshlrev_b64 v[78:79], 11, v[78:79]
	global_store_short v[56:57], v32, off offset:64
	v_cvt_pk_bf16_f32 v32, v42, s0
	s_waitcnt lgkmcnt(0)
; DI bf16_t f2bf(float f) { return (bf16_t)(pk2(f, 0.f) & 0xffffu); }
; DI int crow32(int r, int half) { return (r & 3) + 8 * (r >> 2) + 4 * half; }
; template <class Epi>
; DI void gemm256(const bf16_t* __restrict__ A, int lda, const bf16_t* __restrict__ B, int ldb, int K, int m0, int n0,
;                 bf16_t* sA, bf16_t* sB, Epi epi) {
;     ...
; #pragma unroll
;   for (int i = 0; i < 4; ++i)
; #pragma unroll
;     for (int j = 0; j < 2; ++j)
; #pragma unroll
;       for (int r = 0; r < 16; ++r) {
;         const int m = m0 + wm * 128 + i * 32 + crow32(r, lane >> 5);
;         const int n = n0 + wn * 64 + j * 32 + (lane & 31);
;         epi(m, n, acc[i][j][r]);
;       }
; __global__ void __launch_bounds__(256, 2) hymba_mega(Params p) {
;     ...
;     for (int tile = blockIdx.x; tile < 64 * 8; tile += gridDim.x) {
;       const int mt = (tile & 7) * 8 + (tile >> 6), nt = (tile >> 3) & 7;
;       gemm256((const bf16_t*)(ws + OFF_H2), 1024, (const bf16_t*)(ws + OFF_WQT), 1024, 1024, mt * 256, nt * 128, sA, (bf16_t*)(smem + 36864),
;               [&](int m, int n, float v) { Qx[(size_t)m * 1024 + n] = f2bf(v); });
;     }
	v_mfma_f32_32x32x16_bf16 v[16:31], v[136:139], v[132:135], v[16:31]
	v_cvt_pk_bf16_f32 v62, v62, s0
	v_lshl_add_u64 v[78:79], v[140:141], 0, v[78:79]
	global_store_short v[74:75], v32, off offset:64
	v_cvt_pk_bf16_f32 v32, v43, s0
	global_store_short v[78:79], v62, off
	v_or_b32_e32 v62, 0x5b, v142
	global_store_short v[58:59], v32, off offset:64
	v_cvt_pk_bf16_f32 v32, v44, s0
	v_cvt_pk_bf16_f32 v80, v63, s0
	v_ashrrev_i32_e32 v63, 31, v62
	global_store_short v[76:77], v32, off offset:64
	v_cvt_pk_bf16_f32 v32, v45, s0
	v_lshlrev_b64 v[62:63], 11, v[62:63]
	global_store_short v[60:61], v32, off offset:64
	v_cvt_pk_bf16_f32 v32, v46, s0
	v_lshl_add_u64 v[62:63], v[140:141], 0, v[62:63]
	global_store_short v[78:79], v32, off offset:64
	v_cvt_pk_bf16_f32 v32, v47, s0
	global_store_short v[62:63], v32, off offset:64
	v_or_b32_e32 v32, 0x60, v142
	v_ashrrev_i32_e32 v33, 31, v32
	v_lshlrev_b64 v[32:33], 11, v[32:33]
	v_cvt_pk_bf16_f32 v16, v16, s0
	v_lshl_add_u64 v[32:33], v[140:141], 0, v[32:33]
	global_store_short v[32:33], v16, off
	v_or_b32_e32 v16, 0x61, v142
	v_cvt_pk_bf16_f32 v34, v17, s0
	v_ashrrev_i32_e32 v17, 31, v16
	v_lshlrev_b64 v[16:17], 11, v[16:17]
	v_lshl_add_u64 v[16:17], v[140:141], 0, v[16:17]
	global_store_short v[16:17], v34, off
	v_or_b32_e32 v34, 0x62, v142
	v_ashrrev_i32_e32 v35, 31, v34
	v_lshlrev_b64 v[34:35], 11, v[34:35]
	v_cvt_pk_bf16_f32 v18, v18, s0
	v_lshl_add_u64 v[34:35], v[140:141], 0, v[34:35]
	global_store_short v[34:35], v18, off
	v_or_b32_e32 v18, 0x63, v142
	v_cvt_pk_bf16_f32 v36, v19, s0
	v_ashrrev_i32_e32 v19, 31, v18
	v_lshlrev_b64 v[18:19], 11, v[18:19]
	v_mfma_f32_32x32x16_bf16 v[0:15], v[168:171], v[156:159], v[0:15]
	v_lshl_add_u64 v[18:19], v[140:141], 0, v[18:19]
	global_store_short v[18:19], v36, off
	v_or_b32_e32 v36, 0x68, v142
	v_ashrrev_i32_e32 v37, 31, v36
	v_lshlrev_b64 v[36:37], 11, v[36:37]
	v_cvt_pk_bf16_f32 v20, v20, s0
	v_lshl_add_u64 v[36:37], v[140:141], 0, v[36:37]
	global_store_short v[36:37], v20, off
	v_or_b32_e32 v20, 0x69, v142
	v_cvt_pk_bf16_f32 v38, v21, s0
	v_ashrrev_i32_e32 v21, 31, v20
	v_lshlrev_b64 v[20:21], 11, v[20:21]
	v_mfma_f32_32x32x16_bf16 v[0:15], v[172:175], v[160:163], v[0:15]
	v_lshl_add_u64 v[20:21], v[140:141], 0, v[20:21]
	global_store_short v[20:21], v38, off
	v_or_b32_e32 v38, 0x6a, v142
	v_ashrrev_i32_e32 v39, 31, v38
	v_lshlrev_b64 v[38:39], 11, v[38:39]
	v_cvt_pk_bf16_f32 v22, v22, s0
	v_lshl_add_u64 v[38:39], v[140:141], 0, v[38:39]
	global_store_short v[38:39], v22, off
	v_or_b32_e32 v22, 0x6b, v142
	v_cvt_pk_bf16_f32 v40, v23, s0
	v_ashrrev_i32_e32 v23, 31, v22
	v_lshlrev_b64 v[22:23], 11, v[22:23]
	v_mfma_f32_32x32x16_bf16 v[0:15], v[226:229], v[202:205], v[0:15]
	v_lshl_add_u64 v[22:23], v[140:141], 0, v[22:23]
	global_store_short v[22:23], v40, off
	v_or_b32_e32 v40, 0x70, v142
	v_ashrrev_i32_e32 v41, 31, v40
	v_lshlrev_b64 v[40:41], 11, v[40:41]
	v_cvt_pk_bf16_f32 v24, v24, s0
	v_lshl_add_u64 v[40:41], v[140:141], 0, v[40:41]
	global_store_short v[40:41], v24, off
	v_or_b32_e32 v24, 0x71, v142
	v_cvt_pk_bf16_f32 v42, v25, s0
	v_ashrrev_i32_e32 v25, 31, v24
	v_lshlrev_b64 v[24:25], 11, v[24:25]
	v_mfma_f32_32x32x16_bf16 v[0:15], v[136:139], v[128:131], v[0:15]
	v_lshl_add_u64 v[24:25], v[140:141], 0, v[24:25]
	global_store_short v[24:25], v42, off
	v_or_b32_e32 v42, 0x72, v142
	v_ashrrev_i32_e32 v43, 31, v42
	v_lshlrev_b64 v[42:43], 11, v[42:43]
	v_cvt_pk_bf16_f32 v26, v26, s0
	v_lshl_add_u64 v[42:43], v[140:141], 0, v[42:43]
	global_store_short v[42:43], v26, off
	v_or_b32_e32 v26, 0x73, v142
	v_cvt_pk_bf16_f32 v44, v27, s0
	v_ashrrev_i32_e32 v27, 31, v26
	v_lshlrev_b64 v[26:27], 11, v[26:27]
	v_lshl_add_u64 v[26:27], v[140:141], 0, v[26:27]
	v_cvt_pk_bf16_f32 v0, v0, s0
	global_store_short v[26:27], v44, off
	v_or_b32_e32 v44, 0x78, v142
	global_store_short v[32:33], v0, off offset:64
	v_cvt_pk_bf16_f32 v0, v1, s0
	v_ashrrev_i32_e32 v45, 31, v44
	global_store_short v[16:17], v0, off offset:64
	v_cvt_pk_bf16_f32 v0, v2, s0
	v_lshlrev_b64 v[44:45], 11, v[44:45]
	global_store_short v[34:35], v0, off offset:64
	v_cvt_pk_bf16_f32 v0, v3, s0
	v_cvt_pk_bf16_f32 v28, v28, s0
	v_lshl_add_u64 v[44:45], v[140:141], 0, v[44:45]
	global_store_short v[18:19], v0, off offset:64
	v_cvt_pk_bf16_f32 v0, v4, s0
	global_store_short v[44:45], v28, off
	v_or_b32_e32 v28, 0x79, v142
	global_store_short v[36:37], v0, off offset:64
	v_cvt_pk_bf16_f32 v0, v5, s0
	v_cvt_pk_bf16_f32 v46, v29, s0
	v_ashrrev_i32_e32 v29, 31, v28
	global_store_short v[20:21], v0, off offset:64
	v_cvt_pk_bf16_f32 v0, v6, s0
	v_lshlrev_b64 v[28:29], 11, v[28:29]
	global_store_short v[38:39], v0, off offset:64
	v_cvt_pk_bf16_f32 v0, v7, s0
	v_lshl_add_u64 v[28:29], v[140:141], 0, v[28:29]
	global_store_short v[22:23], v0, off offset:64
	v_cvt_pk_bf16_f32 v0, v8, s0
	global_store_short v[28:29], v46, off
	v_or_b32_e32 v46, 0x7a, v142
	global_store_short v[40:41], v0, off offset:64
	v_cvt_pk_bf16_f32 v0, v9, s0
	v_ashrrev_i32_e32 v47, 31, v46
	global_store_short v[24:25], v0, off offset:64
	v_cvt_pk_bf16_f32 v0, v10, s0
	v_lshlrev_b64 v[46:47], 11, v[46:47]
	global_store_short v[42:43], v0, off offset:64
	v_cvt_pk_bf16_f32 v0, v11, s0
	v_cvt_pk_bf16_f32 v30, v30, s0
	v_lshl_add_u64 v[46:47], v[140:141], 0, v[46:47]
	global_store_short v[26:27], v0, off offset:64
	v_cvt_pk_bf16_f32 v0, v12, s0
	global_store_short v[46:47], v30, off
	v_or_b32_e32 v30, 0x7b, v142
	global_store_short v[44:45], v0, off offset:64
	v_cvt_pk_bf16_f32 v0, v13, s0
	v_cvt_pk_bf16_f32 v48, v31, s0
	v_ashrrev_i32_e32 v31, 31, v30
	global_store_short v[28:29], v0, off offset:64
	v_cvt_pk_bf16_f32 v0, v14, s0
	v_lshlrev_b64 v[30:31], 11, v[30:31]
	global_store_short v[46:47], v0, off offset:64
	v_cvt_pk_bf16_f32 v0, v15, s0
	s_add_i32 s0, s0, s1
	v_lshl_add_u64 v[30:31], v[140:141], 0, v[30:31]
	s_cmpk_gt_i32 s31, 0x1ff
	global_store_short v[126:127], v143, off
	global_store_short v[94:95], v112, off
	global_store_short v[62:63], v80, off
	global_store_short v[30:31], v48, off
	global_store_short v[30:31], v0, off offset:64
	s_cbranch_scc0 .LBB0_1039

; DI int otid() { int t = threadIdx.x; asm volatile("" : "+v"(t)); return t; }
; template <class Epi>
; DI void gemm256(const bf16_t* __restrict__ A, int lda, const bf16_t* __restrict__ B, int ldb, int K, int m0, int n0,
;                 bf16_t* sA, bf16_t* sB, Epi epi) {
;   const int tid = otid(), lane = tid & 63, wave = tid >> 6;
;   const int wm = wave >> 1, wn = wave & 1;
;   const int lr = tid >> 3, lc = (tid & 7) * 8;
;   f32x16 acc[4][2];
; #pragma unroll
;   for (int i = 0; i < 4; ++i)
; #pragma unroll
;     for (int j = 0; j < 2; ++j)
; #pragma unroll
;       for (int r = 0; r < 16; ++r) acc[i][j][r] = 0.f;
;   u32x4 ra0, ra1, ra2, ra3, ra4, ra5, ra6, ra7, rb0, rb1, rb2, rb3;
;   const bf16_t* Ap = A + (size_t)(m0 + lr) * lda + lc;
;   const bf16_t* Bp = B + (size_t)(n0 + lr) * ldb + lc;
;     ...
;   G256_LOAD(0)
;   const int nk = K >> 6;
; __global__ void __launch_bounds__(256, 2) hymba_mega(Params p) {
;     ...
;     for (int tile = blockIdx.x; tile < 64 * 8; tile += gridDim.x) {
;       const int mt = (tile & 7) * 8 + (tile >> 6), nt = (tile >> 3) & 7;
;       gemm256((const bf16_t*)(ws + OFF_AO), 1024, (const bf16_t*)(ws + OFF_WOT), 1024, 1024, mt * 256, nt * 128, sA, (bf16_t*)(smem + 36864),
.LBB0_1172:
	s_lshl_b32 s8, s35, 3
	s_and_b32 s8, s8, 56
	s_ashr_i32 s42, s35, 6
	s_add_i32 s8, s8, s42
	v_mov_b32_e32 v186, v192
	s_lshl_b32 s36, s8, 8
	s_lshl_b32 s8, s35, 4
	v_ashrrev_i32_e32 v0, 3, v186
	v_add_u32_e32 v2, s36, v0
	v_ashrrev_i32_e32 v3, 31, v2
	v_lshlrev_b64 v[2:3], 11, v[2:3]
	v_lshlrev_b32_e32 v1, 4, v186
	v_lshl_add_u64 v[2:3], s[4:5], 0, v[2:3]
	v_and_b32_e32 v176, 0x70, v1
	v_lshl_add_u64 v[2:3], v[2:3], 0, v[176:177]
	v_add_co_u32_e32 v6, vcc, s11, v2
	s_and_b32 s37, s8, 0x380
	s_nop 0
	v_addc_co_u32_e32 v7, vcc, 0, v3, vcc
	s_waitcnt vmcnt(6)
	v_add_co_u32_e32 v8, vcc, s12, v2
	v_add_u32_e32 v4, s37, v0
	s_nop 0
	v_addc_co_u32_e32 v9, vcc, 0, v3, vcc
	global_load_dwordx4 v[200:203], v[6:7], off
	global_load_dwordx4 v[204:207], v[8:9], off
	v_add_co_u32_e32 v6, vcc, s13, v2
	v_ashrrev_i32_e32 v5, 31, v4
	s_nop 0
	v_addc_co_u32_e32 v7, vcc, 0, v3, vcc
	v_add_co_u32_e32 v8, vcc, s14, v2
	v_lshlrev_b64 v[4:5], 11, v[4:5]
	s_nop 0
	v_addc_co_u32_e32 v9, vcc, 0, v3, vcc
	global_load_dwordx4 v[208:211], v[6:7], off
	global_load_dwordx4 v[212:215], v[8:9], off
	v_add_co_u32_e32 v6, vcc, s15, v2
	v_lshl_add_u64 v[4:5], s[18:19], 0, v[4:5]
	s_nop 0
	v_addc_co_u32_e32 v7, vcc, 0, v3, vcc
	v_add_co_u32_e32 v8, vcc, s16, v2
	v_lshl_add_u64 v[4:5], v[4:5], 0, v[176:177]
	s_nop 0
	v_addc_co_u32_e32 v9, vcc, 0, v3, vcc
	global_load_dwordx4 v[216:219], v[6:7], off
	global_load_dwordx4 v[220:223], v[8:9], off
	v_add_co_u32_e32 v6, vcc, s17, v2
	global_load_dwordx4 v[232:235], v[2:3], off
	global_load_dwordx4 v[224:227], v[4:5], off
	v_addc_co_u32_e32 v7, vcc, 0, v3, vcc
	v_add_co_u32_e32 v2, vcc, s11, v4
	s_lshl_b32 s2, s0, 8
	s_nop 0
	v_addc_co_u32_e32 v3, vcc, 0, v5, vcc
	global_load_dwordx4 v[236:239], v[6:7], off
	global_load_dwordx4 v[240:243], v[2:3], off
	v_add_co_u32_e32 v2, vcc, s12, v4
	v_mad_u64_u32 v[178:179], s[8:9], v0, s20, v[176:177]
	s_nop 0
	v_addc_co_u32_e32 v3, vcc, 0, v5, vcc
	v_add_co_u32_e32 v4, vcc, s13, v4
	s_and_b32 s2, s2, 0x3800
	s_nop 0
	v_addc_co_u32_e32 v5, vcc, 0, v5, vcc
	global_load_dwordx4 v[244:247], v[2:3], off
	global_load_dwordx4 v[248:251], v[4:5], off
	v_and_b32_e32 v1, 0xfffff9f, v186
	s_lshl_b32 s8, s42, 8
	v_lshrrev_b32_e32 v2, 1, v186
	v_mul_lo_u32 v5, v1, s20
	v_or_b32_e32 v1, 0x60, v186
	s_add_i32 s8, s8, s2
	s_lshl_b32 s6, s3, 11
	v_and_b32_e32 v4, 16, v2
	v_mul_lo_u32 v6, v1, s20
	v_add_u32_e32 v2, s8, v0
	v_ashrrev_i32_e32 v1, 31, v0
	s_and_b32 s6, s6, 0x1c0000
	v_ashrrev_i32_e32 v3, 31, v2
	v_lshlrev_b64 v[0:1], 11, v[0:1]
	v_lshlrev_b64 v[2:3], 11, v[2:3]
	v_lshl_add_u64 v[0:1], s[6:7], 0, v[0:1]
	v_and_b32_e32 v179, 0x5f, v186
	v_or_b32_e32 v2, v2, v176
	v_or_b32_e32 v0, v0, v176
	v_mad_u32_u24 v187, v179, s20, v4
	v_lshl_add_u64 v[180:181], s[86:87], 0, v[2:3]
	v_lshl_add_u64 v[182:183], s[86:87], 0, v[0:1]
	s_mov_b64 s[8:9], 0
	v_add_u32_e32 v185, v4, v5
	v_add_u32_e32 v184, v4, v6
	v_mov_b32_e32 v0, 0
	v_mov_b32_e32 v1, v177
	v_mov_b32_e32 v2, v177
	v_mov_b32_e32 v3, v177
	v_mov_b32_e32 v4, v177
	v_mov_b32_e32 v5, v177
	v_mov_b32_e32 v6, v177
	v_mov_b32_e32 v7, v177
	v_mov_b32_e32 v8, v177
	v_mov_b32_e32 v9, v177
	v_mov_b32_e32 v10, v177
	v_mov_b32_e32 v11, v177
	v_mov_b32_e32 v12, v177
	v_mov_b32_e32 v13, v177
	v_mov_b32_e32 v14, v177
	v_mov_b32_e32 v15, v177
	v_mov_b32_e32 v16, 0
	v_mov_b32_e32 v17, v177
	v_mov_b32_e32 v18, v177
	v_mov_b32_e32 v19, v177
	v_mov_b32_e32 v20, v177
	v_mov_b32_e32 v21, v177
	v_mov_b32_e32 v22, v177
	v_mov_b32_e32 v23, v177
	v_mov_b32_e32 v24, v177
	v_mov_b32_e32 v25, v177
	v_mov_b32_e32 v26, v177
	v_mov_b32_e32 v27, v177
	v_mov_b32_e32 v28, v177
	v_mov_b32_e32 v29, v177
	v_mov_b32_e32 v30, v177
	v_mov_b32_e32 v31, v177
	s_waitcnt vmcnt(17)
	v_mov_b32_e32 v32, 0
	v_mov_b32_e32 v33, v177
	v_mov_b32_e32 v34, v177
	v_mov_b32_e32 v35, v177
	v_mov_b32_e32 v36, v177
	v_mov_b32_e32 v37, v177
	v_mov_b32_e32 v38, v177
	v_mov_b32_e32 v39, v177
	v_mov_b32_e32 v40, v177
	v_mov_b32_e32 v41, v177
	v_mov_b32_e32 v42, v177
	v_mov_b32_e32 v43, v177
	v_mov_b32_e32 v44, v177
	v_mov_b32_e32 v45, v177
	v_mov_b32_e32 v46, v177
	v_mov_b32_e32 v47, v177
	v_mov_b32_e32 v48, 0
	v_mov_b32_e32 v49, v177
	v_mov_b32_e32 v50, v177
	v_mov_b32_e32 v51, v177
	v_mov_b32_e32 v52, v177
	v_mov_b32_e32 v53, v177
	v_mov_b32_e32 v54, v177
	v_mov_b32_e32 v55, v177
	v_mov_b32_e32 v56, v177
	v_mov_b32_e32 v57, v177
	v_mov_b32_e32 v58, v177
	v_mov_b32_e32 v59, v177
	v_mov_b32_e32 v60, v177
	v_mov_b32_e32 v61, v177
	v_mov_b32_e32 v62, v177
	v_mov_b32_e32 v63, v177
	v_mov_b32_e32 v64, 0
	v_mov_b32_e32 v65, v177
	v_mov_b32_e32 v66, v177
	v_mov_b32_e32 v67, v177
	v_mov_b32_e32 v68, v177
	v_mov_b32_e32 v69, v177
	v_mov_b32_e32 v70, v177
	v_mov_b32_e32 v71, v177
	v_mov_b32_e32 v72, v177
	v_mov_b32_e32 v73, v177
	v_mov_b32_e32 v74, v177
	v_mov_b32_e32 v75, v177
	v_mov_b32_e32 v76, v177
	v_mov_b32_e32 v77, v177
	v_mov_b32_e32 v78, v177
	v_mov_b32_e32 v79, v177
	v_mov_b32_e32 v80, 0
	v_mov_b32_e32 v81, v177
	v_mov_b32_e32 v82, v177
	v_mov_b32_e32 v83, v177
	v_mov_b32_e32 v84, v177
	v_mov_b32_e32 v85, v177
	v_mov_b32_e32 v86, v177
	v_mov_b32_e32 v87, v177
	v_mov_b32_e32 v88, v177
	v_mov_b32_e32 v89, v177
	v_mov_b32_e32 v90, v177
	v_mov_b32_e32 v91, v177
	v_mov_b32_e32 v92, v177
	v_mov_b32_e32 v93, v177
	v_mov_b32_e32 v94, v177
	v_mov_b32_e32 v95, v177
	v_mov_b32_e32 v96, 0
	v_mov_b32_e32 v97, v177
	v_mov_b32_e32 v98, v177
	v_mov_b32_e32 v99, v177
	v_mov_b32_e32 v100, v177
	v_mov_b32_e32 v101, v177
	v_mov_b32_e32 v102, v177
	v_mov_b32_e32 v103, v177
	v_mov_b32_e32 v104, v177
	v_mov_b32_e32 v105, v177
	v_mov_b32_e32 v106, v177
	v_mov_b32_e32 v107, v177
	v_mov_b32_e32 v108, v177
	v_mov_b32_e32 v109, v177
	v_mov_b32_e32 v110, v177
	v_mov_b32_e32 v111, v177
	v_mov_b32_e32 v112, 0
	v_mov_b32_e32 v113, v177
	v_mov_b32_e32 v114, v177
	v_mov_b32_e32 v115, v177
	v_mov_b32_e32 v116, v177
	v_mov_b32_e32 v117, v177
	v_mov_b32_e32 v118, v177
	v_mov_b32_e32 v119, v177
	v_mov_b32_e32 v120, v177
	v_mov_b32_e32 v121, v177
	v_mov_b32_e32 v122, v177
	v_mov_b32_e32 v123, v177
	v_mov_b32_e32 v124, v177
	v_mov_b32_e32 v125, v177
	v_mov_b32_e32 v126, v177
	v_mov_b32_e32 v127, v177
; #define MFMA32(a, b, c) __builtin_amdgcn_mfma_f32_32x32x16_bf16((a), (b), (c), 0, 0, 0)
; template <class Epi>
; DI void gemm256(const bf16_t* __restrict__ A, int lda, const bf16_t* __restrict__ B, int ldb, int K, int m0, int n0,
;                 bf16_t* sA, bf16_t* sB, Epi epi) {
;     ...
;   for (int kt = 0; kt < nk; ++kt) {
;     __syncthreads();
;     *(u32x4*)(sA + (lr) * LDS_ROW + lc) = ra0; *(u32x4*)(sA + (lr + 32) * LDS_ROW + lc) = ra1;
;     *(u32x4*)(sA + (lr + 64) * LDS_ROW + lc) = ra2; *(u32x4*)(sA + (lr + 96) * LDS_ROW + lc) = ra3;
;     *(u32x4*)(sA + (lr + 128) * LDS_ROW + lc) = ra4; *(u32x4*)(sA + (lr + 160) * LDS_ROW + lc) = ra5;
;     *(u32x4*)(sA + (lr + 192) * LDS_ROW + lc) = ra6; *(u32x4*)(sA + (lr + 224) * LDS_ROW + lc) = ra7;
;     *(u32x4*)(sB + (lr) * LDS_ROW + lc) = rb0; *(u32x4*)(sB + (lr + 32) * LDS_ROW + lc) = rb1;
;     *(u32x4*)(sB + (lr + 64) * LDS_ROW + lc) = rb2; *(u32x4*)(sB + (lr + 96) * LDS_ROW + lc) = rb3;
;     __syncthreads();
;     if (kt + 1 < nk) {
;       const int ko2 = (kt + 1) * 64;
;       G256_LOAD(ko2)
;     }
; #pragma unroll
;     for (int s = 0; s < 4; ++s) {
;       const int ko = s * 16 + (lane >> 5) * 8;
;       bf16x8 b0 = *(const bf16x8*)(sB + (wn * 64 + (lane & 31)) * LDS_ROW + ko);
;       bf16x8 b1 = *(const bf16x8*)(sB + (wn * 64 + 32 + (lane & 31)) * LDS_ROW + ko);
; #pragma unroll
;       for (int i = 0; i < 4; ++i) {
;         bf16x8 a = *(const bf16x8*)(sA + (wm * 128 + i * 32 + (lane & 31)) * LDS_ROW + ko);
;         acc[i][0] = MFMA32(a, b0, acc[i][0]);
;         acc[i][1] = MFMA32(a, b1, acc[i][1]);
;       }
;     }
;   }
.LBB0_1173:
	s_barrier
	s_waitcnt vmcnt(5)
	ds_write_b128 v178, v[232:235]
	ds_write_b128 v178, v[200:203] offset:4608
	ds_write_b128 v178, v[204:207] offset:9216
	ds_write_b128 v178, v[208:211] offset:13824
	ds_write_b128 v178, v[212:215] offset:18432
	ds_write_b128 v178, v[216:219] offset:23040
	ds_write_b128 v178, v[220:223] offset:27648
	s_waitcnt vmcnt(3)
	ds_write_b128 v178, v[236:239] offset:32256
	ds_write_b128 v178, v[224:227] offset:36864
	s_waitcnt vmcnt(2)
	ds_write_b128 v178, v[240:243] offset:41472
	s_waitcnt vmcnt(1)
	ds_write_b128 v178, v[244:247] offset:46080
	s_waitcnt vmcnt(0)
	ds_write_b128 v178, v[248:251] offset:50688
	s_waitcnt lgkmcnt(0)
	s_barrier
	v_lshl_add_u64 v[252:253], v[180:181], 0, s[8:9]
	v_lshl_add_u64 v[254:255], v[182:183], 0, s[8:9]
	ds_read_b128 v[128:131], v185
	ds_read_b128 v[132:135], v187 offset:36864
	ds_read_b128 v[136:139], v187 offset:36896
	ds_read_b128 v[140:143], v185 offset:32
	ds_read_b128 v[144:147], v187 offset:41472
	ds_read_b128 v[148:151], v187 offset:41504
	s_waitcnt lgkmcnt(4)
	v_mfma_f32_32x32x16_bf16 v[112:127], v[128:131], v[132:135], v[112:127]
	v_add_co_u32_e64 v228, vcc, s21, v252
	v_add_co_u32_e64 v198, s[98:99], s22, v252
	s_waitcnt lgkmcnt(1)
	v_mfma_f32_32x32x16_bf16 v[96:111], v[128:131], v[144:147], v[96:111]
	v_addc_co_u32_e64 v229, vcc, 0, v253, vcc
	v_addc_co_u32_e64 v199, s[98:99], 0, v253, s[98:99]
	global_load_dwordx4 v[232:235], v[228:229], off offset:128
	global_load_dwordx4 v[200:203], v[198:199], off offset:128
	ds_read_b128 v[128:131], v185 offset:4608
	ds_read_b128 v[152:155], v185 offset:4640
	s_waitcnt lgkmcnt(1)
	v_mfma_f32_32x32x16_bf16 v[80:95], v[128:131], v[132:135], v[80:95]
	v_add_co_u32_e64 v228, vcc, s23, v252
	v_add_co_u32_e64 v198, s[98:99], s24, v252
	v_mfma_f32_32x32x16_bf16 v[64:79], v[128:131], v[144:147], v[64:79]
	v_addc_co_u32_e64 v229, vcc, 0, v253, vcc
	v_addc_co_u32_e64 v199, s[98:99], 0, v253, s[98:99]
	global_load_dwordx4 v[204:207], v[228:229], off offset:128
	global_load_dwordx4 v[208:211], v[198:199], off offset:128
	ds_read_b128 v[128:131], v185 offset:9216
	ds_read_b128 v[156:159], v185 offset:9248
	s_waitcnt lgkmcnt(1)
	v_mfma_f32_32x32x16_bf16 v[48:63], v[128:131], v[132:135], v[48:63]
	v_add_co_u32_e64 v228, vcc, s25, v252
	v_add_co_u32_e64 v198, s[98:99], s26, v252
	v_mfma_f32_32x32x16_bf16 v[32:47], v[128:131], v[144:147], v[32:47]
	v_addc_co_u32_e64 v229, vcc, 0, v253, vcc
	v_addc_co_u32_e64 v199, s[98:99], 0, v253, s[98:99]
	global_load_dwordx4 v[212:215], v[228:229], off offset:128
	global_load_dwordx4 v[216:219], v[198:199], off offset:128
	ds_read_b128 v[128:131], v184
	ds_read_b128 v[160:163], v184 offset:32
	s_waitcnt lgkmcnt(1)
	v_mfma_f32_32x32x16_bf16 v[16:31], v[128:131], v[132:135], v[16:31]
	v_add_co_u32_e64 v228, vcc, s27, v252
	v_add_co_u32_e64 v198, s[98:99], s28, v252
	v_mfma_f32_32x32x16_bf16 v[112:127], v[140:143], v[136:139], v[112:127]
	v_addc_co_u32_e64 v229, vcc, 0, v253, vcc
	v_addc_co_u32_e64 v199, s[98:99], 0, v253, s[98:99]
	global_load_dwordx4 v[220:223], v[228:229], off offset:128
	global_load_dwordx4 v[236:239], v[198:199], off offset:128
	v_mfma_f32_32x32x16_bf16 v[96:111], v[140:143], v[148:151], v[96:111]
	v_add_co_u32_e64 v228, vcc, s29, v254
	v_add_co_u32_e64 v198, s[98:99], s30, v254
	v_mfma_f32_32x32x16_bf16 v[0:15], v[128:131], v[144:147], v[0:15]
	v_addc_co_u32_e64 v229, vcc, 0, v255, vcc
	v_addc_co_u32_e64 v199, s[98:99], 0, v255, s[98:99]
	global_load_dwordx4 v[224:227], v[228:229], off offset:128
	global_load_dwordx4 v[240:243], v[198:199], off offset:128
	v_mfma_f32_32x32x16_bf16 v[80:95], v[152:155], v[136:139], v[80:95]
	v_add_co_u32_e64 v228, vcc, s31, v254
	v_add_co_u32_e64 v198, s[98:99], s34, v254
	v_mfma_f32_32x32x16_bf16 v[64:79], v[152:155], v[148:151], v[64:79]
	v_addc_co_u32_e64 v229, vcc, 0, v255, vcc
	v_addc_co_u32_e64 v199, s[98:99], 0, v255, s[98:99]
	global_load_dwordx4 v[244:247], v[228:229], off offset:128
	global_load_dwordx4 v[248:251], v[198:199], off offset:128
	v_mfma_f32_32x32x16_bf16 v[48:63], v[156:159], v[136:139], v[48:63]
	s_waitcnt lgkmcnt(0)
	v_mfma_f32_32x32x16_bf16 v[16:31], v[160:163], v[136:139], v[16:31]
	ds_read_b128 v[128:131], v185 offset:64
	ds_read_b128 v[132:135], v187 offset:36928
	ds_read_b128 v[172:175], v187 offset:36960
	ds_read_b128 v[136:139], v185 offset:96
	ds_read_b128 v[140:143], v187 offset:41536
	ds_read_b128 v[188:191], v187 offset:41568
	v_mfma_f32_32x32x16_bf16 v[32:47], v[156:159], v[148:151], v[32:47]
	s_waitcnt lgkmcnt(4)
	v_mfma_f32_32x32x16_bf16 v[112:127], v[128:131], v[132:135], v[112:127]
	s_waitcnt lgkmcnt(1)
	v_mfma_f32_32x32x16_bf16 v[96:111], v[128:131], v[140:143], v[96:111]
	ds_read_b128 v[128:131], v185 offset:4672
	ds_read_b128 v[144:147], v185 offset:4704
	v_mfma_f32_32x32x16_bf16 v[0:15], v[160:163], v[148:151], v[0:15]
	s_waitcnt lgkmcnt(1)
	v_mfma_f32_32x32x16_bf16 v[80:95], v[128:131], v[132:135], v[80:95]
	v_mfma_f32_32x32x16_bf16 v[64:79], v[128:131], v[140:143], v[64:79]
	ds_read_b128 v[128:131], v185 offset:9280
	ds_read_b128 v[148:151], v185 offset:9312
	s_waitcnt lgkmcnt(1)
	v_mfma_f32_32x32x16_bf16 v[48:63], v[128:131], v[132:135], v[48:63]
	v_mfma_f32_32x32x16_bf16 v[32:47], v[128:131], v[140:143], v[32:47]
	ds_read_b128 v[128:131], v184 offset:64
	ds_read_b128 v[194:197], v184 offset:96
	s_waitcnt lgkmcnt(1)
	v_mfma_f32_32x32x16_bf16 v[16:31], v[128:131], v[132:135], v[16:31]
	s_add_u32 s8, s8, 0x80
	v_mfma_f32_32x32x16_bf16 v[0:15], v[128:131], v[140:143], v[0:15]
	s_addc_u32 s9, s9, 0
	v_mfma_f32_32x32x16_bf16 v[112:127], v[136:139], v[172:175], v[112:127]
	s_cmpk_lg_i32 s8, 0x780
	v_mfma_f32_32x32x16_bf16 v[96:111], v[136:139], v[188:191], v[96:111]
	v_mfma_f32_32x32x16_bf16 v[80:95], v[144:147], v[172:175], v[80:95]
	v_mfma_f32_32x32x16_bf16 v[64:79], v[144:147], v[188:191], v[64:79]
	v_mfma_f32_32x32x16_bf16 v[48:63], v[148:151], v[172:175], v[48:63]
	v_mfma_f32_32x32x16_bf16 v[32:47], v[148:151], v[188:191], v[32:47]
	s_waitcnt lgkmcnt(0)
	v_mfma_f32_32x32x16_bf16 v[16:31], v[194:197], v[172:175], v[16:31]
	v_mfma_f32_32x32x16_bf16 v[0:15], v[194:197], v[188:191], v[0:15]
	s_cbranch_scc1 .LBB0_1173
; #define MFMA32(a, b, c) __builtin_amdgcn_mfma_f32_32x32x16_bf16((a), (b), (c), 0, 0, 0)
; DI int crow32(int r, int half) { return (r & 3) + 8 * (r >> 2) + 4 * half; }
; template <class Epi>
; DI void gemm256(const bf16_t* __restrict__ A, int lda, const bf16_t* __restrict__ B, int ldb, int K, int m0, int n0,
;                 bf16_t* sA, bf16_t* sB, Epi epi) {
;     ...
;     __syncthreads();
;     *(u32x4*)(sA + (lr) * LDS_ROW + lc) = ra0; *(u32x4*)(sA + (lr + 32) * LDS_ROW + lc) = ra1;
;     *(u32x4*)(sA + (lr + 64) * LDS_ROW + lc) = ra2; *(u32x4*)(sA + (lr + 96) * LDS_ROW + lc) = ra3;
;     *(u32x4*)(sA + (lr + 128) * LDS_ROW + lc) = ra4; *(u32x4*)(sA + (lr + 160) * LDS_ROW + lc) = ra5;
;     *(u32x4*)(sA + (lr + 192) * LDS_ROW + lc) = ra6; *(u32x4*)(sA + (lr + 224) * LDS_ROW + lc) = ra7;
;     *(u32x4*)(sB + (lr) * LDS_ROW + lc) = rb0; *(u32x4*)(sB + (lr + 32) * LDS_ROW + lc) = rb1;
;     *(u32x4*)(sB + (lr + 64) * LDS_ROW + lc) = rb2; *(u32x4*)(sB + (lr + 96) * LDS_ROW + lc) = rb3;
;     __syncthreads();
;     if (kt + 1 < nk) {
;       const int ko2 = (kt + 1) * 64;
;       G256_LOAD(ko2)
;     }
; #pragma unroll
;     for (int s = 0; s < 4; ++s) {
;       const int ko = s * 16 + (lane >> 5) * 8;
;       bf16x8 b0 = *(const bf16x8*)(sB + (wn * 64 + (lane & 31)) * LDS_ROW + ko);
;       bf16x8 b1 = *(const bf16x8*)(sB + (wn * 64 + 32 + (lane & 31)) * LDS_ROW + ko);
; #pragma unroll
;       for (int i = 0; i < 4; ++i) {
;         bf16x8 a = *(const bf16x8*)(sA + (wm * 128 + i * 32 + (lane & 31)) * LDS_ROW + ko);
;         acc[i][0] = MFMA32(a, b0, acc[i][0]);
;         acc[i][1] = MFMA32(a, b1, acc[i][1]);
;       }
;     }
;   }
;     ...
; #pragma unroll
;   for (int i = 0; i < 4; ++i)
; #pragma unroll
;     for (int j = 0; j < 2; ++j)
; #pragma unroll
;       for (int r = 0; r < 16; ++r) {
;         const int m = m0 + wm * 128 + i * 32 + crow32(r, lane >> 5);
;         const int n = n0 + wn * 64 + j * 32 + (lane & 31);
;         epi(m, n, acc[i][j][r]);
;       }
; __global__ void __launch_bounds__(256, 2) hymba_mega(Params p) {
;     ...
;               [&](int m, int n, float v) { out[(size_t)m * 1024 + n] += v; });
	s_barrier
	s_waitcnt vmcnt(11)
	ds_write_b128 v178, v[232:235]
	s_waitcnt vmcnt(10)
	ds_write_b128 v178, v[200:203] offset:4608
	s_waitcnt vmcnt(9)
	ds_write_b128 v178, v[204:207] offset:9216
	s_waitcnt vmcnt(8)
	ds_write_b128 v178, v[208:211] offset:13824
	s_waitcnt vmcnt(7)
	ds_write_b128 v178, v[212:215] offset:18432
	s_waitcnt vmcnt(6)
	ds_write_b128 v178, v[216:219] offset:23040
	s_waitcnt vmcnt(5)
	ds_write_b128 v178, v[220:223] offset:27648
	s_waitcnt vmcnt(4)
	ds_write_b128 v178, v[236:239] offset:32256
	s_waitcnt vmcnt(3)
	ds_write_b128 v178, v[224:227] offset:36864
	s_waitcnt vmcnt(2)
	ds_write_b128 v178, v[240:243] offset:41472
	s_waitcnt vmcnt(1)
	ds_write_b128 v178, v[244:247] offset:46080
	s_waitcnt vmcnt(0)
	ds_write_b128 v178, v[248:251] offset:50688
	s_waitcnt lgkmcnt(0)
	s_barrier
	ds_read_b128 v[128:131], v185
	ds_read_b128 v[148:151], v187 offset:36864
	ds_read_b128 v[172:175], v187 offset:36896
	ds_read_b128 v[158:161], v185 offset:32
	ds_read_b128 v[152:155], v187 offset:41472
	ds_read_b128 v[180:183], v187 offset:41504
	s_waitcnt lgkmcnt(4)
	v_mfma_f32_32x32x16_bf16 v[112:127], v[128:131], v[148:151], v[112:127]
	s_add_i32 s35, s35, s88
	s_add_i32 s0, s0, s1
	s_add_i32 s3, s3, s10
	s_cmpk_gt_i32 s35, 0x1ff
	s_waitcnt lgkmcnt(1)
	v_mfma_f32_32x32x16_bf16 v[96:111], v[128:131], v[152:155], v[96:111]
	ds_read_b128 v[128:131], v185 offset:4608
	ds_read_b128 v[164:167], v185 offset:4640
	s_waitcnt lgkmcnt(1)
	v_mfma_f32_32x32x16_bf16 v[80:95], v[128:131], v[148:151], v[80:95]
	v_mfma_f32_32x32x16_bf16 v[64:79], v[128:131], v[152:155], v[64:79]
	ds_read_b128 v[128:131], v185 offset:9216
	ds_read_b128 v[188:191], v185 offset:9248
	ds_read_b128 v[168:171], v184
	s_waitcnt lgkmcnt(2)
	v_mfma_f32_32x32x16_bf16 v[48:63], v[128:131], v[148:151], v[48:63]
	s_waitcnt lgkmcnt(0)
	v_mfma_f32_32x32x16_bf16 v[16:31], v[168:171], v[148:151], v[16:31]
	v_and_b32_e32 v148, 0xffffff80, v186
	v_lshrrev_b32_e32 v149, 3, v186
	v_add_u32_e32 v148, s36, v148
	v_and_or_b32 v150, v149, 4, v148
	v_or_b32_e32 v148, s37, v179
	v_lshlrev_b32_e32 v176, 2, v148
	v_ashrrev_i32_e32 v151, 31, v150
	v_mfma_f32_32x32x16_bf16 v[32:47], v[128:131], v[152:155], v[32:47]
	v_or_b32_e32 v156, 2, v150
	v_or_b32_e32 v162, 3, v150
	v_lshl_add_u64 v[148:149], s[84:85], 0, v[176:177]
	v_ashrrev_i32_e32 v157, 31, v156
	v_ashrrev_i32_e32 v163, 31, v162
	v_lshlrev_b64 v[156:157], 12, v[156:157]
	v_lshlrev_b64 v[162:163], 12, v[162:163]
	v_mfma_f32_32x32x16_bf16 v[0:15], v[168:171], v[152:155], v[0:15]
	v_or_b32_e32 v154, 1, v150
	v_lshlrev_b64 v[152:153], 12, v[150:151]
	v_ashrrev_i32_e32 v155, 31, v154
	v_lshl_add_u64 v[152:153], v[148:149], 0, v[152:153]
	v_lshlrev_b64 v[154:155], 12, v[154:155]
	ds_read_b128 v[194:197], v184 offset:32
	ds_read_b128 v[144:147], v187 offset:36928
	ds_read_b128 v[132:135], v187 offset:36960
	ds_read_b128 v[140:143], v187 offset:41536
	ds_read_b128 v[128:131], v187 offset:41568
	ds_read_b128 v[198:201], v185 offset:64
	ds_read_b128 v[136:139], v185 offset:96
	v_lshl_add_u64 v[154:155], v[148:149], 0, v[154:155]
	v_mfma_f32_32x32x16_bf16 v[112:127], v[158:161], v[172:175], v[112:127]
	v_lshl_add_u64 v[156:157], v[148:149], 0, v[156:157]
	v_or_b32_e32 v168, 10, v150
	v_ashrrev_i32_e32 v169, 31, v168
	v_or_b32_e32 v170, 17, v150
	v_ashrrev_i32_e32 v171, 31, v170
	v_or_b32_e32 v178, 18, v150
	v_lshlrev_b64 v[170:171], 12, v[170:171]
	v_mfma_f32_32x32x16_bf16 v[96:111], v[158:161], v[180:183], v[96:111]
	v_lshl_add_u64 v[158:159], v[148:149], 0, v[162:163]
	global_load_dword v151, v[152:153], off
	global_load_dword v176, v[154:155], off
	global_load_dword v193, v[156:157], off
	global_load_dword v214, v[158:159], off
	v_or_b32_e32 v160, 8, v150
	v_ashrrev_i32_e32 v161, 31, v160
	v_or_b32_e32 v162, 9, v150
	v_lshlrev_b64 v[160:161], 12, v[160:161]
	v_ashrrev_i32_e32 v163, 31, v162
	v_mfma_f32_32x32x16_bf16 v[80:95], v[164:167], v[172:175], v[80:95]
	v_lshl_add_u64 v[160:161], v[148:149], 0, v[160:161]
	v_lshlrev_b64 v[162:163], 12, v[162:163]
	v_lshl_add_u64 v[162:163], v[148:149], 0, v[162:163]
	v_ashrrev_i32_e32 v179, 31, v178
	v_lshl_add_u64 v[170:171], v[148:149], 0, v[170:171]
	v_lshlrev_b64 v[178:179], 12, v[178:179]
	v_mfma_f32_32x32x16_bf16 v[64:79], v[164:167], v[180:183], v[64:79]
	v_or_b32_e32 v166, 11, v150
	v_lshlrev_b64 v[164:165], 12, v[168:169]
	v_ashrrev_i32_e32 v167, 31, v166
	v_or_b32_e32 v168, 16, v150
	v_lshlrev_b64 v[166:167], 12, v[166:167]
	v_ashrrev_i32_e32 v169, 31, v168
	v_lshl_add_u64 v[164:165], v[148:149], 0, v[164:165]
	v_lshl_add_u64 v[166:167], v[148:149], 0, v[166:167]
	global_load_dword v215, v[160:161], off
	global_load_dword v216, v[162:163], off
	global_load_dword v217, v[164:165], off
	global_load_dword v218, v[166:167], off
	v_lshlrev_b64 v[168:169], 12, v[168:169]
	v_mfma_f32_32x32x16_bf16 v[48:63], v[188:191], v[172:175], v[48:63]
	v_lshl_add_u64 v[168:169], v[148:149], 0, v[168:169]
	s_waitcnt lgkmcnt(6)
	v_mfma_f32_32x32x16_bf16 v[16:31], v[194:197], v[172:175], v[16:31]
	v_or_b32_e32 v174, 19, v150
	v_ashrrev_i32_e32 v175, 31, v174
	v_lshl_add_u64 v[172:173], v[148:149], 0, v[178:179]
	v_lshlrev_b64 v[174:175], 12, v[174:175]
	v_lshl_add_u64 v[174:175], v[148:149], 0, v[174:175]
	v_or_b32_e32 v178, 24, v150
	v_ashrrev_i32_e32 v179, 31, v178
	v_mfma_f32_32x32x16_bf16 v[32:47], v[188:191], v[180:183], v[32:47]
	global_load_dword v190, v[168:169], off
	global_load_dword v191, v[170:171], off
	global_load_dword v219, v[172:173], off
	global_load_dword v220, v[174:175], off
	v_lshlrev_b64 v[178:179], 12, v[178:179]
	v_lshl_add_u64 v[178:179], v[148:149], 0, v[178:179]
	v_mfma_f32_32x32x16_bf16 v[0:15], v[194:197], v[180:183], v[0:15]
	v_or_b32_e32 v180, 25, v150
	v_ashrrev_i32_e32 v181, 31, v180
	v_lshlrev_b64 v[180:181], 12, v[180:181]
	v_lshl_add_u64 v[180:181], v[148:149], 0, v[180:181]
	global_load_dword v221, v[178:179], off
	global_load_dword v222, v[180:181], off
	v_or_b32_e32 v182, 26, v150
	v_ashrrev_i32_e32 v183, 31, v182
	s_waitcnt lgkmcnt(1)
; DI int crow32(int r, int half) { return (r & 3) + 8 * (r >> 2) + 4 * half; }
; template <class Epi>
; DI void gemm256(const bf16_t* __restrict__ A, int lda, const bf16_t* __restrict__ B, int ldb, int K, int m0, int n0,
;                 bf16_t* sA, bf16_t* sB, Epi epi) {
;     ...
; #pragma unroll
;   for (int i = 0; i < 4; ++i)
; #pragma unroll
;     for (int j = 0; j < 2; ++j)
; #pragma unroll
;       for (int r = 0; r < 16; ++r) {
;         const int m = m0 + wm * 128 + i * 32 + crow32(r, lane >> 5);
;         const int n = n0 + wn * 64 + j * 32 + (lane & 31);
;         epi(m, n, acc[i][j][r]);
;       }
; __global__ void __launch_bounds__(256, 2) hymba_mega(Params p) {
;     ...
;               [&](int m, int n, float v) { out[(size_t)m * 1024 + n] += v; });
	v_mfma_f32_32x32x16_bf16 v[112:127], v[198:201], v[144:147], v[112:127]
	v_lshlrev_b64 v[182:183], 12, v[182:183]
	v_lshl_add_u64 v[182:183], v[148:149], 0, v[182:183]
	global_load_dword v223, v[182:183], off
	s_waitcnt lgkmcnt(0)
	v_mfma_f32_32x32x16_bf16 v[112:127], v[136:139], v[132:135], v[112:127]
	v_mfma_f32_32x32x16_bf16 v[96:111], v[198:201], v[140:143], v[96:111]
	ds_read_b128 v[186:189], v185 offset:4672
	ds_read_b128 v[194:197], v185 offset:4704
	ds_read_b128 v[198:201], v185 offset:9280
	ds_read_b128 v[202:205], v185 offset:9312
	ds_read_b128 v[206:209], v184 offset:64
	ds_read_b128 v[210:213], v184 offset:96
	global_load_dword v224, v[158:159], off offset:128
	global_load_dword v225, v[156:157], off offset:128
	global_load_dword v226, v[154:155], off offset:128
	global_load_dword v227, v[152:153], off offset:128
	s_waitcnt vmcnt(18)
	v_add_f32_e32 v112, v112, v151
	global_store_dword v[152:153], v112, off
	s_waitcnt vmcnt(18)
	v_add_f32_e32 v112, v113, v176
	global_store_dword v[154:155], v112, off
	s_waitcnt vmcnt(18)
	v_add_f32_e32 v112, v114, v193
	global_store_dword v[156:157], v112, off
	s_waitcnt vmcnt(18)
	v_add_f32_e32 v112, v115, v214
	global_store_dword v[158:159], v112, off
	global_load_dword v151, v[166:167], off offset:128
	global_load_dword v176, v[164:165], off offset:128
	global_load_dword v193, v[162:163], off offset:128
	global_load_dword v214, v[160:161], off offset:128
	s_waitcnt lgkmcnt(5)
	v_mfma_f32_32x32x16_bf16 v[80:95], v[186:189], v[144:147], v[80:95]
	v_or_b32_e32 v114, 34, v150
	v_ashrrev_i32_e32 v115, 31, v114
	v_lshlrev_b64 v[114:115], 12, v[114:115]
	v_lshl_add_u64 v[114:115], v[148:149], 0, v[114:115]
	s_waitcnt vmcnt(22)
	v_add_f32_e32 v112, v116, v215
	global_store_dword v[160:161], v112, off
	s_waitcnt vmcnt(22)
	v_add_f32_e32 v112, v117, v216
	global_store_dword v[162:163], v112, off
	s_waitcnt vmcnt(22)
	v_add_f32_e32 v112, v118, v217
	global_store_dword v[164:165], v112, off
	s_waitcnt vmcnt(22)
	v_add_f32_e32 v112, v119, v218
	global_store_dword v[166:167], v112, off
	v_mfma_f32_32x32x16_bf16 v[64:79], v[186:189], v[140:143], v[64:79]
	global_load_dword v186, v[174:175], off offset:128
	global_load_dword v187, v[172:173], off offset:128
	global_load_dword v188, v[170:171], off offset:128
	global_load_dword v189, v[168:169], off offset:128
	v_or_b32_e32 v116, 35, v150
	v_ashrrev_i32_e32 v117, 31, v116
	v_lshlrev_b64 v[116:117], 12, v[116:117]
	v_lshl_add_u64 v[116:117], v[148:149], 0, v[116:117]
	v_or_b32_e32 v118, 40, v150
	v_ashrrev_i32_e32 v119, 31, v118
	s_waitcnt lgkmcnt(3)
	v_mfma_f32_32x32x16_bf16 v[48:63], v[198:201], v[144:147], v[48:63]
	v_lshlrev_b64 v[118:119], 12, v[118:119]
	v_lshl_add_u64 v[118:119], v[148:149], 0, v[118:119]
	s_waitcnt vmcnt(26)
	v_add_f32_e32 v112, v120, v190
	global_store_dword v[168:169], v112, off
	s_waitcnt vmcnt(26)
	v_add_f32_e32 v112, v121, v191
	global_store_dword v[170:171], v112, off
	s_waitcnt vmcnt(26)
	v_add_f32_e32 v112, v122, v219
	global_store_dword v[172:173], v112, off
	s_waitcnt vmcnt(26)
	v_add_f32_e32 v112, v123, v220
	global_store_dword v[174:175], v112, off
	v_or_b32_e32 v112, 27, v150
	v_ashrrev_i32_e32 v113, 31, v112
	v_lshlrev_b64 v[112:113], 12, v[112:113]
	v_lshl_add_u64 v[184:185], v[148:149], 0, v[112:113]
	s_waitcnt vmcnt(26)
	v_add_f32_e32 v112, v124, v221
	v_mfma_f32_32x32x16_bf16 v[32:47], v[198:201], v[140:143], v[32:47]
	v_or_b32_e32 v120, 41, v150
	v_or_b32_e32 v122, 42, v150
	v_or_b32_e32 v124, 43, v150
	v_ashrrev_i32_e32 v121, 31, v120
	v_ashrrev_i32_e32 v123, 31, v122
	v_lshlrev_b64 v[120:121], 12, v[120:121]
	v_lshlrev_b64 v[122:123], 12, v[122:123]
	s_waitcnt lgkmcnt(1)
	v_mfma_f32_32x32x16_bf16 v[16:31], v[206:209], v[144:147], v[16:31]
	global_load_dword v146, v[184:185], off
	global_load_dword v147, v[184:185], off offset:128
	global_load_dword v190, v[182:183], off offset:128
	global_load_dword v191, v[180:181], off offset:128
	global_load_dword v198, v[178:179], off offset:128
	v_lshl_add_u64 v[120:121], v[148:149], 0, v[120:121]
	global_store_dword v[178:179], v112, off
	s_waitcnt vmcnt(31)
	v_add_f32_e32 v112, v125, v222
	global_store_dword v[180:181], v112, off
	v_or_b32_e32 v112, 32, v150
	v_ashrrev_i32_e32 v113, 31, v112
	v_lshlrev_b64 v[112:113], 12, v[112:113]
	v_mfma_f32_32x32x16_bf16 v[0:15], v[206:209], v[140:143], v[0:15]
	v_lshl_add_u64 v[144:145], v[148:149], 0, v[112:113]
	v_or_b32_e32 v112, 33, v150
	v_ashrrev_i32_e32 v113, 31, v112
	v_lshlrev_b64 v[112:113], 12, v[112:113]
	v_lshl_add_u64 v[112:113], v[148:149], 0, v[112:113]
	global_load_dword v199, v[144:145], off
	global_load_dword v200, v[112:113], off
	global_load_dword v201, v[114:115], off
	global_load_dword v206, v[116:117], off
	v_ashrrev_i32_e32 v125, 31, v124
	v_mfma_f32_32x32x16_bf16 v[96:111], v[136:139], v[128:131], v[96:111]
	v_or_b32_e32 v136, 48, v150
	v_ashrrev_i32_e32 v137, 31, v136
	v_lshlrev_b64 v[136:137], 12, v[136:137]
	v_lshlrev_b64 v[124:125], 12, v[124:125]
	v_lshl_add_u64 v[122:123], v[148:149], 0, v[122:123]
	v_lshl_add_u64 v[124:125], v[148:149], 0, v[124:125]
	v_or_b32_e32 v138, 57, v150
	v_mfma_f32_32x32x16_bf16 v[80:95], v[194:197], v[132:135], v[80:95]
	v_ashrrev_i32_e32 v139, 31, v138
	v_or_b32_e32 v140, 58, v150
	v_or_b32_e32 v142, 59, v150
	v_lshlrev_b64 v[138:139], 12, v[138:139]
	v_ashrrev_i32_e32 v141, 31, v140
	v_ashrrev_i32_e32 v143, 31, v142
	v_lshl_add_u64 v[138:139], v[148:149], 0, v[138:139]
	v_mfma_f32_32x32x16_bf16 v[48:63], v[202:205], v[132:135], v[48:63]
	v_lshlrev_b64 v[140:141], 12, v[140:141]
	v_lshlrev_b64 v[142:143], 12, v[142:143]
	v_lshl_add_u64 v[140:141], v[148:149], 0, v[140:141]
	v_lshl_add_u64 v[142:143], v[148:149], 0, v[142:143]
	s_waitcnt vmcnt(31)
; DI int crow32(int r, int half) { return (r & 3) + 8 * (r >> 2) + 4 * half; }
; template <class Epi>
; DI void gemm256(const bf16_t* __restrict__ A, int lda, const bf16_t* __restrict__ B, int ldb, int K, int m0, int n0,
;                 bf16_t* sA, bf16_t* sB, Epi epi) {
;     ...
; #pragma unroll
;   for (int i = 0; i < 4; ++i)
; #pragma unroll
;     for (int j = 0; j < 2; ++j)
; #pragma unroll
;       for (int r = 0; r < 16; ++r) {
;         const int m = m0 + wm * 128 + i * 32 + crow32(r, lane >> 5);
;         const int n = n0 + wn * 64 + j * 32 + (lane & 31);
;         epi(m, n, acc[i][j][r]);
;       }
; __global__ void __launch_bounds__(256, 2) hymba_mega(Params p) {
;     ...
;               [&](int m, int n, float v) { out[(size_t)m * 1024 + n] += v; });
	v_add_f32_e32 v96, v96, v227
	v_add_f32_e32 v126, v126, v223
	s_waitcnt vmcnt(3)
	v_add_f32_e32 v80, v80, v199
	s_waitcnt lgkmcnt(0)
	v_mfma_f32_32x32x16_bf16 v[16:31], v[210:213], v[132:135], v[16:31]
	v_lshl_add_u64 v[132:133], v[148:149], 0, v[136:137]
	v_or_b32_e32 v136, 50, v150
	v_ashrrev_i32_e32 v137, 31, v136
	v_or_b32_e32 v134, 49, v150
	v_ashrrev_i32_e32 v135, 31, v134
	v_lshlrev_b64 v[134:135], 12, v[134:135]
	v_lshl_add_u64 v[134:135], v[148:149], 0, v[134:135]
	v_mfma_f32_32x32x16_bf16 v[64:79], v[194:197], v[128:131], v[64:79]
	global_load_dword v194, v[118:119], off
	global_load_dword v195, v[120:121], off
	global_load_dword v196, v[122:123], off
	global_load_dword v197, v[124:125], off
	v_mfma_f32_32x32x16_bf16 v[32:47], v[202:205], v[128:131], v[32:47]
	v_mfma_f32_32x32x16_bf16 v[0:15], v[210:213], v[128:131], v[0:15]
	v_lshlrev_b64 v[128:129], 12, v[136:137]
	v_or_b32_e32 v130, 51, v150
	v_or_b32_e32 v136, 56, v150
	v_ashrrev_i32_e32 v131, 31, v130
	v_ashrrev_i32_e32 v137, 31, v136
	v_lshlrev_b64 v[130:131], 12, v[130:131]
	v_lshlrev_b64 v[136:137], 12, v[136:137]
	v_lshl_add_u64 v[128:129], v[148:149], 0, v[128:129]
	v_lshl_add_u64 v[130:131], v[148:149], 0, v[130:131]
	global_load_dword v202, v[132:133], off
	global_load_dword v203, v[134:135], off
	global_load_dword v204, v[128:129], off
	global_load_dword v205, v[130:131], off
	v_lshl_add_u64 v[136:137], v[148:149], 0, v[136:137]
	global_load_dword v207, v[136:137], off
	global_load_dword v208, v[138:139], off
	global_load_dword v209, v[140:141], off
	global_load_dword v210, v[142:143], off
	global_load_dword v211, v[116:117], off offset:128
	global_load_dword v212, v[114:115], off offset:128
	global_load_dword v213, v[112:113], off offset:128
	global_load_dword v215, v[144:145], off offset:128
	s_waitcnt vmcnt(1)
	v_add_f32_e32 v65, v65, v213
	global_store_dword v[152:153], v96, off offset:128
	v_add_f32_e32 v96, v97, v226
	global_store_dword v[154:155], v96, off offset:128
	v_add_f32_e32 v96, v98, v225
	global_store_dword v[156:157], v96, off offset:128
	v_add_f32_e32 v96, v99, v224
	global_store_dword v[158:159], v96, off offset:128
	v_add_f32_e32 v96, v100, v214
	global_store_dword v[160:161], v96, off offset:128
	v_add_f32_e32 v96, v101, v193
	global_store_dword v[162:163], v96, off offset:128
	v_add_f32_e32 v96, v102, v176
	global_store_dword v[164:165], v96, off offset:128
	v_add_f32_e32 v96, v103, v151
	global_store_dword v[166:167], v96, off offset:128
	v_add_f32_e32 v96, v104, v189
	global_store_dword v[168:169], v96, off offset:128
	v_add_f32_e32 v96, v105, v188
	global_store_dword v[170:171], v96, off offset:128
	v_add_f32_e32 v96, v106, v187
	global_store_dword v[172:173], v96, off offset:128
	v_add_f32_e32 v96, v107, v186
	global_store_dword v[174:175], v96, off offset:128
	v_add_f32_e32 v96, v108, v198
	global_store_dword v[178:179], v96, off offset:128
	v_add_f32_e32 v96, v109, v191
	global_store_dword v[144:145], v80, off
	v_add_f32_e32 v80, v81, v200
	global_store_dword v[180:181], v96, off offset:128
	v_add_f32_e32 v96, v110, v190
	global_store_dword v[112:113], v80, off
	v_add_f32_e32 v80, v82, v201
	global_store_dword v[182:183], v126, off
	v_add_f32_e32 v126, v127, v146
	global_store_dword v[182:183], v96, off offset:128
	v_add_f32_e32 v96, v111, v147
	global_store_dword v[114:115], v80, off
	v_add_f32_e32 v80, v83, v206
	global_store_dword v[184:185], v126, off
	global_store_dword v[184:185], v96, off offset:128
	global_store_dword v[116:117], v80, off
	v_add_f32_e32 v80, v84, v194
	global_load_dword v110, v[124:125], off offset:128
	global_load_dword v111, v[122:123], off offset:128
	global_load_dword v126, v[120:121], off offset:128
	global_load_dword v127, v[118:119], off offset:128
	v_or_b32_e32 v84, 0x43, v150
	global_store_dword v[118:119], v80, off
	v_add_f32_e32 v80, v85, v195
	global_store_dword v[120:121], v80, off
	v_add_f32_e32 v80, v86, v196
	global_store_dword v[122:123], v80, off
	v_add_f32_e32 v80, v87, v197
	global_store_dword v[124:125], v80, off
	v_add_f32_e32 v80, v88, v202
	global_load_dword v146, v[130:131], off offset:128
	global_load_dword v147, v[128:129], off offset:128
	global_load_dword v151, v[134:135], off offset:128
	global_load_dword v152, v[132:133], off offset:128
	s_waitcnt vmcnt(34)
; DI int crow32(int r, int half) { return (r & 3) + 8 * (r >> 2) + 4 * half; }
; template <class Epi>
; DI void gemm256(const bf16_t* __restrict__ A, int lda, const bf16_t* __restrict__ B, int ldb, int K, int m0, int n0,
;                 bf16_t* sA, bf16_t* sB, Epi epi) {
;     ...
; #pragma unroll
;   for (int i = 0; i < 4; ++i)
; #pragma unroll
;     for (int j = 0; j < 2; ++j)
; #pragma unroll
;       for (int r = 0; r < 16; ++r) {
;         const int m = m0 + wm * 128 + i * 32 + crow32(r, lane >> 5);
;         const int n = n0 + wn * 64 + j * 32 + (lane & 31);
;         epi(m, n, acc[i][j][r]);
;       }
; __global__ void __launch_bounds__(256, 2) hymba_mega(Params p) {
;     ...
;               [&](int m, int n, float v) { out[(size_t)m * 1024 + n] += v; });
	v_add_f32_e32 v64, v64, v215
	global_store_dword v[132:133], v80, off
	v_add_f32_e32 v80, v89, v203
	global_store_dword v[134:135], v80, off
	v_add_f32_e32 v80, v90, v204
	global_store_dword v[128:129], v80, off
	v_add_f32_e32 v80, v91, v205
	global_store_dword v[130:131], v80, off
	v_add_f32_e32 v80, v92, v207
	global_load_dword v153, v[142:143], off offset:128
	global_load_dword v154, v[140:141], off offset:128
	global_load_dword v155, v[138:139], off offset:128
	global_load_dword v156, v[136:137], off offset:128
	v_ashrrev_i32_e32 v85, 31, v84
	global_store_dword v[136:137], v80, off
	v_add_f32_e32 v80, v93, v208
	global_store_dword v[138:139], v80, off
	v_add_f32_e32 v80, v94, v209
	global_store_dword v[140:141], v80, off
	v_add_f32_e32 v80, v95, v210
	global_store_dword v[142:143], v80, off
	v_or_b32_e32 v80, 64, v150
	v_ashrrev_i32_e32 v81, 31, v80
	v_lshlrev_b64 v[80:81], 12, v[80:81]
	v_lshl_add_u64 v[82:83], v[148:149], 0, v[80:81]
	v_or_b32_e32 v80, 0x41, v150
	v_ashrrev_i32_e32 v81, 31, v80
	v_lshlrev_b64 v[80:81], 12, v[80:81]
	v_lshl_add_u64 v[88:89], v[148:149], 0, v[80:81]
	v_or_b32_e32 v80, 0x42, v150
	v_ashrrev_i32_e32 v81, 31, v80
	global_store_dword v[144:145], v64, off offset:128
	v_lshlrev_b64 v[80:81], 12, v[80:81]
	v_lshlrev_b64 v[84:85], 12, v[84:85]
	v_lshl_add_u64 v[80:81], v[148:149], 0, v[80:81]
	v_lshl_add_u64 v[86:87], v[148:149], 0, v[84:85]
	global_load_dword v64, v[82:83], off
	global_load_dword v144, v[88:89], off
	global_load_dword v145, v[80:81], off
	global_load_dword v157, v[86:87], off
	v_or_b32_e32 v84, 0x48, v150
	v_ashrrev_i32_e32 v85, 31, v84
	v_or_b32_e32 v90, 0x49, v150
	v_or_b32_e32 v92, 0x4a, v150
	v_or_b32_e32 v94, 0x4b, v150
	v_lshlrev_b64 v[84:85], 12, v[84:85]
	v_ashrrev_i32_e32 v91, 31, v90
	v_ashrrev_i32_e32 v93, 31, v92
	v_ashrrev_i32_e32 v95, 31, v94
	v_lshl_add_u64 v[84:85], v[148:149], 0, v[84:85]
	v_lshlrev_b64 v[90:91], 12, v[90:91]
	v_lshlrev_b64 v[92:93], 12, v[92:93]
	v_lshlrev_b64 v[94:95], 12, v[94:95]
	v_or_b32_e32 v96, 0x50, v150
	v_lshl_add_u64 v[90:91], v[148:149], 0, v[90:91]
	v_lshl_add_u64 v[92:93], v[148:149], 0, v[92:93]
	v_lshl_add_u64 v[94:95], v[148:149], 0, v[94:95]
	global_load_dword v158, v[84:85], off
	global_load_dword v159, v[90:91], off
	global_load_dword v160, v[92:93], off
	global_load_dword v161, v[94:95], off
	v_ashrrev_i32_e32 v97, 31, v96
	v_or_b32_e32 v98, 0x51, v150
	v_or_b32_e32 v100, 0x52, v150
	v_or_b32_e32 v102, 0x53, v150
	v_lshlrev_b64 v[96:97], 12, v[96:97]
	v_ashrrev_i32_e32 v99, 31, v98
	v_ashrrev_i32_e32 v101, 31, v100
	v_ashrrev_i32_e32 v103, 31, v102
	v_lshl_add_u64 v[96:97], v[148:149], 0, v[96:97]
	v_lshlrev_b64 v[98:99], 12, v[98:99]
	v_lshlrev_b64 v[100:101], 12, v[100:101]
	v_lshlrev_b64 v[102:103], 12, v[102:103]
	v_lshl_add_u64 v[98:99], v[148:149], 0, v[98:99]
	v_lshl_add_u64 v[100:101], v[148:149], 0, v[100:101]
	global_load_dword v162, v[96:97], off
	global_load_dword v163, v[98:99], off
	global_load_dword v164, v[100:101], off
	v_lshl_add_u64 v[102:103], v[148:149], 0, v[102:103]
	global_load_dword v165, v[102:103], off
	v_or_b32_e32 v104, 0x58, v150
	v_ashrrev_i32_e32 v105, 31, v104
	v_or_b32_e32 v106, 0x59, v150
	v_lshlrev_b64 v[104:105], 12, v[104:105]
	v_ashrrev_i32_e32 v107, 31, v106
	v_lshl_add_u64 v[104:105], v[148:149], 0, v[104:105]
	v_lshlrev_b64 v[106:107], 12, v[106:107]
	v_lshl_add_u64 v[106:107], v[148:149], 0, v[106:107]
	global_load_dword v166, v[104:105], off
	global_load_dword v167, v[106:107], off
	v_or_b32_e32 v108, 0x5a, v150
	global_store_dword v[112:113], v65, off offset:128
	v_add_f32_e32 v65, v66, v212
	global_store_dword v[114:115], v65, off offset:128
	v_add_f32_e32 v65, v67, v211
	global_store_dword v[116:117], v65, off offset:128
	s_waitcnt vmcnt(38)
	v_add_f32_e32 v65, v68, v127
	global_store_dword v[118:119], v65, off offset:128
	v_add_f32_e32 v65, v69, v126
	global_store_dword v[120:121], v65, off offset:128
	v_add_f32_e32 v65, v70, v111
	global_store_dword v[122:123], v65, off offset:128
	v_add_f32_e32 v65, v71, v110
	global_store_dword v[124:125], v65, off offset:128
	s_waitcnt vmcnt(34)
	v_add_f32_e32 v65, v72, v152
	global_store_dword v[132:133], v65, off offset:128
	v_add_f32_e32 v65, v73, v151
	global_store_dword v[134:135], v65, off offset:128
	v_add_f32_e32 v65, v74, v147
	global_store_dword v[128:129], v65, off offset:128
	v_add_f32_e32 v65, v75, v146
	global_store_dword v[130:131], v65, off offset:128
	s_waitcnt vmcnt(30)
	v_add_f32_e32 v65, v76, v156
	global_store_dword v[136:137], v65, off offset:128
	v_add_f32_e32 v65, v77, v155
	v_ashrrev_i32_e32 v109, 31, v108
	global_store_dword v[138:139], v65, off offset:128
	v_add_f32_e32 v65, v78, v154
	v_lshlrev_b64 v[108:109], 12, v[108:109]
	global_store_dword v[140:141], v65, off offset:128
	v_add_f32_e32 v65, v79, v153
	v_lshl_add_u64 v[108:109], v[148:149], 0, v[108:109]
	global_store_dword v[142:143], v65, off offset:128
	s_waitcnt vmcnt(28)
	v_add_f32_e32 v48, v48, v64
	global_load_dword v168, v[108:109], off
	global_load_dword v114, v[86:87], off offset:128
	global_load_dword v115, v[80:81], off offset:128
	global_load_dword v116, v[88:89], off offset:128
	global_load_dword v117, v[82:83], off offset:128
	v_or_b32_e32 v68, 0x70, v150
	global_store_dword v[82:83], v48, off
	s_waitcnt vmcnt(33)
	v_add_f32_e32 v48, v49, v144
	global_store_dword v[88:89], v48, off
	s_waitcnt vmcnt(33)
	v_add_f32_e32 v48, v50, v145
	global_store_dword v[80:81], v48, off
	s_waitcnt vmcnt(33)
; DI int crow32(int r, int half) { return (r & 3) + 8 * (r >> 2) + 4 * half; }
; template <class Epi>
; DI void gemm256(const bf16_t* __restrict__ A, int lda, const bf16_t* __restrict__ B, int ldb, int K, int m0, int n0,
;                 bf16_t* sA, bf16_t* sB, Epi epi) {
;     ...
; #pragma unroll
;   for (int i = 0; i < 4; ++i)
; #pragma unroll
;     for (int j = 0; j < 2; ++j)
; #pragma unroll
;       for (int r = 0; r < 16; ++r) {
;         const int m = m0 + wm * 128 + i * 32 + crow32(r, lane >> 5);
;         const int n = n0 + wn * 64 + j * 32 + (lane & 31);
;         epi(m, n, acc[i][j][r]);
;       }
; __global__ void __launch_bounds__(256, 2) hymba_mega(Params p) {
;     ...
;               [&](int m, int n, float v) { out[(size_t)m * 1024 + n] += v; });
	v_add_f32_e32 v48, v51, v157
	global_store_dword v[86:87], v48, off
	global_load_dword v118, v[94:95], off offset:128
	global_load_dword v119, v[92:93], off offset:128
	global_load_dword v120, v[90:91], off offset:128
	global_load_dword v121, v[84:85], off offset:128
	v_or_b32_e32 v76, 0x78, v150
	v_or_b32_e32 v78, 0x79, v150
	v_or_b32_e32 v64, 0x6a, v150
	v_or_b32_e32 v66, 0x6b, v150
	v_ashrrev_i32_e32 v69, 31, v68
	s_waitcnt vmcnt(37)
	v_add_f32_e32 v48, v52, v158
	global_store_dword v[84:85], v48, off
	s_waitcnt vmcnt(37)
	v_add_f32_e32 v48, v53, v159
	global_store_dword v[90:91], v48, off
	s_waitcnt vmcnt(37)
	v_add_f32_e32 v48, v54, v160
	global_store_dword v[92:93], v48, off
	s_waitcnt vmcnt(37)
	v_add_f32_e32 v48, v55, v161
	global_store_dword v[94:95], v48, off
	global_load_dword v122, v[102:103], off offset:128
	global_load_dword v123, v[100:101], off offset:128
	global_load_dword v124, v[98:99], off offset:128
	global_load_dword v125, v[96:97], off offset:128
	v_or_b32_e32 v52, 0x61, v150
	v_or_b32_e32 v54, 0x62, v150
	v_or_b32_e32 v70, 0x71, v150
	v_or_b32_e32 v72, 0x72, v150
	v_or_b32_e32 v74, 0x73, v150
	v_ashrrev_i32_e32 v77, 31, v76
	v_ashrrev_i32_e32 v79, 31, v78
	s_waitcnt vmcnt(41)
	v_add_f32_e32 v48, v56, v162
	global_store_dword v[96:97], v48, off
	s_waitcnt vmcnt(41)
	v_add_f32_e32 v48, v57, v163
	global_store_dword v[98:99], v48, off
	s_waitcnt vmcnt(41)
	v_add_f32_e32 v48, v58, v164
	global_store_dword v[100:101], v48, off
	s_waitcnt vmcnt(41)
	v_add_f32_e32 v48, v59, v165
	global_store_dword v[102:103], v48, off
	v_or_b32_e32 v48, 0x5b, v150
	v_ashrrev_i32_e32 v49, 31, v48
	v_lshlrev_b64 v[48:49], 12, v[48:49]
	v_lshl_add_u64 v[50:51], v[148:149], 0, v[48:49]
	global_load_dword v126, v[50:51], off
	global_load_dword v127, v[50:51], off offset:128
	global_load_dword v128, v[108:109], off offset:128
	global_load_dword v129, v[106:107], off offset:128
	global_load_dword v130, v[104:105], off offset:128
	s_waitcnt vmcnt(46)
	v_add_f32_e32 v48, v60, v166
	global_store_dword v[104:105], v48, off
	s_waitcnt vmcnt(46)
	v_add_f32_e32 v48, v61, v167
	global_store_dword v[106:107], v48, off
	v_or_b32_e32 v48, 0x60, v150
	v_or_b32_e32 v58, 0x68, v150
	v_ashrrev_i32_e32 v49, 31, v48
	v_or_b32_e32 v56, 0x63, v150
	v_ashrrev_i32_e32 v59, 31, v58
	v_or_b32_e32 v60, 0x69, v150
	v_or_b32_e32 v110, 0x7a, v150
	v_or_b32_e32 v112, 0x7b, v150
	v_lshlrev_b64 v[48:49], 12, v[48:49]
	v_ashrrev_i32_e32 v53, 31, v52
	v_ashrrev_i32_e32 v55, 31, v54
	v_ashrrev_i32_e32 v57, 31, v56
	v_lshlrev_b64 v[58:59], 12, v[58:59]
	v_ashrrev_i32_e32 v61, 31, v60
	v_ashrrev_i32_e32 v65, 31, v64
	v_ashrrev_i32_e32 v67, 31, v66
	v_lshlrev_b64 v[68:69], 12, v[68:69]
	v_ashrrev_i32_e32 v71, 31, v70
	v_ashrrev_i32_e32 v73, 31, v72
	v_ashrrev_i32_e32 v75, 31, v74
	v_lshlrev_b64 v[76:77], 12, v[76:77]
	v_lshlrev_b64 v[78:79], 12, v[78:79]
	v_ashrrev_i32_e32 v111, 31, v110
	v_ashrrev_i32_e32 v113, 31, v112
	v_lshl_add_u64 v[48:49], v[148:149], 0, v[48:49]
	v_lshlrev_b64 v[52:53], 12, v[52:53]
	v_lshlrev_b64 v[54:55], 12, v[54:55]
	v_lshlrev_b64 v[56:57], 12, v[56:57]
	v_lshl_add_u64 v[58:59], v[148:149], 0, v[58:59]
	v_lshlrev_b64 v[60:61], 12, v[60:61]
	v_lshlrev_b64 v[64:65], 12, v[64:65]
	v_lshlrev_b64 v[66:67], 12, v[66:67]
	v_lshl_add_u64 v[68:69], v[148:149], 0, v[68:69]
	v_lshlrev_b64 v[70:71], 12, v[70:71]
	v_lshlrev_b64 v[72:73], 12, v[72:73]
	v_lshlrev_b64 v[74:75], 12, v[74:75]
	v_lshl_add_u64 v[76:77], v[148:149], 0, v[76:77]
	v_lshl_add_u64 v[78:79], v[148:149], 0, v[78:79]
	v_lshlrev_b64 v[110:111], 12, v[110:111]
	v_lshlrev_b64 v[112:113], 12, v[112:113]
	v_lshl_add_u64 v[52:53], v[148:149], 0, v[52:53]
	v_lshl_add_u64 v[54:55], v[148:149], 0, v[54:55]
	v_lshl_add_u64 v[56:57], v[148:149], 0, v[56:57]
	global_load_dword v131, v[48:49], off
	global_load_dword v132, v[52:53], off
	global_load_dword v133, v[54:55], off
	global_load_dword v134, v[56:57], off
	v_lshl_add_u64 v[60:61], v[148:149], 0, v[60:61]
	v_lshl_add_u64 v[64:65], v[148:149], 0, v[64:65]
	v_lshl_add_u64 v[66:67], v[148:149], 0, v[66:67]
	global_load_dword v135, v[58:59], off
	global_load_dword v136, v[60:61], off
	global_load_dword v137, v[64:65], off
	global_load_dword v138, v[66:67], off
	v_lshl_add_u64 v[70:71], v[148:149], 0, v[70:71]
	v_lshl_add_u64 v[72:73], v[148:149], 0, v[72:73]
	v_lshl_add_u64 v[74:75], v[148:149], 0, v[74:75]
	global_load_dword v139, v[68:69], off
	global_load_dword v140, v[70:71], off
	global_load_dword v141, v[72:73], off
	global_load_dword v142, v[74:75], off
	global_load_dword v143, v[76:77], off
	v_lshl_add_u64 v[110:111], v[148:149], 0, v[110:111]
	v_lshl_add_u64 v[112:113], v[148:149], 0, v[112:113]
	global_load_dword v144, v[78:79], off
	global_load_dword v145, v[110:111], off
	global_load_dword v146, v[112:113], off
	global_load_dword v147, v[56:57], off offset:128
	global_load_dword v148, v[54:55], off offset:128
	global_load_dword v149, v[52:53], off offset:128
	global_load_dword v150, v[48:49], off offset:128
	s_waitcnt vmcnt(51)
; DI int crow32(int r, int half) { return (r & 3) + 8 * (r >> 2) + 4 * half; }
; template <class Epi>
; DI void gemm256(const bf16_t* __restrict__ A, int lda, const bf16_t* __restrict__ B, int ldb, int K, int m0, int n0,
;                 bf16_t* sA, bf16_t* sB, Epi epi) {
;     ...
; #pragma unroll
;   for (int i = 0; i < 4; ++i)
; #pragma unroll
;     for (int j = 0; j < 2; ++j)
; #pragma unroll
;       for (int r = 0; r < 16; ++r) {
;         const int m = m0 + wm * 128 + i * 32 + crow32(r, lane >> 5);
;         const int n = n0 + wn * 64 + j * 32 + (lane & 31);
;         epi(m, n, acc[i][j][r]);
;       }
; __global__ void __launch_bounds__(256, 2) hymba_mega(Params p) {
;     ...
;     for (int tile = blockIdx.x; tile < 64 * 8; tile += gridDim.x) {
;       const int mt = (tile & 7) * 8 + (tile >> 6), nt = (tile >> 3) & 7;
;       gemm256((const bf16_t*)(ws + OFF_AO), 1024, (const bf16_t*)(ws + OFF_WOT), 1024, 1024, mt * 256, nt * 128, sA, (bf16_t*)(smem + 36864),
;               [&](int m, int n, float v) { out[(size_t)m * 1024 + n] += v; });
;     }
	v_add_f32_e32 v62, v62, v168
	global_store_dword v[108:109], v62, off
	s_waitcnt vmcnt(48)
	v_add_f32_e32 v32, v32, v117
	s_waitcnt vmcnt(27)
	v_add_f32_e32 v62, v63, v126
	global_store_dword v[50:51], v62, off
	global_load_dword v62, v[66:67], off offset:128
	s_nop 0
	global_load_dword v63, v[64:65], off offset:128
	global_load_dword v117, v[60:61], off offset:128
	global_load_dword v126, v[58:59], off offset:128
	s_waitcnt vmcnt(25)
	v_add_f32_e32 v16, v16, v131
	global_store_dword v[82:83], v32, off offset:128
	v_add_f32_e32 v32, v33, v116
	global_store_dword v[88:89], v32, off offset:128
	v_add_f32_e32 v32, v34, v115
	global_load_dword v33, v[74:75], off offset:128
	global_load_dword v34, v[72:73], off offset:128
	global_load_dword v82, v[70:71], off offset:128
	global_load_dword v83, v[68:69], off offset:128
	s_waitcnt vmcnt(12)
	v_add_f32_e32 v0, v0, v150
	global_store_dword v[80:81], v32, off offset:128
	v_add_f32_e32 v32, v35, v114
	global_store_dword v[86:87], v32, off offset:128
	v_add_f32_e32 v32, v36, v121
	global_load_dword v35, v[112:113], off offset:128
	global_load_dword v36, v[110:111], off offset:128
	global_load_dword v80, v[78:79], off offset:128
	global_load_dword v81, v[76:77], off offset:128
	s_nop 0
	global_store_dword v[48:49], v16, off
	v_add_f32_e32 v16, v17, v132
	global_store_dword v[48:49], v0, off offset:128
	v_add_f32_e32 v0, v1, v149
	global_store_dword v[52:53], v16, off
	v_add_f32_e32 v16, v18, v133
	global_store_dword v[52:53], v0, off offset:128
	v_add_f32_e32 v0, v2, v148
	global_store_dword v[54:55], v16, off
	v_add_f32_e32 v16, v19, v134
	global_store_dword v[54:55], v0, off offset:128
	v_add_f32_e32 v0, v3, v147
	global_store_dword v[56:57], v16, off
	v_add_f32_e32 v16, v20, v135
	global_store_dword v[56:57], v0, off offset:128
	s_waitcnt vmcnt(20)
	v_add_f32_e32 v0, v4, v126
	global_store_dword v[84:85], v32, off offset:128
	v_add_f32_e32 v32, v37, v120
	global_store_dword v[58:59], v16, off
	v_add_f32_e32 v16, v21, v136
	global_store_dword v[58:59], v0, off offset:128
	v_add_f32_e32 v0, v5, v117
	global_store_dword v[90:91], v32, off offset:128
	v_add_f32_e32 v32, v38, v119
	global_store_dword v[60:61], v16, off
	v_add_f32_e32 v16, v22, v137
	global_store_dword v[60:61], v0, off offset:128
	v_add_f32_e32 v0, v6, v63
	global_store_dword v[92:93], v32, off offset:128
	v_add_f32_e32 v32, v39, v118
	global_store_dword v[64:65], v16, off
	v_add_f32_e32 v16, v23, v138
	global_store_dword v[64:65], v0, off offset:128
	v_add_f32_e32 v0, v7, v62
	global_store_dword v[94:95], v32, off offset:128
	v_add_f32_e32 v32, v40, v125
	global_store_dword v[66:67], v16, off
	v_add_f32_e32 v16, v24, v139
	global_store_dword v[66:67], v0, off offset:128
	global_store_dword v[96:97], v32, off offset:128
	v_add_f32_e32 v32, v41, v124
	global_store_dword v[68:69], v16, off
	v_add_f32_e32 v16, v25, v140
	global_store_dword v[98:99], v32, off offset:128
	v_add_f32_e32 v32, v42, v123
	global_store_dword v[70:71], v16, off
	v_add_f32_e32 v16, v26, v141
	global_store_dword v[100:101], v32, off offset:128
	v_add_f32_e32 v32, v43, v122
	global_store_dword v[72:73], v16, off
	v_add_f32_e32 v16, v27, v142
	global_store_dword v[102:103], v32, off offset:128
	v_add_f32_e32 v32, v44, v130
	global_store_dword v[74:75], v16, off
	v_add_f32_e32 v16, v28, v143
	global_store_dword v[104:105], v32, off offset:128
	v_add_f32_e32 v32, v45, v129
	global_store_dword v[76:77], v16, off
	v_add_f32_e32 v16, v29, v144
	global_store_dword v[106:107], v32, off offset:128
	v_add_f32_e32 v32, v46, v128
	global_store_dword v[78:79], v16, off
	v_add_f32_e32 v16, v30, v145
	s_waitcnt vmcnt(38)
	v_add_f32_e32 v0, v8, v83
	global_store_dword v[68:69], v0, off offset:128
	v_add_f32_e32 v0, v9, v82
	global_store_dword v[70:71], v0, off offset:128
	v_add_f32_e32 v0, v10, v34
	global_store_dword v[72:73], v0, off offset:128
	v_add_f32_e32 v0, v11, v33
	global_store_dword v[74:75], v0, off offset:128
	global_store_dword v[108:109], v32, off offset:128
	v_add_f32_e32 v32, v47, v127
	global_store_dword v[110:111], v16, off
	v_add_f32_e32 v16, v31, v146
	global_store_dword v[50:51], v32, off offset:128
	global_store_dword v[112:113], v16, off
	s_waitcnt vmcnt(40)
	v_add_f32_e32 v0, v12, v81
	global_store_dword v[76:77], v0, off offset:128
	v_add_f32_e32 v0, v13, v80
	global_store_dword v[78:79], v0, off offset:128
	v_add_f32_e32 v0, v14, v36
	global_store_dword v[110:111], v0, off offset:128
	v_add_f32_e32 v0, v15, v35
	global_store_dword v[112:113], v0, off offset:128
	s_cbranch_scc0 .LBB0_1172

; __global__ void __launch_bounds__(256, 2) hymba_mega(Params p) {
;   cg::grid_group grid = cg::this_grid();
;   __shared__ __attribute__((aligned(16))) char smem[SMEM_BYTES];
	.amdhsa_kernel _Z10hymba_mega6Params
		.amdhsa_group_segment_fixed_size 77840
		.amdhsa_private_segment_fixed_size 0
		.amdhsa_kernarg_size 464
		.amdhsa_user_sgpr_count 2
		.amdhsa_user_sgpr_dispatch_ptr 0
		.amdhsa_user_sgpr_queue_ptr 0
		.amdhsa_user_sgpr_kernarg_segment_ptr 1
		.amdhsa_user_sgpr_dispatch_id 0
		.amdhsa_user_sgpr_kernarg_preload_length 0
		.amdhsa_user_sgpr_kernarg_preload_offset 0
		.amdhsa_user_sgpr_private_segment_size 0
		.amdhsa_uses_dynamic_stack 0
		.amdhsa_enable_private_segment 0
		.amdhsa_system_sgpr_workgroup_id_x 1
		.amdhsa_system_sgpr_workgroup_id_y 0
		.amdhsa_system_sgpr_workgroup_id_z 0
		.amdhsa_system_sgpr_workgroup_info 0
		.amdhsa_system_vgpr_workitem_id 2
		.amdhsa_next_free_vgpr 256
		.amdhsa_next_free_sgpr 102
		.amdhsa_accum_offset 256
		.amdhsa_reserve_vcc 1
		.amdhsa_float_round_mode_32 0
		.amdhsa_float_round_mode_16_64 0
		.amdhsa_float_denorm_mode_32 3
		.amdhsa_float_denorm_mode_16_64 3
		.amdhsa_dx10_clamp 1
		.amdhsa_ieee_mode 1
		.amdhsa_fp16_overflow 0
		.amdhsa_tg_split 0
		.amdhsa_exception_fp_ieee_invalid_op 0
		.amdhsa_exception_fp_denorm_src 0
		.amdhsa_exception_fp_ieee_div_zero 0
		.amdhsa_exception_fp_ieee_overflow 0
		.amdhsa_exception_fp_ieee_underflow 0
		.amdhsa_exception_fp_ieee_inexact 0
		.amdhsa_exception_int_div_zero 0
	.end_amdhsa_kernel

; __global__ void __launch_bounds__(256, 2) hymba_mega(Params p) {
amdhsa.kernels:
  - .agpr_count:     0
    .args:
      - .offset:         0
        .size:           208
        .value_kind:     by_value
      - .offset:         208
        .size:           4
        .value_kind:     hidden_block_count_x
      - .offset:         212
        .size:           4
        .value_kind:     hidden_block_count_y
      - .offset:         216
        .size:           4
        .value_kind:     hidden_block_count_z
      - .offset:         220
        .size:           2
        .value_kind:     hidden_group_size_x
      - .offset:         222
        .size:           2
        .value_kind:     hidden_group_size_y
      - .offset:         224
        .size:           2
        .value_kind:     hidden_group_size_z
      - .offset:         226
        .size:           2
        .value_kind:     hidden_remainder_x
      - .offset:         228
        .size:           2
        .value_kind:     hidden_remainder_y
      - .offset:         230
        .size:           2
        .value_kind:     hidden_remainder_z
      - .offset:         248
        .size:           8
        .value_kind:     hidden_global_offset_x
      - .offset:         256
        .size:           8
        .value_kind:     hidden_global_offset_y
      - .offset:         264
        .size:           8
        .value_kind:     hidden_global_offset_z
      - .offset:         272
        .size:           2
        .value_kind:     hidden_grid_dims
      - .offset:         296
        .size:           8
        .value_kind:     hidden_multigrid_sync_arg
    .group_segment_fixed_size: 77840
    .kernarg_segment_align: 8
    .kernarg_segment_size: 464
    .language:       OpenCL C
    .language_version:
      - 2
      - 0
    .max_flat_workgroup_size: 256
    .name:           _Z10hymba_mega6Params
    .private_segment_fixed_size: 0
    .sgpr_count:     108
    .sgpr_spill_count: 18
    .symbol:         _Z10hymba_mega6Params.kd
    .uniform_work_group_size: 1
    .uses_dynamic_stack: false
    .vgpr_count:     256
    .vgpr_spill_count: 0
    .wavefront_size: 64
